# k-loops: the two loop-invariant LDS read addresses computed once in front of the loop (v244/v245) instead of by VALU every iteration
# baseline (speedup 1.0000x reference)
; #define PG8_STAGE(bufoff, gbase, voff) do { _Pragma("unroll") for (int _i = 0; _i < 2; ++_i) \
;         __builtin_amdgcn_global_load_lds((const unsigned*)((const char*)(gbase) + (voff)[_i]), (PG8_LAS unsigned*)(lds + (bufoff) + ldsw + _i * 8192), 16, 0, 0); } while (0)
; #define PG8_LDA(dst, b, h) do { _Pragma("unroll") for (int m = 0; m < 4; ++m) _Pragma("unroll") for (int k = 0; k < 2; ++k) dst[m][k] = *(const PG8_LAS bf16x8*)(lds + PG8_SA(b, h) + aoff + m * 2048 + k * 1024); } while (0)
; #define PG8_LDB(dst, b, h) do { _Pragma("unroll") for (int n = 0; n < 2; ++n) _Pragma("unroll") for (int k = 0; k < 2; ++k) dst[n][k] = *(const PG8_LAS bf16x8*)(lds + PG8_SB(b, h) + boff + n * 2048 + k * 1024); } while (0)
; #define PG8_SCHED __builtin_amdgcn_sched_barrier(0)
; template <class Epi, class Sched, bool ALIGN_EPI = false, bool SP2 = false>
; __device__ __forceinline__ void gemm_phase(PG8_LAS unsigned char* lds, const Gemm g, const Sched& S, const Epi& E) {
;     ...
;         const bool has_next = S.next(ui + 1, nxt);
;         const char* nA = has_next ? (const char*)g.A + (size_t)nxt.pm * tstep : cA; const char* nB = has_next ? (const char*)g.Bt + (size_t)nxt.pn * tstep : cB;
;         for (int t = 0; t < nt; t += 2) {
;             const bool last = (t == nt - 2);
;             const char* a1 = cA + (size_t)(t + 1) * kstep;
;             const char* a2 = last ? nA : cA + (size_t)(t + 2) * kstep; const char* b2 = last ? nB : cB + (size_t)(t + 2) * kstep;
;             const char* a3 = a2 + kstep; const char* b3 = b2 + kstep;
;             if (last && has_next) S.a_ready(nxt);
;             if constexpr (SP2) {
;             PG8_LDB(B0, 0, 0); PG8_LDB(B1, 0, 1); PG8_SCHED; PG8_LDA(At, 0, 0); PG8_STAGE(PG8_SA(1, 1), a1 + hstep, voffA);
;     ...
; #pragma unroll
;         for (int a = 0; a < 2; ++a)
; #pragma unroll
;             for (int b = 0; b < 2; ++b)
; #pragma unroll
;                 for (int m = 0; m < 4; ++m)
; #pragma unroll
;                     for (int n = 0; n < 2; ++n) acc[a][b][m][n] = (f32x4){0.f, 0.f, 0.f, 0.f};
.LBB0_217:
	s_ashr_i32 s41, s40, 31
	s_lshl_b64 s[6:7], s[40:41], 19
	s_add_u32 s46, s22, s6
	s_load_dwordx2 s[48:49], s[0:1], 0xd0
	s_addc_u32 s47, s23, s7
	s_and_b64 s[6:7], s[42:43], exec
	s_cselect_b32 s4, s47, s53
	s_cselect_b32 s41, s46, s52
	s_ashr_i32 s39, s38, 31
	s_lshl_b64 s[6:7], s[38:39], 19
	s_waitcnt lgkmcnt(0)
	s_add_u32 s48, s48, s6
	s_addc_u32 s49, s49, s7
	s_and_b64 s[6:7], s[42:43], exec
	s_cselect_b32 s39, s49, s55
	s_cselect_b32 s78, s48, s54
	s_add_u32 s52, s52, 0x40080
	s_addc_u32 s53, s53, 0
	s_add_u32 s79, s54, 0x100
	v_mov_b32_e32 v0, 0
	s_addc_u32 s33, s55, 0
	s_mov_b32 s72, -2
	v_mov_b32_e32 v1, v0
	v_mov_b32_e32 v2, v0
	v_mov_b32_e32 v3, v0
	v_mov_b32_e32 v8, v0
	v_mov_b32_e32 v9, v0
	v_mov_b32_e32 v10, v0
	v_mov_b32_e32 v11, v0
	v_mov_b32_e32 v16, v0
	v_mov_b32_e32 v17, v0
	v_mov_b32_e32 v18, v0
	v_mov_b32_e32 v19, v0
	v_mov_b32_e32 v24, v0
	v_mov_b32_e32 v25, v0
	v_mov_b32_e32 v26, v0
	v_mov_b32_e32 v27, v0
	v_mov_b32_e32 v32, v0
	v_mov_b32_e32 v33, v0
	v_mov_b32_e32 v34, v0
	v_mov_b32_e32 v35, v0
	v_mov_b32_e32 v40, v0
	v_mov_b32_e32 v41, v0
	v_mov_b32_e32 v42, v0
	v_mov_b32_e32 v43, v0
	v_mov_b32_e32 v48, v0
	v_mov_b32_e32 v49, v0
	v_mov_b32_e32 v50, v0
	v_mov_b32_e32 v51, v0
	v_mov_b32_e32 v56, v0
	v_mov_b32_e32 v57, v0
	v_mov_b32_e32 v58, v0
	v_mov_b32_e32 v59, v0
	v_mov_b32_e32 v4, v0
	v_mov_b32_e32 v5, v0
	v_mov_b32_e32 v6, v0
	v_mov_b32_e32 v7, v0
	v_mov_b32_e32 v12, v0
	v_mov_b32_e32 v13, v0
	v_mov_b32_e32 v14, v0
	v_mov_b32_e32 v15, v0
	v_mov_b32_e32 v20, v0
	v_mov_b32_e32 v21, v0
	v_mov_b32_e32 v22, v0
	v_mov_b32_e32 v23, v0
	v_mov_b32_e32 v28, v0
	v_mov_b32_e32 v29, v0
	v_mov_b32_e32 v30, v0
	v_mov_b32_e32 v31, v0
	v_mov_b32_e32 v36, v0
	v_mov_b32_e32 v37, v0
	v_mov_b32_e32 v38, v0
	v_mov_b32_e32 v39, v0
	v_mov_b32_e32 v44, v0
	v_mov_b32_e32 v45, v0
	v_mov_b32_e32 v46, v0
	v_mov_b32_e32 v47, v0
	v_mov_b32_e32 v52, v0
	v_mov_b32_e32 v53, v0
	v_mov_b32_e32 v54, v0
	v_mov_b32_e32 v55, v0
	v_mov_b32_e32 v60, v0
	v_mov_b32_e32 v61, v0
	v_mov_b32_e32 v62, v0
	v_mov_b32_e32 v63, v0
	v_mov_b32_e32 v64, v0
	v_mov_b32_e32 v65, v0
	v_mov_b32_e32 v66, v0
	v_mov_b32_e32 v67, v0
	v_mov_b32_e32 v72, v0
	v_mov_b32_e32 v73, v0
	v_mov_b32_e32 v74, v0
	v_mov_b32_e32 v75, v0
	v_mov_b32_e32 v80, v0
	v_mov_b32_e32 v81, v0
	v_mov_b32_e32 v82, v0
	v_mov_b32_e32 v83, v0
	v_mov_b32_e32 v88, v0
	v_mov_b32_e32 v89, v0
	v_mov_b32_e32 v90, v0
	v_mov_b32_e32 v91, v0
	v_mov_b32_e32 v96, v0
	v_mov_b32_e32 v97, v0
	v_mov_b32_e32 v98, v0
	v_mov_b32_e32 v99, v0
	v_mov_b32_e32 v104, v0
	v_mov_b32_e32 v105, v0
	v_mov_b32_e32 v106, v0
	v_mov_b32_e32 v107, v0
	v_mov_b32_e32 v112, v0
	v_mov_b32_e32 v113, v0
	v_mov_b32_e32 v114, v0
	v_mov_b32_e32 v115, v0
	v_mov_b32_e32 v120, v0
	v_mov_b32_e32 v121, v0
	v_mov_b32_e32 v122, v0
	v_mov_b32_e32 v123, v0
	v_mov_b32_e32 v68, v0
	v_mov_b32_e32 v69, v0
	v_mov_b32_e32 v70, v0
	v_mov_b32_e32 v71, v0
	v_mov_b32_e32 v76, v0
	v_mov_b32_e32 v77, v0
	v_mov_b32_e32 v78, v0
	v_mov_b32_e32 v79, v0
	v_mov_b32_e32 v84, v0
	v_mov_b32_e32 v85, v0
	v_mov_b32_e32 v86, v0
	v_mov_b32_e32 v87, v0
	v_mov_b32_e32 v92, v0
	v_mov_b32_e32 v93, v0
	v_mov_b32_e32 v94, v0
	v_mov_b32_e32 v95, v0
	v_mov_b32_e32 v100, v0
	v_mov_b32_e32 v101, v0
	v_mov_b32_e32 v102, v0
	v_mov_b32_e32 v103, v0
	v_mov_b32_e32 v108, v0
	v_mov_b32_e32 v109, v0
	v_mov_b32_e32 v110, v0
	v_mov_b32_e32 v111, v0
	v_mov_b32_e32 v116, v0
	v_mov_b32_e32 v117, v0
	v_mov_b32_e32 v118, v0
	v_mov_b32_e32 v119, v0
	v_mov_b32_e32 v124, v0
	v_mov_b32_e32 v125, v0
	v_mov_b32_e32 v126, v0
	v_mov_b32_e32 v127, v0
	v_add_u32_e32 v244, 0x18000, v154
	v_add_u32_e32 v245, 0x1c000, v154
.LBB0_218:
	ds_read_b128 v[148:151], v157
	ds_read_b128 v[166:169], v157 offset:1024
	ds_read_b128 v[172:175], v157 offset:2048
	ds_read_b128 v[176:179], v157 offset:3072
	ds_read_b128 v[180:183], v158
	ds_read_b128 v[184:187], v158 offset:1024
	ds_read_b128 v[188:191], v158 offset:2048
	ds_read_b128 v[196:199], v158 offset:3072
	s_add_u32 s6, s52, 0xfffc0080
	s_addc_u32 s7, s53, -1
	s_cmp_eq_u32 s72, 12
	s_cselect_b32 s57, s4, s7
	s_cselect_b32 s56, s41, s6
	s_cselect_b32 s55, s39, s33
	s_cselect_b32 s54, s78, s79
	s_add_i32 m0, s37, 0xc000
	ds_read_b128 v[200:203], v159
	ds_read_b128 v[204:207], v159 offset:1024
	ds_read_b128 v[208:211], v159 offset:2048
	ds_read_b128 v[212:215], v159 offset:3072
	ds_read_b128 v[216:219], v159 offset:4096
	ds_read_b128 v[220:223], v159 offset:5120
	ds_read_b128 v[224:227], v159 offset:6144
	ds_read_b128 v[228:231], v159 offset:7168
	global_load_lds_dwordx4 v140, s[52:53]
	s_add_i32 m0, s37, 0xe000
	s_nop 0
	global_load_lds_dwordx4 v142, s[52:53]
	s_waitcnt vmcnt(8)
	s_waitcnt lgkmcnt(0)
	s_barrier
; #define PG8_STAGE(bufoff, gbase, voff) do { _Pragma("unroll") for (int _i = 0; _i < 2; ++_i) \
;         __builtin_amdgcn_global_load_lds((const unsigned*)((const char*)(gbase) + (voff)[_i]), (PG8_LAS unsigned*)(lds + (bufoff) + ldsw + _i * 8192), 16, 0, 0); } while (0)
; #define PG8_LDA(dst, b, h) do { _Pragma("unroll") for (int m = 0; m < 4; ++m) _Pragma("unroll") for (int k = 0; k < 2; ++k) dst[m][k] = *(const PG8_LAS bf16x8*)(lds + PG8_SA(b, h) + aoff + m * 2048 + k * 1024); } while (0)
; #define PG8_MMA(ai, bj, At, Bt) do { __builtin_amdgcn_s_setprio(1); _Pragma("unroll") for (int m = 0; m < 4; ++m) _Pragma("unroll") for (int n = 0; n < 2; ++n) _Pragma("unroll") for (int k = 0; k < 2; ++k) \
;         acc[ai][bj][m][n] = __builtin_amdgcn_mfma_f32_16x16x32_bf16(Bt[n][k], At[m][k], acc[ai][bj][m][n], 0, 0, 0); __builtin_amdgcn_s_setprio(0); } while (0)
; #define PG8_WAIT_V(n) asm volatile("s_waitcnt vmcnt(" #n ")" ::: "memory")
; #define PG8_WAIT_L(n) asm volatile("s_waitcnt lgkmcnt(" #n ")" ::: "memory")
; #define PG8_BAR __builtin_amdgcn_s_barrier()
; #define PG8_SCHED __builtin_amdgcn_sched_barrier(0)
; template <class Epi, class Sched, bool ALIGN_EPI = false, bool SP2 = false>
; __device__ __forceinline__ void gemm_phase(PG8_LAS unsigned char* lds, const Gemm g, const Sched& S, const Epi& E) {
;     ...
;             PG8_WAIT_V(8); PG8_WAIT_L(0); PG8_BAR; PG8_MMA(0, 0, At, B0); PG8_MMA(0, 1, At, B1); PG8_BAR; PG8_SCHED;
;             PG8_LDA(At, 0, 1); PG8_STAGE(PG8_SB(0, 0), b2, voffB); PG8_STAGE(PG8_SB(0, 1), b2 + hstep, voffB); PG8_STAGE(PG8_SA(0, 0), a2, voffA);
;             PG8_WAIT_V(8); PG8_WAIT_L(0); PG8_BAR; PG8_MMA(1, 0, At, B0); PG8_MMA(1, 1, At, B1); PG8_BAR; PG8_SCHED;
	s_waitcnt lgkmcnt(0)
	v_mfma_f32_16x16x32_bf16 v[124:127], v[148:151], v[200:203], v[124:127]
	v_mfma_f32_16x16x32_bf16 v[116:119], v[172:175], v[200:203], v[116:119]
	v_mfma_f32_16x16x32_bf16 v[108:111], v[148:151], v[208:211], v[108:111]
	v_mfma_f32_16x16x32_bf16 v[100:103], v[172:175], v[208:211], v[100:103]
	v_mfma_f32_16x16x32_bf16 v[92:95], v[148:151], v[216:219], v[92:95]
	v_mfma_f32_16x16x32_bf16 v[84:87], v[172:175], v[216:219], v[84:87]
	v_mfma_f32_16x16x32_bf16 v[76:79], v[148:151], v[224:227], v[76:79]
	v_mfma_f32_16x16x32_bf16 v[68:71], v[172:175], v[224:227], v[68:71]
	v_mfma_f32_16x16x32_bf16 v[124:127], v[166:169], v[204:207], v[124:127]
	v_mfma_f32_16x16x32_bf16 v[116:119], v[176:179], v[204:207], v[116:119]
	v_mfma_f32_16x16x32_bf16 v[108:111], v[166:169], v[212:215], v[108:111]
	v_mfma_f32_16x16x32_bf16 v[100:103], v[176:179], v[212:215], v[100:103]
	v_mfma_f32_16x16x32_bf16 v[92:95], v[166:169], v[220:223], v[92:95]
	v_mfma_f32_16x16x32_bf16 v[84:87], v[176:179], v[220:223], v[84:87]
	v_mfma_f32_16x16x32_bf16 v[76:79], v[166:169], v[228:231], v[76:79]
	v_mfma_f32_16x16x32_bf16 v[68:71], v[176:179], v[228:231], v[68:71]
	v_mfma_f32_16x16x32_bf16 v[120:123], v[180:183], v[200:203], v[120:123]
	v_mfma_f32_16x16x32_bf16 v[112:115], v[188:191], v[200:203], v[112:115]
	v_mfma_f32_16x16x32_bf16 v[104:107], v[180:183], v[208:211], v[104:107]
	v_mfma_f32_16x16x32_bf16 v[96:99], v[188:191], v[208:211], v[96:99]
	v_mfma_f32_16x16x32_bf16 v[88:91], v[180:183], v[216:219], v[88:91]
	v_mfma_f32_16x16x32_bf16 v[80:83], v[188:191], v[216:219], v[80:83]
	v_mfma_f32_16x16x32_bf16 v[72:75], v[180:183], v[224:227], v[72:75]
	v_mfma_f32_16x16x32_bf16 v[64:67], v[188:191], v[224:227], v[64:67]
	v_mfma_f32_16x16x32_bf16 v[120:123], v[184:187], v[204:207], v[120:123]
	v_mfma_f32_16x16x32_bf16 v[112:115], v[196:199], v[204:207], v[112:115]
	v_mfma_f32_16x16x32_bf16 v[104:107], v[184:187], v[212:215], v[104:107]
	v_mfma_f32_16x16x32_bf16 v[96:99], v[196:199], v[212:215], v[96:99]
	v_mfma_f32_16x16x32_bf16 v[88:91], v[184:187], v[220:223], v[88:91]
	v_mfma_f32_16x16x32_bf16 v[80:83], v[196:199], v[220:223], v[80:83]
	v_mfma_f32_16x16x32_bf16 v[72:75], v[184:187], v[228:231], v[72:75]
	v_mfma_f32_16x16x32_bf16 v[64:67], v[196:199], v[228:231], v[64:67]
	s_barrier
	s_add_i32 s6, s69, s36
	s_mov_b32 m0, s6
	ds_read_b128 v[200:203], v159 offset:16384
	ds_read_b128 v[204:207], v159 offset:17408
	ds_read_b128 v[208:211], v159 offset:18432
	ds_read_b128 v[212:215], v159 offset:19456
	ds_read_b128 v[216:219], v159 offset:20480
	ds_read_b128 v[220:223], v159 offset:21504
	ds_read_b128 v[224:227], v159 offset:22528
	ds_read_b128 v[228:231], v159 offset:23552
	global_load_lds_dwordx4 v136, s[54:55]
	s_add_i32 m0, s6, 0x2000
	s_add_u32 s6, s54, 0x40000
	s_addc_u32 s7, s55, 0
	s_add_i32 s73, s74, s36
	global_load_lds_dwordx4 v132, s[54:55]
	s_mov_b32 m0, s73
	s_nop 0
	global_load_lds_dwordx4 v136, s[6:7]
	s_add_i32 m0, s73, 0x2000
	s_nop 0
	global_load_lds_dwordx4 v132, s[6:7]
	s_mov_b32 m0, s37
	s_nop 0
	global_load_lds_dwordx4 v138, s[56:57]
	s_mov_b32 m0, s59
	s_nop 0
	global_load_lds_dwordx4 v134, s[56:57]
	s_waitcnt vmcnt(8)
	s_waitcnt lgkmcnt(0)
	s_barrier
	s_waitcnt lgkmcnt(0)
	v_mfma_f32_16x16x32_bf16 v[60:63], v[148:151], v[200:203], v[60:63]
	v_mfma_f32_16x16x32_bf16 v[52:55], v[172:175], v[200:203], v[52:55]
	v_mfma_f32_16x16x32_bf16 v[44:47], v[148:151], v[208:211], v[44:47]
	v_mfma_f32_16x16x32_bf16 v[36:39], v[172:175], v[208:211], v[36:39]
	v_mfma_f32_16x16x32_bf16 v[28:31], v[148:151], v[216:219], v[28:31]
	v_mfma_f32_16x16x32_bf16 v[20:23], v[172:175], v[216:219], v[20:23]
	v_mfma_f32_16x16x32_bf16 v[12:15], v[148:151], v[224:227], v[12:15]
	v_mfma_f32_16x16x32_bf16 v[4:7], v[172:175], v[224:227], v[4:7]
	v_mfma_f32_16x16x32_bf16 v[60:63], v[166:169], v[204:207], v[60:63]
	v_mfma_f32_16x16x32_bf16 v[52:55], v[176:179], v[204:207], v[52:55]
	v_mfma_f32_16x16x32_bf16 v[44:47], v[166:169], v[212:215], v[44:47]
	v_mfma_f32_16x16x32_bf16 v[36:39], v[176:179], v[212:215], v[36:39]
	v_mfma_f32_16x16x32_bf16 v[28:31], v[166:169], v[220:223], v[28:31]
	v_mfma_f32_16x16x32_bf16 v[20:23], v[176:179], v[220:223], v[20:23]
	v_mfma_f32_16x16x32_bf16 v[12:15], v[166:169], v[228:231], v[12:15]
	v_mfma_f32_16x16x32_bf16 v[4:7], v[176:179], v[228:231], v[4:7]
	v_mfma_f32_16x16x32_bf16 v[56:59], v[180:183], v[200:203], v[56:59]
	v_mfma_f32_16x16x32_bf16 v[48:51], v[188:191], v[200:203], v[48:51]
	v_mfma_f32_16x16x32_bf16 v[40:43], v[180:183], v[208:211], v[40:43]
	v_mfma_f32_16x16x32_bf16 v[32:35], v[188:191], v[208:211], v[32:35]
	v_mfma_f32_16x16x32_bf16 v[24:27], v[180:183], v[216:219], v[24:27]
	v_mfma_f32_16x16x32_bf16 v[16:19], v[188:191], v[216:219], v[16:19]
	v_mfma_f32_16x16x32_bf16 v[8:11], v[180:183], v[224:227], v[8:11]
	v_mfma_f32_16x16x32_bf16 v[0:3], v[188:191], v[224:227], v[0:3]
	v_mfma_f32_16x16x32_bf16 v[56:59], v[184:187], v[204:207], v[56:59]
	v_mfma_f32_16x16x32_bf16 v[48:51], v[196:199], v[204:207], v[48:51]
	v_mfma_f32_16x16x32_bf16 v[40:43], v[184:187], v[212:215], v[40:43]
	v_mfma_f32_16x16x32_bf16 v[32:35], v[196:199], v[212:215], v[32:35]
	v_mfma_f32_16x16x32_bf16 v[24:27], v[184:187], v[220:223], v[24:27]
	v_mfma_f32_16x16x32_bf16 v[16:19], v[196:199], v[220:223], v[16:19]
	v_mfma_f32_16x16x32_bf16 v[8:11], v[184:187], v[228:231], v[8:11]
	v_mfma_f32_16x16x32_bf16 v[0:3], v[196:199], v[228:231], v[0:3]
	s_barrier
; #define PG8_STAGE(bufoff, gbase, voff) do { _Pragma("unroll") for (int _i = 0; _i < 2; ++_i) \
;         __builtin_amdgcn_global_load_lds((const unsigned*)((const char*)(gbase) + (voff)[_i]), (PG8_LAS unsigned*)(lds + (bufoff) + ldsw + _i * 8192), 16, 0, 0); } while (0)
; #define PG8_LDA(dst, b, h) do { _Pragma("unroll") for (int m = 0; m < 4; ++m) _Pragma("unroll") for (int k = 0; k < 2; ++k) dst[m][k] = *(const PG8_LAS bf16x8*)(lds + PG8_SA(b, h) + aoff + m * 2048 + k * 1024); } while (0)
; #define PG8_LDB(dst, b, h) do { _Pragma("unroll") for (int n = 0; n < 2; ++n) _Pragma("unroll") for (int k = 0; k < 2; ++k) dst[n][k] = *(const PG8_LAS bf16x8*)(lds + PG8_SB(b, h) + boff + n * 2048 + k * 1024); } while (0)
; #define PG8_MMA(ai, bj, At, Bt) do { __builtin_amdgcn_s_setprio(1); _Pragma("unroll") for (int m = 0; m < 4; ++m) _Pragma("unroll") for (int n = 0; n < 2; ++n) _Pragma("unroll") for (int k = 0; k < 2; ++k) \
;         acc[ai][bj][m][n] = __builtin_amdgcn_mfma_f32_16x16x32_bf16(Bt[n][k], At[m][k], acc[ai][bj][m][n], 0, 0, 0); __builtin_amdgcn_s_setprio(0); } while (0)
; #define PG8_WAIT_V(n) asm volatile("s_waitcnt vmcnt(" #n ")" ::: "memory")
; #define PG8_WAIT_L(n) asm volatile("s_waitcnt lgkmcnt(" #n ")" ::: "memory")
; #define PG8_BAR __builtin_amdgcn_s_barrier()
; #define PG8_SCHED __builtin_amdgcn_sched_barrier(0)
; template <class Epi, class Sched, bool ALIGN_EPI = false, bool SP2 = false>
; __device__ __forceinline__ void gemm_phase(PG8_LAS unsigned char* lds, const Gemm g, const Sched& S, const Epi& E) {
;     ...
;             PG8_LDB(B0, 1, 0); PG8_LDB(B1, 1, 1); PG8_SCHED; PG8_LDA(At, 1, 0); PG8_STAGE(PG8_SA(0, 1), a2 + hstep, voffA);
;             PG8_WAIT_V(8); PG8_WAIT_L(0); PG8_BAR; PG8_MMA(0, 0, At, B0); PG8_MMA(0, 1, At, B1); PG8_BAR; PG8_SCHED;
;             PG8_LDA(At, 1, 1); PG8_STAGE(PG8_SB(1, 0), b3, voffB); PG8_STAGE(PG8_SB(1, 1), b3 + hstep, voffB); PG8_STAGE(PG8_SA(1, 0), a3, voffA);
;             PG8_WAIT_V(8); PG8_WAIT_L(0); PG8_BAR; PG8_MMA(1, 0, At, B0); PG8_MMA(1, 1, At, B1); PG8_BAR; PG8_SCHED;
	s_add_i32 s73, 0, 0x18000
	s_add_i32 s80, 0, 0x1c000
	ds_read_b128 v[148:151], v244
	ds_read_b128 v[166:169], v244 offset:1024
	ds_read_b128 v[172:175], v244 offset:2048
	ds_read_b128 v[176:179], v244 offset:3072
	ds_read_b128 v[180:183], v245
	ds_read_b128 v[184:187], v245 offset:1024
	ds_read_b128 v[188:191], v245 offset:2048
	ds_read_b128 v[196:199], v245 offset:3072
	s_add_u32 s6, s56, 0x40000
	s_addc_u32 s7, s57, 0
	s_mov_b32 m0, s60
	ds_read_b128 v[200:203], v159 offset:32768
	ds_read_b128 v[204:207], v159 offset:33792
	ds_read_b128 v[208:211], v159 offset:34816
	ds_read_b128 v[212:215], v159 offset:35840
	ds_read_b128 v[216:219], v159 offset:36864
	ds_read_b128 v[220:223], v159 offset:37888
	ds_read_b128 v[224:227], v159 offset:38912
	ds_read_b128 v[228:231], v159 offset:39936
	global_load_lds_dwordx4 v138, s[6:7]
	s_mov_b32 m0, s61
	s_nop 0
	global_load_lds_dwordx4 v134, s[6:7]
	s_waitcnt vmcnt(8)
	s_waitcnt lgkmcnt(0)
	s_barrier
	s_waitcnt lgkmcnt(0)
	v_mfma_f32_16x16x32_bf16 v[124:127], v[148:151], v[200:203], v[124:127]
	v_mfma_f32_16x16x32_bf16 v[116:119], v[172:175], v[200:203], v[116:119]
	v_mfma_f32_16x16x32_bf16 v[108:111], v[148:151], v[208:211], v[108:111]
	v_mfma_f32_16x16x32_bf16 v[100:103], v[172:175], v[208:211], v[100:103]
	v_mfma_f32_16x16x32_bf16 v[92:95], v[148:151], v[216:219], v[92:95]
	v_mfma_f32_16x16x32_bf16 v[84:87], v[172:175], v[216:219], v[84:87]
	v_mfma_f32_16x16x32_bf16 v[76:79], v[148:151], v[224:227], v[76:79]
	v_mfma_f32_16x16x32_bf16 v[68:71], v[172:175], v[224:227], v[68:71]
	v_mfma_f32_16x16x32_bf16 v[124:127], v[166:169], v[204:207], v[124:127]
	v_mfma_f32_16x16x32_bf16 v[116:119], v[176:179], v[204:207], v[116:119]
	v_mfma_f32_16x16x32_bf16 v[108:111], v[166:169], v[212:215], v[108:111]
	v_mfma_f32_16x16x32_bf16 v[100:103], v[176:179], v[212:215], v[100:103]
	v_mfma_f32_16x16x32_bf16 v[92:95], v[166:169], v[220:223], v[92:95]
	v_mfma_f32_16x16x32_bf16 v[84:87], v[176:179], v[220:223], v[84:87]
	v_mfma_f32_16x16x32_bf16 v[76:79], v[166:169], v[228:231], v[76:79]
	v_mfma_f32_16x16x32_bf16 v[68:71], v[176:179], v[228:231], v[68:71]
	v_mfma_f32_16x16x32_bf16 v[120:123], v[180:183], v[200:203], v[120:123]
	v_mfma_f32_16x16x32_bf16 v[112:115], v[188:191], v[200:203], v[112:115]
	v_mfma_f32_16x16x32_bf16 v[104:107], v[180:183], v[208:211], v[104:107]
	v_mfma_f32_16x16x32_bf16 v[96:99], v[188:191], v[208:211], v[96:99]
	v_mfma_f32_16x16x32_bf16 v[88:91], v[180:183], v[216:219], v[88:91]
	v_mfma_f32_16x16x32_bf16 v[80:83], v[188:191], v[216:219], v[80:83]
	v_mfma_f32_16x16x32_bf16 v[72:75], v[180:183], v[224:227], v[72:75]
	v_mfma_f32_16x16x32_bf16 v[64:67], v[188:191], v[224:227], v[64:67]
	v_mfma_f32_16x16x32_bf16 v[120:123], v[184:187], v[204:207], v[120:123]
	v_mfma_f32_16x16x32_bf16 v[112:115], v[196:199], v[204:207], v[112:115]
	v_mfma_f32_16x16x32_bf16 v[104:107], v[184:187], v[212:215], v[104:107]
	v_mfma_f32_16x16x32_bf16 v[96:99], v[196:199], v[212:215], v[96:99]
	v_mfma_f32_16x16x32_bf16 v[88:91], v[184:187], v[220:223], v[88:91]
	v_mfma_f32_16x16x32_bf16 v[80:83], v[196:199], v[220:223], v[80:83]
	v_mfma_f32_16x16x32_bf16 v[72:75], v[184:187], v[228:231], v[72:75]
	v_mfma_f32_16x16x32_bf16 v[64:67], v[196:199], v[228:231], v[64:67]
	s_barrier
	s_add_i32 s6, s73, s36
	s_add_u32 s98, s54, 0x80
	s_addc_u32 s99, s55, 0
	s_add_u32 s100, s56, 0x80
	s_addc_u32 s101, s57, 0
	s_mov_b32 m0, s6
	ds_read_b128 v[200:203], v159 offset:49152
	ds_read_b128 v[204:207], v159 offset:50176
	ds_read_b128 v[208:211], v159 offset:51200
	ds_read_b128 v[212:215], v159 offset:52224
	ds_read_b128 v[216:219], v159 offset:53248
	ds_read_b128 v[220:223], v159 offset:54272
	ds_read_b128 v[224:227], v159 offset:55296
	ds_read_b128 v[228:231], v159 offset:56320
	global_load_lds_dwordx4 v136, s[98:99]
	s_add_i32 m0, s6, 0x2000
	s_add_u32 s6, s54, 0x40080
	s_addc_u32 s7, s55, 0
	s_add_i32 s54, s80, s36
	global_load_lds_dwordx4 v132, s[98:99]
	s_mov_b32 m0, s54
	s_nop 0
	global_load_lds_dwordx4 v136, s[6:7]
	s_add_i32 m0, s54, 0x2000
	s_nop 0
	global_load_lds_dwordx4 v132, s[6:7]
	s_mov_b32 m0, s67
	s_nop 0
	global_load_lds_dwordx4 v138, s[100:101]
	s_mov_b32 m0, s68
	s_nop 0
	global_load_lds_dwordx4 v134, s[100:101]
	s_waitcnt vmcnt(8)
	s_waitcnt lgkmcnt(0)
	s_barrier
	s_waitcnt lgkmcnt(0)
	v_mfma_f32_16x16x32_bf16 v[60:63], v[148:151], v[200:203], v[60:63]
	v_mfma_f32_16x16x32_bf16 v[52:55], v[172:175], v[200:203], v[52:55]
	v_mfma_f32_16x16x32_bf16 v[44:47], v[148:151], v[208:211], v[44:47]
	v_mfma_f32_16x16x32_bf16 v[36:39], v[172:175], v[208:211], v[36:39]
	v_mfma_f32_16x16x32_bf16 v[28:31], v[148:151], v[216:219], v[28:31]
	v_mfma_f32_16x16x32_bf16 v[20:23], v[172:175], v[216:219], v[20:23]
	v_mfma_f32_16x16x32_bf16 v[12:15], v[148:151], v[224:227], v[12:15]
	v_mfma_f32_16x16x32_bf16 v[4:7], v[172:175], v[224:227], v[4:7]
	v_mfma_f32_16x16x32_bf16 v[60:63], v[166:169], v[204:207], v[60:63]
	v_mfma_f32_16x16x32_bf16 v[52:55], v[176:179], v[204:207], v[52:55]
	v_mfma_f32_16x16x32_bf16 v[44:47], v[166:169], v[212:215], v[44:47]
	v_mfma_f32_16x16x32_bf16 v[36:39], v[176:179], v[212:215], v[36:39]
	v_mfma_f32_16x16x32_bf16 v[28:31], v[166:169], v[220:223], v[28:31]
	v_mfma_f32_16x16x32_bf16 v[20:23], v[176:179], v[220:223], v[20:23]
	v_mfma_f32_16x16x32_bf16 v[12:15], v[166:169], v[228:231], v[12:15]
	v_mfma_f32_16x16x32_bf16 v[4:7], v[176:179], v[228:231], v[4:7]
	v_mfma_f32_16x16x32_bf16 v[56:59], v[180:183], v[200:203], v[56:59]
	v_mfma_f32_16x16x32_bf16 v[48:51], v[188:191], v[200:203], v[48:51]
	v_mfma_f32_16x16x32_bf16 v[40:43], v[180:183], v[208:211], v[40:43]
	v_mfma_f32_16x16x32_bf16 v[32:35], v[188:191], v[208:211], v[32:35]
	v_mfma_f32_16x16x32_bf16 v[24:27], v[180:183], v[216:219], v[24:27]
	v_mfma_f32_16x16x32_bf16 v[16:19], v[188:191], v[216:219], v[16:19]
	v_mfma_f32_16x16x32_bf16 v[8:11], v[180:183], v[224:227], v[8:11]
	v_mfma_f32_16x16x32_bf16 v[0:3], v[188:191], v[224:227], v[0:3]
	v_mfma_f32_16x16x32_bf16 v[56:59], v[184:187], v[204:207], v[56:59]
	v_mfma_f32_16x16x32_bf16 v[48:51], v[196:199], v[204:207], v[48:51]
	v_mfma_f32_16x16x32_bf16 v[40:43], v[184:187], v[212:215], v[40:43]
	v_mfma_f32_16x16x32_bf16 v[32:35], v[196:199], v[212:215], v[32:35]
	v_mfma_f32_16x16x32_bf16 v[24:27], v[184:187], v[220:223], v[24:27]
	v_mfma_f32_16x16x32_bf16 v[16:19], v[196:199], v[220:223], v[16:19]
	v_mfma_f32_16x16x32_bf16 v[8:11], v[184:187], v[228:231], v[8:11]
	v_mfma_f32_16x16x32_bf16 v[0:3], v[196:199], v[228:231], v[0:3]
	s_barrier
	s_add_i32 s72, s72, 2
	s_add_u32 s52, s52, 0x100
	s_addc_u32 s53, s53, 0
	s_add_u32 s79, s79, 0x100
	s_addc_u32 s33, s33, 0
	s_cmp_gt_u32 s72, 13
	s_cbranch_scc0 .LBB0_218
	s_and_b64 vcc, exec, s[34:35]
	s_cbranch_vccz .LBB0_221
	s_barrier

; #define PG8_STAGE(bufoff, gbase, voff) do { _Pragma("unroll") for (int _i = 0; _i < 2; ++_i) \
;         __builtin_amdgcn_global_load_lds((const unsigned*)((const char*)(gbase) + (voff)[_i]), (PG8_LAS unsigned*)(lds + (bufoff) + ldsw + _i * 8192), 16, 0, 0); } while (0)
; #define PG8_LDA(dst, b, h) do { _Pragma("unroll") for (int m = 0; m < 4; ++m) _Pragma("unroll") for (int k = 0; k < 2; ++k) dst[m][k] = *(const PG8_LAS bf16x8*)(lds + PG8_SA(b, h) + aoff + m * 2048 + k * 1024); } while (0)
; #define PG8_LDB(dst, b, h) do { _Pragma("unroll") for (int n = 0; n < 2; ++n) _Pragma("unroll") for (int k = 0; k < 2; ++k) dst[n][k] = *(const PG8_LAS bf16x8*)(lds + PG8_SB(b, h) + boff + n * 2048 + k * 1024); } while (0)
; #define PG8_MMA(ai, bj, At, Bt) do { __builtin_amdgcn_s_setprio(1); _Pragma("unroll") for (int m = 0; m < 4; ++m) _Pragma("unroll") for (int n = 0; n < 2; ++n) _Pragma("unroll") for (int k = 0; k < 2; ++k) \
;         acc[ai][bj][m][n] = __builtin_amdgcn_mfma_f32_16x16x32_bf16(Bt[n][k], At[m][k], acc[ai][bj][m][n], 0, 0, 0); __builtin_amdgcn_s_setprio(0); } while (0)
; #define PG8_WAIT_V(n) asm volatile("s_waitcnt vmcnt(" #n ")" ::: "memory")
; #define PG8_WAIT_L(n) asm volatile("s_waitcnt lgkmcnt(" #n ")" ::: "memory")
; #define PG8_BAR __builtin_amdgcn_s_barrier()
; template <class Epi, class Sched, bool ALIGN_EPI = false, bool SP2 = false>
; __device__ __forceinline__ void gemm_phase(PG8_LAS unsigned char* lds, const Gemm g, const Sched& S, const Epi& E) {
;     ...
;             const char* a1 = cA + (size_t)(t + 1) * kstep;
;             const char* a2 = last ? nA : cA + (size_t)(t + 2) * kstep; const char* b2 = last ? nB : cB + (size_t)(t + 2) * kstep;
;             const char* a3 = a2 + kstep; const char* b3 = b2 + kstep;
;             if (last && has_next) S.a_ready(nxt);
;             if constexpr (SP2) {
;             PG8_LDB(B0, 0, 0); PG8_LDB(B1, 0, 1); PG8_SCHED; PG8_LDA(At, 0, 0); PG8_STAGE(PG8_SA(1, 1), a1 + hstep, voffA);
;             PG8_WAIT_V(8); PG8_WAIT_L(0); PG8_BAR; PG8_MMA(0, 0, At, B0); PG8_MMA(0, 1, At, B1); PG8_BAR; PG8_SCHED;
;     ...
; #pragma unroll
;         for (int a = 0; a < 2; ++a)
; #pragma unroll
;             for (int b = 0; b < 2; ++b)
; #pragma unroll
;                 for (int m = 0; m < 4; ++m)
; #pragma unroll
;                     for (int n = 0; n < 2; ++n) acc[a][b][m][n] = (f32x4){0.f, 0.f, 0.f, 0.f};
.LBB0_322:
	s_add_u32 s4, s56, 0x100
	v_mov_b32_e32 v0, 0
	s_addc_u32 s33, s57, 0
	s_mov_b32 s69, -2
	s_waitcnt lgkmcnt(0)
	v_mov_b32_e32 v1, v0
	v_mov_b32_e32 v2, v0
	v_mov_b32_e32 v3, v0
	v_mov_b32_e32 v4, v0
	v_mov_b32_e32 v5, v0
	v_mov_b32_e32 v6, v0
	v_mov_b32_e32 v7, v0
	v_mov_b32_e32 v16, v0
	v_mov_b32_e32 v17, v0
	v_mov_b32_e32 v18, v0
	v_mov_b32_e32 v19, v0
	v_mov_b32_e32 v20, v0
	v_mov_b32_e32 v21, v0
	v_mov_b32_e32 v22, v0
	v_mov_b32_e32 v23, v0
	v_mov_b32_e32 v32, v0
	v_mov_b32_e32 v33, v0
	v_mov_b32_e32 v34, v0
	v_mov_b32_e32 v35, v0
	v_mov_b32_e32 v36, v0
	v_mov_b32_e32 v37, v0
	v_mov_b32_e32 v38, v0
	v_mov_b32_e32 v39, v0
	v_mov_b32_e32 v48, v0
	v_mov_b32_e32 v49, v0
	v_mov_b32_e32 v50, v0
	v_mov_b32_e32 v51, v0
	v_mov_b32_e32 v52, v0
	v_mov_b32_e32 v53, v0
	v_mov_b32_e32 v54, v0
	v_mov_b32_e32 v55, v0
	v_mov_b32_e32 v8, v0
	v_mov_b32_e32 v9, v0
	v_mov_b32_e32 v10, v0
	v_mov_b32_e32 v11, v0
	v_mov_b32_e32 v12, v0
	v_mov_b32_e32 v13, v0
	v_mov_b32_e32 v14, v0
	v_mov_b32_e32 v15, v0
	v_mov_b32_e32 v24, v0
	v_mov_b32_e32 v25, v0
	v_mov_b32_e32 v26, v0
	v_mov_b32_e32 v27, v0
	v_mov_b32_e32 v28, v0
	v_mov_b32_e32 v29, v0
	v_mov_b32_e32 v30, v0
	v_mov_b32_e32 v31, v0
	v_mov_b32_e32 v40, v0
	v_mov_b32_e32 v41, v0
	v_mov_b32_e32 v42, v0
	v_mov_b32_e32 v43, v0
	v_mov_b32_e32 v44, v0
	v_mov_b32_e32 v45, v0
	v_mov_b32_e32 v46, v0
	v_mov_b32_e32 v47, v0
	v_mov_b32_e32 v56, v0
	v_mov_b32_e32 v57, v0
	v_mov_b32_e32 v58, v0
	v_mov_b32_e32 v59, v0
	v_mov_b32_e32 v60, v0
	v_mov_b32_e32 v61, v0
	v_mov_b32_e32 v62, v0
	v_mov_b32_e32 v63, v0
	v_mov_b32_e32 v64, v0
	v_mov_b32_e32 v65, v0
	v_mov_b32_e32 v66, v0
	v_mov_b32_e32 v67, v0
	v_mov_b32_e32 v68, v0
	v_mov_b32_e32 v69, v0
	v_mov_b32_e32 v70, v0
	v_mov_b32_e32 v71, v0
	v_mov_b32_e32 v80, v0
	v_mov_b32_e32 v81, v0
	v_mov_b32_e32 v82, v0
	v_mov_b32_e32 v83, v0
	v_mov_b32_e32 v84, v0
	v_mov_b32_e32 v85, v0
	v_mov_b32_e32 v86, v0
	v_mov_b32_e32 v87, v0
	v_mov_b32_e32 v96, v0
	v_mov_b32_e32 v97, v0
	v_mov_b32_e32 v98, v0
	v_mov_b32_e32 v99, v0
	v_mov_b32_e32 v100, v0
	v_mov_b32_e32 v101, v0
	v_mov_b32_e32 v102, v0
	v_mov_b32_e32 v103, v0
	v_mov_b32_e32 v112, v0
	v_mov_b32_e32 v113, v0
	v_mov_b32_e32 v114, v0
	v_mov_b32_e32 v115, v0
	v_mov_b32_e32 v116, v0
	v_mov_b32_e32 v117, v0
	v_mov_b32_e32 v118, v0
	v_mov_b32_e32 v119, v0
	v_mov_b32_e32 v72, v0
	v_mov_b32_e32 v73, v0
	v_mov_b32_e32 v74, v0
	v_mov_b32_e32 v75, v0
	v_mov_b32_e32 v76, v0
	v_mov_b32_e32 v77, v0
	v_mov_b32_e32 v78, v0
	v_mov_b32_e32 v79, v0
	v_mov_b32_e32 v88, v0
	v_mov_b32_e32 v89, v0
	v_mov_b32_e32 v90, v0
	v_mov_b32_e32 v91, v0
	v_mov_b32_e32 v92, v0
	v_mov_b32_e32 v93, v0
	v_mov_b32_e32 v94, v0
	v_mov_b32_e32 v95, v0
	v_mov_b32_e32 v104, v0
	v_mov_b32_e32 v105, v0
	v_mov_b32_e32 v106, v0
	v_mov_b32_e32 v107, v0
	v_mov_b32_e32 v108, v0
	v_mov_b32_e32 v109, v0
	v_mov_b32_e32 v110, v0
	v_mov_b32_e32 v111, v0
	v_mov_b32_e32 v120, v0
	v_mov_b32_e32 v121, v0
	v_mov_b32_e32 v122, v0
	v_mov_b32_e32 v123, v0
	v_mov_b32_e32 v124, v0
	v_mov_b32_e32 v125, v0
	v_mov_b32_e32 v126, v0
	v_mov_b32_e32 v127, v0
	v_add_u32_e32 v244, 0x18000, v154
	v_add_u32_e32 v245, 0x1c000, v154
.LBB0_323:
	ds_read_b128 v[148:151], v156
	ds_read_b128 v[166:169], v156 offset:1024
	ds_read_b128 v[172:175], v156 offset:2048
	ds_read_b128 v[176:179], v156 offset:3072
	ds_read_b128 v[180:183], v157
	ds_read_b128 v[184:187], v157 offset:1024
	ds_read_b128 v[188:191], v157 offset:2048
	ds_read_b128 v[196:199], v157 offset:3072
	s_add_u32 s56, s54, 0x100
	s_addc_u32 s57, s55, 0
	s_cmp_eq_u32 s69, 40
	s_cselect_b32 s61, s51, s57
	s_cselect_b32 s60, s50, s56
	s_cselect_b32 s59, s53, s33
	s_cselect_b32 s58, s52, s4
	s_add_i32 m0, s37, 0xc000
	ds_read_b128 v[200:203], v158
	ds_read_b128 v[204:207], v158 offset:1024
	ds_read_b128 v[208:211], v158 offset:2048
	ds_read_b128 v[212:215], v158 offset:3072
	ds_read_b128 v[216:219], v158 offset:4096
	ds_read_b128 v[220:223], v158 offset:5120
	ds_read_b128 v[224:227], v158 offset:6144
	ds_read_b128 v[228:231], v158 offset:7168
	global_load_lds_dwordx4 v140, s[54:55]
	s_add_i32 m0, s37, 0xe000
	s_nop 0
	global_load_lds_dwordx4 v142, s[54:55]
	s_waitcnt vmcnt(8)
	s_waitcnt lgkmcnt(0)
	s_barrier
	s_waitcnt lgkmcnt(0)
	v_mfma_f32_16x16x32_bf16 v[124:127], v[148:151], v[200:203], v[124:127]
	v_mfma_f32_16x16x32_bf16 v[120:123], v[172:175], v[200:203], v[120:123]
	v_mfma_f32_16x16x32_bf16 v[108:111], v[148:151], v[208:211], v[108:111]
	v_mfma_f32_16x16x32_bf16 v[104:107], v[172:175], v[208:211], v[104:107]
	v_mfma_f32_16x16x32_bf16 v[92:95], v[148:151], v[216:219], v[92:95]
	v_mfma_f32_16x16x32_bf16 v[88:91], v[172:175], v[216:219], v[88:91]
	v_mfma_f32_16x16x32_bf16 v[76:79], v[148:151], v[224:227], v[76:79]
	v_mfma_f32_16x16x32_bf16 v[72:75], v[172:175], v[224:227], v[72:75]
	v_mfma_f32_16x16x32_bf16 v[124:127], v[166:169], v[204:207], v[124:127]
	v_mfma_f32_16x16x32_bf16 v[120:123], v[176:179], v[204:207], v[120:123]
	v_mfma_f32_16x16x32_bf16 v[108:111], v[166:169], v[212:215], v[108:111]
	v_mfma_f32_16x16x32_bf16 v[104:107], v[176:179], v[212:215], v[104:107]
	v_mfma_f32_16x16x32_bf16 v[92:95], v[166:169], v[220:223], v[92:95]
	v_mfma_f32_16x16x32_bf16 v[88:91], v[176:179], v[220:223], v[88:91]
	v_mfma_f32_16x16x32_bf16 v[76:79], v[166:169], v[228:231], v[76:79]
	v_mfma_f32_16x16x32_bf16 v[72:75], v[176:179], v[228:231], v[72:75]
	v_mfma_f32_16x16x32_bf16 v[116:119], v[180:183], v[200:203], v[116:119]
	v_mfma_f32_16x16x32_bf16 v[112:115], v[188:191], v[200:203], v[112:115]
	v_mfma_f32_16x16x32_bf16 v[100:103], v[180:183], v[208:211], v[100:103]
	v_mfma_f32_16x16x32_bf16 v[96:99], v[188:191], v[208:211], v[96:99]
	v_mfma_f32_16x16x32_bf16 v[84:87], v[180:183], v[216:219], v[84:87]
	v_mfma_f32_16x16x32_bf16 v[80:83], v[188:191], v[216:219], v[80:83]
	v_mfma_f32_16x16x32_bf16 v[68:71], v[180:183], v[224:227], v[68:71]
	v_mfma_f32_16x16x32_bf16 v[64:67], v[188:191], v[224:227], v[64:67]
	v_mfma_f32_16x16x32_bf16 v[116:119], v[184:187], v[204:207], v[116:119]
	v_mfma_f32_16x16x32_bf16 v[112:115], v[196:199], v[204:207], v[112:115]
	v_mfma_f32_16x16x32_bf16 v[100:103], v[184:187], v[212:215], v[100:103]
	v_mfma_f32_16x16x32_bf16 v[96:99], v[196:199], v[212:215], v[96:99]
	v_mfma_f32_16x16x32_bf16 v[84:87], v[184:187], v[220:223], v[84:87]
	v_mfma_f32_16x16x32_bf16 v[80:83], v[196:199], v[220:223], v[80:83]
	v_mfma_f32_16x16x32_bf16 v[68:71], v[184:187], v[228:231], v[68:71]
	v_mfma_f32_16x16x32_bf16 v[64:67], v[196:199], v[228:231], v[64:67]
	s_barrier
; #define PG8_STAGE(bufoff, gbase, voff) do { _Pragma("unroll") for (int _i = 0; _i < 2; ++_i) \
;         __builtin_amdgcn_global_load_lds((const unsigned*)((const char*)(gbase) + (voff)[_i]), (PG8_LAS unsigned*)(lds + (bufoff) + ldsw + _i * 8192), 16, 0, 0); } while (0)
; #define PG8_LDA(dst, b, h) do { _Pragma("unroll") for (int m = 0; m < 4; ++m) _Pragma("unroll") for (int k = 0; k < 2; ++k) dst[m][k] = *(const PG8_LAS bf16x8*)(lds + PG8_SA(b, h) + aoff + m * 2048 + k * 1024); } while (0)
; #define PG8_LDB(dst, b, h) do { _Pragma("unroll") for (int n = 0; n < 2; ++n) _Pragma("unroll") for (int k = 0; k < 2; ++k) dst[n][k] = *(const PG8_LAS bf16x8*)(lds + PG8_SB(b, h) + boff + n * 2048 + k * 1024); } while (0)
; #define PG8_MMA(ai, bj, At, Bt) do { __builtin_amdgcn_s_setprio(1); _Pragma("unroll") for (int m = 0; m < 4; ++m) _Pragma("unroll") for (int n = 0; n < 2; ++n) _Pragma("unroll") for (int k = 0; k < 2; ++k) \
;         acc[ai][bj][m][n] = __builtin_amdgcn_mfma_f32_16x16x32_bf16(Bt[n][k], At[m][k], acc[ai][bj][m][n], 0, 0, 0); __builtin_amdgcn_s_setprio(0); } while (0)
; #define PG8_WAIT_V(n) asm volatile("s_waitcnt vmcnt(" #n ")" ::: "memory")
; #define PG8_WAIT_L(n) asm volatile("s_waitcnt lgkmcnt(" #n ")" ::: "memory")
; #define PG8_BAR __builtin_amdgcn_s_barrier()
; #define PG8_SCHED __builtin_amdgcn_sched_barrier(0)
; template <class Epi, class Sched, bool ALIGN_EPI = false, bool SP2 = false>
; __device__ __forceinline__ void gemm_phase(PG8_LAS unsigned char* lds, const Gemm g, const Sched& S, const Epi& E) {
;     ...
;             PG8_LDA(At, 0, 1); PG8_STAGE(PG8_SB(0, 0), b2, voffB); PG8_STAGE(PG8_SB(0, 1), b2 + hstep, voffB); PG8_STAGE(PG8_SA(0, 0), a2, voffA);
;             PG8_WAIT_V(8); PG8_WAIT_L(0); PG8_BAR; PG8_MMA(1, 0, At, B0); PG8_MMA(1, 1, At, B1); PG8_BAR; PG8_SCHED;
;             PG8_LDB(B0, 1, 0); PG8_LDB(B1, 1, 1); PG8_SCHED; PG8_LDA(At, 1, 0); PG8_STAGE(PG8_SA(0, 1), a2 + hstep, voffA);
	s_add_i32 s6, s74, s36
	s_mov_b32 m0, s6
	ds_read_b128 v[200:203], v158 offset:16384
	ds_read_b128 v[204:207], v158 offset:17408
	ds_read_b128 v[208:211], v158 offset:18432
	ds_read_b128 v[212:215], v158 offset:19456
	ds_read_b128 v[216:219], v158 offset:20480
	ds_read_b128 v[220:223], v158 offset:21504
	ds_read_b128 v[224:227], v158 offset:22528
	ds_read_b128 v[228:231], v158 offset:23552
	global_load_lds_dwordx4 v134, s[58:59]
	s_add_i32 m0, s6, 0x2000
	s_add_u32 s54, s58, 0xb0000
	s_addc_u32 s55, s59, 0
	s_add_i32 s6, s75, s36
	global_load_lds_dwordx4 v138, s[58:59]
	s_mov_b32 m0, s6
	s_nop 0
	global_load_lds_dwordx4 v134, s[54:55]
	s_add_i32 m0, s6, 0x2000
	s_nop 0
	global_load_lds_dwordx4 v138, s[54:55]
	s_mov_b32 m0, s37
	s_nop 0
	global_load_lds_dwordx4 v132, s[60:61]
	s_mov_b32 m0, s30
	s_nop 0
	global_load_lds_dwordx4 v136, s[60:61]
	s_waitcnt vmcnt(8)
	s_waitcnt lgkmcnt(0)
	s_barrier
	s_waitcnt lgkmcnt(0)
	v_mfma_f32_16x16x32_bf16 v[60:63], v[148:151], v[200:203], v[60:63]
	v_mfma_f32_16x16x32_bf16 v[56:59], v[172:175], v[200:203], v[56:59]
	v_mfma_f32_16x16x32_bf16 v[44:47], v[148:151], v[208:211], v[44:47]
	v_mfma_f32_16x16x32_bf16 v[40:43], v[172:175], v[208:211], v[40:43]
	v_mfma_f32_16x16x32_bf16 v[28:31], v[148:151], v[216:219], v[28:31]
	v_mfma_f32_16x16x32_bf16 v[24:27], v[172:175], v[216:219], v[24:27]
	v_mfma_f32_16x16x32_bf16 v[12:15], v[148:151], v[224:227], v[12:15]
	v_mfma_f32_16x16x32_bf16 v[8:11], v[172:175], v[224:227], v[8:11]
	v_mfma_f32_16x16x32_bf16 v[60:63], v[166:169], v[204:207], v[60:63]
	v_mfma_f32_16x16x32_bf16 v[56:59], v[176:179], v[204:207], v[56:59]
	v_mfma_f32_16x16x32_bf16 v[44:47], v[166:169], v[212:215], v[44:47]
	v_mfma_f32_16x16x32_bf16 v[40:43], v[176:179], v[212:215], v[40:43]
	v_mfma_f32_16x16x32_bf16 v[28:31], v[166:169], v[220:223], v[28:31]
	v_mfma_f32_16x16x32_bf16 v[24:27], v[176:179], v[220:223], v[24:27]
	v_mfma_f32_16x16x32_bf16 v[12:15], v[166:169], v[228:231], v[12:15]
	v_mfma_f32_16x16x32_bf16 v[8:11], v[176:179], v[228:231], v[8:11]
	v_mfma_f32_16x16x32_bf16 v[52:55], v[180:183], v[200:203], v[52:55]
	v_mfma_f32_16x16x32_bf16 v[48:51], v[188:191], v[200:203], v[48:51]
	v_mfma_f32_16x16x32_bf16 v[36:39], v[180:183], v[208:211], v[36:39]
	v_mfma_f32_16x16x32_bf16 v[32:35], v[188:191], v[208:211], v[32:35]
	v_mfma_f32_16x16x32_bf16 v[20:23], v[180:183], v[216:219], v[20:23]
	v_mfma_f32_16x16x32_bf16 v[16:19], v[188:191], v[216:219], v[16:19]
	v_mfma_f32_16x16x32_bf16 v[4:7], v[180:183], v[224:227], v[4:7]
	v_mfma_f32_16x16x32_bf16 v[0:3], v[188:191], v[224:227], v[0:3]
	v_mfma_f32_16x16x32_bf16 v[52:55], v[184:187], v[204:207], v[52:55]
	v_mfma_f32_16x16x32_bf16 v[48:51], v[196:199], v[204:207], v[48:51]
	v_mfma_f32_16x16x32_bf16 v[36:39], v[184:187], v[212:215], v[36:39]
	v_mfma_f32_16x16x32_bf16 v[32:35], v[196:199], v[212:215], v[32:35]
	v_mfma_f32_16x16x32_bf16 v[20:23], v[184:187], v[220:223], v[20:23]
	v_mfma_f32_16x16x32_bf16 v[16:19], v[196:199], v[220:223], v[16:19]
	v_mfma_f32_16x16x32_bf16 v[4:7], v[184:187], v[228:231], v[4:7]
	v_mfma_f32_16x16x32_bf16 v[0:3], v[196:199], v[228:231], v[0:3]
	s_barrier
	s_add_i32 s6, 0, 0x18000
	s_add_i32 s7, 0, 0x1c000
	ds_read_b128 v[148:151], v244
	ds_read_b128 v[166:169], v244 offset:1024
	ds_read_b128 v[172:175], v244 offset:2048
	ds_read_b128 v[176:179], v244 offset:3072
	ds_read_b128 v[180:183], v245
	ds_read_b128 v[184:187], v245 offset:1024
	ds_read_b128 v[188:191], v245 offset:2048
	ds_read_b128 v[196:199], v245 offset:3072
	s_add_u32 s54, s60, 0xb0000
	s_addc_u32 s55, s61, 0
	s_mov_b32 m0, s31
	ds_read_b128 v[200:203], v158 offset:32768
	ds_read_b128 v[204:207], v158 offset:33792
	ds_read_b128 v[208:211], v158 offset:34816
	ds_read_b128 v[212:215], v158 offset:35840
	ds_read_b128 v[216:219], v158 offset:36864
	ds_read_b128 v[220:223], v158 offset:37888
	ds_read_b128 v[224:227], v158 offset:38912
	ds_read_b128 v[228:231], v158 offset:39936
	global_load_lds_dwordx4 v132, s[54:55]
	s_mov_b32 m0, s76
	s_nop 0
	global_load_lds_dwordx4 v136, s[54:55]
	s_waitcnt vmcnt(8)
	s_waitcnt lgkmcnt(0)
	s_barrier
; #define PG8_STAGE(bufoff, gbase, voff) do { _Pragma("unroll") for (int _i = 0; _i < 2; ++_i) \
;         __builtin_amdgcn_global_load_lds((const unsigned*)((const char*)(gbase) + (voff)[_i]), (PG8_LAS unsigned*)(lds + (bufoff) + ldsw + _i * 8192), 16, 0, 0); } while (0)
; #define PG8_LDA(dst, b, h) do { _Pragma("unroll") for (int m = 0; m < 4; ++m) _Pragma("unroll") for (int k = 0; k < 2; ++k) dst[m][k] = *(const PG8_LAS bf16x8*)(lds + PG8_SA(b, h) + aoff + m * 2048 + k * 1024); } while (0)
; #define PG8_MMA(ai, bj, At, Bt) do { __builtin_amdgcn_s_setprio(1); _Pragma("unroll") for (int m = 0; m < 4; ++m) _Pragma("unroll") for (int n = 0; n < 2; ++n) _Pragma("unroll") for (int k = 0; k < 2; ++k) \
;         acc[ai][bj][m][n] = __builtin_amdgcn_mfma_f32_16x16x32_bf16(Bt[n][k], At[m][k], acc[ai][bj][m][n], 0, 0, 0); __builtin_amdgcn_s_setprio(0); } while (0)
; #define PG8_WAIT_V(n) asm volatile("s_waitcnt vmcnt(" #n ")" ::: "memory")
; #define PG8_WAIT_L(n) asm volatile("s_waitcnt lgkmcnt(" #n ")" ::: "memory")
; #define PG8_BAR __builtin_amdgcn_s_barrier()
; #define PG8_SCHED __builtin_amdgcn_sched_barrier(0)
; template <class Epi, class Sched, bool ALIGN_EPI = false, bool SP2 = false>
; __device__ __forceinline__ void gemm_phase(PG8_LAS unsigned char* lds, const Gemm g, const Sched& S, const Epi& E) {
;     ...
;             PG8_WAIT_V(8); PG8_WAIT_L(0); PG8_BAR; PG8_MMA(0, 0, At, B0); PG8_MMA(0, 1, At, B1); PG8_BAR; PG8_SCHED;
;             PG8_LDA(At, 1, 1); PG8_STAGE(PG8_SB(1, 0), b3, voffB); PG8_STAGE(PG8_SB(1, 1), b3 + hstep, voffB); PG8_STAGE(PG8_SA(1, 0), a3, voffA);
;             PG8_WAIT_V(8); PG8_WAIT_L(0); PG8_BAR; PG8_MMA(1, 0, At, B0); PG8_MMA(1, 1, At, B1); PG8_BAR; PG8_SCHED;
	s_waitcnt lgkmcnt(0)
	v_mfma_f32_16x16x32_bf16 v[124:127], v[148:151], v[200:203], v[124:127]
	v_mfma_f32_16x16x32_bf16 v[120:123], v[172:175], v[200:203], v[120:123]
	v_mfma_f32_16x16x32_bf16 v[108:111], v[148:151], v[208:211], v[108:111]
	v_mfma_f32_16x16x32_bf16 v[104:107], v[172:175], v[208:211], v[104:107]
	v_mfma_f32_16x16x32_bf16 v[92:95], v[148:151], v[216:219], v[92:95]
	v_mfma_f32_16x16x32_bf16 v[88:91], v[172:175], v[216:219], v[88:91]
	v_mfma_f32_16x16x32_bf16 v[76:79], v[148:151], v[224:227], v[76:79]
	v_mfma_f32_16x16x32_bf16 v[72:75], v[172:175], v[224:227], v[72:75]
	v_mfma_f32_16x16x32_bf16 v[124:127], v[166:169], v[204:207], v[124:127]
	v_mfma_f32_16x16x32_bf16 v[120:123], v[176:179], v[204:207], v[120:123]
	v_mfma_f32_16x16x32_bf16 v[108:111], v[166:169], v[212:215], v[108:111]
	v_mfma_f32_16x16x32_bf16 v[104:107], v[176:179], v[212:215], v[104:107]
	v_mfma_f32_16x16x32_bf16 v[92:95], v[166:169], v[220:223], v[92:95]
	v_mfma_f32_16x16x32_bf16 v[88:91], v[176:179], v[220:223], v[88:91]
	v_mfma_f32_16x16x32_bf16 v[76:79], v[166:169], v[228:231], v[76:79]
	v_mfma_f32_16x16x32_bf16 v[72:75], v[176:179], v[228:231], v[72:75]
	v_mfma_f32_16x16x32_bf16 v[116:119], v[180:183], v[200:203], v[116:119]
	v_mfma_f32_16x16x32_bf16 v[112:115], v[188:191], v[200:203], v[112:115]
	v_mfma_f32_16x16x32_bf16 v[100:103], v[180:183], v[208:211], v[100:103]
	v_mfma_f32_16x16x32_bf16 v[96:99], v[188:191], v[208:211], v[96:99]
	v_mfma_f32_16x16x32_bf16 v[84:87], v[180:183], v[216:219], v[84:87]
	v_mfma_f32_16x16x32_bf16 v[80:83], v[188:191], v[216:219], v[80:83]
	v_mfma_f32_16x16x32_bf16 v[68:71], v[180:183], v[224:227], v[68:71]
	v_mfma_f32_16x16x32_bf16 v[64:67], v[188:191], v[224:227], v[64:67]
	v_mfma_f32_16x16x32_bf16 v[116:119], v[184:187], v[204:207], v[116:119]
	v_mfma_f32_16x16x32_bf16 v[112:115], v[196:199], v[204:207], v[112:115]
	v_mfma_f32_16x16x32_bf16 v[100:103], v[184:187], v[212:215], v[100:103]
	v_mfma_f32_16x16x32_bf16 v[96:99], v[196:199], v[212:215], v[96:99]
	v_mfma_f32_16x16x32_bf16 v[84:87], v[184:187], v[220:223], v[84:87]
	v_mfma_f32_16x16x32_bf16 v[80:83], v[196:199], v[220:223], v[80:83]
	v_mfma_f32_16x16x32_bf16 v[68:71], v[184:187], v[228:231], v[68:71]
	v_mfma_f32_16x16x32_bf16 v[64:67], v[196:199], v[228:231], v[64:67]
	s_barrier
	s_add_i32 s6, s6, s36
	s_add_u32 s98, s58, 0x80
	s_addc_u32 s99, s59, 0
	s_add_u32 s100, s60, 0x80
	s_addc_u32 s101, s61, 0
	s_mov_b32 m0, s6
	ds_read_b128 v[200:203], v158 offset:49152
	ds_read_b128 v[204:207], v158 offset:50176
	ds_read_b128 v[208:211], v158 offset:51200
	ds_read_b128 v[212:215], v158 offset:52224
	ds_read_b128 v[216:219], v158 offset:53248
	ds_read_b128 v[220:223], v158 offset:54272
	ds_read_b128 v[224:227], v158 offset:55296
	ds_read_b128 v[228:231], v158 offset:56320
	global_load_lds_dwordx4 v134, s[98:99]
	s_add_i32 m0, s6, 0x2000
	s_add_u32 s54, s58, 0xb0080
	s_addc_u32 s55, s59, 0
	s_add_i32 s6, s7, s36
	global_load_lds_dwordx4 v138, s[98:99]
	s_mov_b32 m0, s6
	s_nop 0
	global_load_lds_dwordx4 v134, s[54:55]
	s_add_i32 m0, s6, 0x2000
	s_nop 0
	global_load_lds_dwordx4 v138, s[54:55]
	s_mov_b32 m0, s78
	s_nop 0
	global_load_lds_dwordx4 v132, s[100:101]
	s_mov_b32 m0, s79
	s_nop 0
	global_load_lds_dwordx4 v136, s[100:101]
	s_waitcnt vmcnt(8)
	s_waitcnt lgkmcnt(0)
	s_barrier
	s_waitcnt lgkmcnt(0)
	v_mfma_f32_16x16x32_bf16 v[60:63], v[148:151], v[200:203], v[60:63]
	v_mfma_f32_16x16x32_bf16 v[56:59], v[172:175], v[200:203], v[56:59]
	v_mfma_f32_16x16x32_bf16 v[44:47], v[148:151], v[208:211], v[44:47]
	v_mfma_f32_16x16x32_bf16 v[40:43], v[172:175], v[208:211], v[40:43]
	v_mfma_f32_16x16x32_bf16 v[28:31], v[148:151], v[216:219], v[28:31]
	v_mfma_f32_16x16x32_bf16 v[24:27], v[172:175], v[216:219], v[24:27]
	v_mfma_f32_16x16x32_bf16 v[12:15], v[148:151], v[224:227], v[12:15]
	v_mfma_f32_16x16x32_bf16 v[8:11], v[172:175], v[224:227], v[8:11]
	v_mfma_f32_16x16x32_bf16 v[60:63], v[166:169], v[204:207], v[60:63]
	v_mfma_f32_16x16x32_bf16 v[56:59], v[176:179], v[204:207], v[56:59]
	v_mfma_f32_16x16x32_bf16 v[44:47], v[166:169], v[212:215], v[44:47]
	v_mfma_f32_16x16x32_bf16 v[40:43], v[176:179], v[212:215], v[40:43]
	v_mfma_f32_16x16x32_bf16 v[28:31], v[166:169], v[220:223], v[28:31]
	v_mfma_f32_16x16x32_bf16 v[24:27], v[176:179], v[220:223], v[24:27]
	v_mfma_f32_16x16x32_bf16 v[12:15], v[166:169], v[228:231], v[12:15]
	v_mfma_f32_16x16x32_bf16 v[8:11], v[176:179], v[228:231], v[8:11]
	v_mfma_f32_16x16x32_bf16 v[52:55], v[180:183], v[200:203], v[52:55]
	v_mfma_f32_16x16x32_bf16 v[48:51], v[188:191], v[200:203], v[48:51]
	v_mfma_f32_16x16x32_bf16 v[36:39], v[180:183], v[208:211], v[36:39]
	v_mfma_f32_16x16x32_bf16 v[32:35], v[188:191], v[208:211], v[32:35]
	v_mfma_f32_16x16x32_bf16 v[20:23], v[180:183], v[216:219], v[20:23]
	v_mfma_f32_16x16x32_bf16 v[16:19], v[188:191], v[216:219], v[16:19]
	v_mfma_f32_16x16x32_bf16 v[4:7], v[180:183], v[224:227], v[4:7]
	v_mfma_f32_16x16x32_bf16 v[0:3], v[188:191], v[224:227], v[0:3]
	v_mfma_f32_16x16x32_bf16 v[52:55], v[184:187], v[204:207], v[52:55]
	v_mfma_f32_16x16x32_bf16 v[48:51], v[196:199], v[204:207], v[48:51]
	v_mfma_f32_16x16x32_bf16 v[36:39], v[184:187], v[212:215], v[36:39]
	v_mfma_f32_16x16x32_bf16 v[32:35], v[196:199], v[212:215], v[32:35]
	v_mfma_f32_16x16x32_bf16 v[20:23], v[184:187], v[220:223], v[20:23]
	v_mfma_f32_16x16x32_bf16 v[16:19], v[196:199], v[220:223], v[16:19]
	v_mfma_f32_16x16x32_bf16 v[4:7], v[184:187], v[228:231], v[4:7]
	v_mfma_f32_16x16x32_bf16 v[0:3], v[196:199], v[228:231], v[0:3]
	s_barrier
	s_add_i32 s69, s69, 2
	s_add_u32 s4, s4, 0x100
	s_addc_u32 s33, s33, 0
	s_cmp_gt_u32 s69, 41
	s_mov_b64 s[54:55], s[56:57]
	s_cbranch_scc0 .LBB0_323
	s_and_b64 vcc, exec, s[40:41]
	s_cbranch_vccz .LBB0_326
	s_barrier

; #define PG8_STAGE(bufoff, gbase, voff) do { _Pragma("unroll") for (int _i = 0; _i < 2; ++_i) \
;         __builtin_amdgcn_global_load_lds((const unsigned*)((const char*)(gbase) + (voff)[_i]), (PG8_LAS unsigned*)(lds + (bufoff) + ldsw + _i * 8192), 16, 0, 0); } while (0)
; #define PG8_LDA(dst, b, h) do { _Pragma("unroll") for (int m = 0; m < 4; ++m) _Pragma("unroll") for (int k = 0; k < 2; ++k) dst[m][k] = *(const PG8_LAS bf16x8*)(lds + PG8_SA(b, h) + aoff + m * 2048 + k * 1024); } while (0)
; #define PG8_LDB(dst, b, h) do { _Pragma("unroll") for (int n = 0; n < 2; ++n) _Pragma("unroll") for (int k = 0; k < 2; ++k) dst[n][k] = *(const PG8_LAS bf16x8*)(lds + PG8_SB(b, h) + boff + n * 2048 + k * 1024); } while (0)
; #define PG8_SCHED __builtin_amdgcn_sched_barrier(0)
; template <class Epi, class Sched, bool ALIGN_EPI = false, bool SP2 = false>
; __device__ __forceinline__ void gemm_phase(PG8_LAS unsigned char* lds, const Gemm g, const Sched& S, const Epi& E) {
;     ...
;         const bool has_next = S.next(ui + 1, nxt);
;         const char* nA = has_next ? (const char*)g.A + (size_t)nxt.pm * tstep : cA; const char* nB = has_next ? (const char*)g.Bt + (size_t)nxt.pn * tstep : cB;
;         for (int t = 0; t < nt; t += 2) {
;             const bool last = (t == nt - 2);
;             const char* a1 = cA + (size_t)(t + 1) * kstep;
;             const char* a2 = last ? nA : cA + (size_t)(t + 2) * kstep; const char* b2 = last ? nB : cB + (size_t)(t + 2) * kstep;
;             const char* a3 = a2 + kstep; const char* b3 = b2 + kstep;
;             if (last && has_next) S.a_ready(nxt);
;             if constexpr (SP2) {
;             PG8_LDB(B0, 0, 0); PG8_LDB(B1, 0, 1); PG8_SCHED; PG8_LDA(At, 0, 0); PG8_STAGE(PG8_SA(1, 1), a1 + hstep, voffA);
;     ...
; #pragma unroll
;         for (int a = 0; a < 2; ++a)
; #pragma unroll
;             for (int b = 0; b < 2; ++b)
; #pragma unroll
;                 for (int m = 0; m < 4; ++m)
; #pragma unroll
;                     for (int n = 0; n < 2; ++n) acc[a][b][m][n] = (f32x4){0.f, 0.f, 0.f, 0.f};
.LBB0_462:
	s_ashr_i32 s55, s54, 31
	s_lshl_b64 s[56:57], s[54:55], 19
	s_add_u32 s56, s22, s56
	s_addc_u32 s57, s23, s57
	s_and_b64 s[58:59], s[46:47], exec
	s_cselect_b32 s49, s57, s61
	s_cselect_b32 s55, s56, s60
	s_ashr_i32 s53, s52, 31
	s_lshl_b64 s[58:59], s[52:53], 19
	s_add_u32 s58, s26, s58
	s_addc_u32 s59, s27, s59
	s_and_b64 s[72:73], s[46:47], exec
	s_cselect_b32 s53, s59, s79
	s_cselect_b32 vcc_lo, s58, s78
	s_add_u32 s60, s60, 0x40080
	s_addc_u32 s61, s61, 0
	s_add_u32 vcc_hi, s78, 0x100
	v_mov_b32_e32 v0, 0
	s_addc_u32 s33, s79, 0
	s_mov_b32 s72, -2
	v_mov_b32_e32 v1, v0
	v_mov_b32_e32 v2, v0
	v_mov_b32_e32 v3, v0
	v_mov_b32_e32 v4, v0
	v_mov_b32_e32 v5, v0
	v_mov_b32_e32 v6, v0
	v_mov_b32_e32 v7, v0
	v_mov_b32_e32 v16, v0
	v_mov_b32_e32 v17, v0
	v_mov_b32_e32 v18, v0
	v_mov_b32_e32 v19, v0
	v_mov_b32_e32 v20, v0
	v_mov_b32_e32 v21, v0
	v_mov_b32_e32 v22, v0
	v_mov_b32_e32 v23, v0
	v_mov_b32_e32 v32, v0
	v_mov_b32_e32 v33, v0
	v_mov_b32_e32 v34, v0
	v_mov_b32_e32 v35, v0
	v_mov_b32_e32 v36, v0
	v_mov_b32_e32 v37, v0
	v_mov_b32_e32 v38, v0
	v_mov_b32_e32 v39, v0
	v_mov_b32_e32 v48, v0
	v_mov_b32_e32 v49, v0
	v_mov_b32_e32 v50, v0
	v_mov_b32_e32 v51, v0
	v_mov_b32_e32 v52, v0
	v_mov_b32_e32 v53, v0
	v_mov_b32_e32 v54, v0
	v_mov_b32_e32 v55, v0
	v_mov_b32_e32 v8, v0
	v_mov_b32_e32 v9, v0
	v_mov_b32_e32 v10, v0
	v_mov_b32_e32 v11, v0
	v_mov_b32_e32 v12, v0
	v_mov_b32_e32 v13, v0
	v_mov_b32_e32 v14, v0
	v_mov_b32_e32 v15, v0
	v_mov_b32_e32 v24, v0
	v_mov_b32_e32 v25, v0
	v_mov_b32_e32 v26, v0
	v_mov_b32_e32 v27, v0
	v_mov_b32_e32 v28, v0
	v_mov_b32_e32 v29, v0
	v_mov_b32_e32 v30, v0
	v_mov_b32_e32 v31, v0
	v_mov_b32_e32 v40, v0
	v_mov_b32_e32 v41, v0
	v_mov_b32_e32 v42, v0
	v_mov_b32_e32 v43, v0
	v_mov_b32_e32 v44, v0
	v_mov_b32_e32 v45, v0
	v_mov_b32_e32 v46, v0
	v_mov_b32_e32 v47, v0
	v_mov_b32_e32 v56, v0
	v_mov_b32_e32 v57, v0
	v_mov_b32_e32 v58, v0
	v_mov_b32_e32 v59, v0
	v_mov_b32_e32 v60, v0
	v_mov_b32_e32 v61, v0
	v_mov_b32_e32 v62, v0
	v_mov_b32_e32 v63, v0
	v_mov_b32_e32 v64, v0
	v_mov_b32_e32 v65, v0
	v_mov_b32_e32 v66, v0
	v_mov_b32_e32 v67, v0
	v_mov_b32_e32 v68, v0
	v_mov_b32_e32 v69, v0
	v_mov_b32_e32 v70, v0
	v_mov_b32_e32 v71, v0
	v_mov_b32_e32 v80, v0
	v_mov_b32_e32 v81, v0
	v_mov_b32_e32 v82, v0
	v_mov_b32_e32 v83, v0
	v_mov_b32_e32 v84, v0
	v_mov_b32_e32 v85, v0
	v_mov_b32_e32 v86, v0
	v_mov_b32_e32 v87, v0
	v_mov_b32_e32 v96, v0
	v_mov_b32_e32 v97, v0
	v_mov_b32_e32 v98, v0
	v_mov_b32_e32 v99, v0
	v_mov_b32_e32 v100, v0
	v_mov_b32_e32 v101, v0
	v_mov_b32_e32 v102, v0
	v_mov_b32_e32 v103, v0
	v_mov_b32_e32 v112, v0
	v_mov_b32_e32 v113, v0
	v_mov_b32_e32 v114, v0
	v_mov_b32_e32 v115, v0
	v_mov_b32_e32 v116, v0
	v_mov_b32_e32 v117, v0
	v_mov_b32_e32 v118, v0
	v_mov_b32_e32 v119, v0
	v_mov_b32_e32 v72, v0
	v_mov_b32_e32 v73, v0
	v_mov_b32_e32 v74, v0
	v_mov_b32_e32 v75, v0
	v_mov_b32_e32 v76, v0
	v_mov_b32_e32 v77, v0
	v_mov_b32_e32 v78, v0
	v_mov_b32_e32 v79, v0
	v_mov_b32_e32 v88, v0
	v_mov_b32_e32 v89, v0
	v_mov_b32_e32 v90, v0
	v_mov_b32_e32 v91, v0
	v_mov_b32_e32 v92, v0
	v_mov_b32_e32 v93, v0
	v_mov_b32_e32 v94, v0
	v_mov_b32_e32 v95, v0
	v_mov_b32_e32 v104, v0
	v_mov_b32_e32 v105, v0
	v_mov_b32_e32 v106, v0
	v_mov_b32_e32 v107, v0
	v_mov_b32_e32 v108, v0
	v_mov_b32_e32 v109, v0
	v_mov_b32_e32 v110, v0
	v_mov_b32_e32 v111, v0
	v_mov_b32_e32 v120, v0
	v_mov_b32_e32 v121, v0
	v_mov_b32_e32 v122, v0
	v_mov_b32_e32 v123, v0
	v_mov_b32_e32 v124, v0
	v_mov_b32_e32 v125, v0
	v_mov_b32_e32 v126, v0
	v_mov_b32_e32 v127, v0
	v_add_u32_e32 v244, 0x18000, v143
	v_add_u32_e32 v245, 0x1c000, v143
.LBB0_463:
	ds_read_b128 v[152:155], v172
	ds_read_b128 v[156:159], v172 offset:1024
	ds_read_b128 v[166:169], v172 offset:2048
	ds_read_b128 v[176:179], v172 offset:3072
	ds_read_b128 v[180:183], v173
	ds_read_b128 v[184:187], v173 offset:1024
	ds_read_b128 v[188:191], v173 offset:2048
	ds_read_b128 v[196:199], v173 offset:3072
	s_add_u32 s6, s60, 0xfffc0080
	s_addc_u32 s7, s61, -1
	s_cmp_eq_u32 s72, 12
	s_cselect_b32 s81, s49, s7
	s_cselect_b32 s80, s55, s6
	s_cselect_b32 s79, s53, s33
	s_cselect_b32 s78, vcc_lo, vcc_hi
	s_add_i32 m0, s31, 0xc000
	ds_read_b128 v[200:203], v174
	ds_read_b128 v[204:207], v174 offset:1024
	ds_read_b128 v[208:211], v174 offset:2048
	ds_read_b128 v[212:215], v174 offset:3072
	ds_read_b128 v[216:219], v174 offset:4096
	ds_read_b128 v[220:223], v174 offset:5120
	ds_read_b128 v[224:227], v174 offset:6144
	ds_read_b128 v[228:231], v174 offset:7168
	global_load_lds_dwordx4 v144, s[60:61]
	s_add_i32 m0, s31, 0xe000
	s_nop 0
	global_load_lds_dwordx4 v146, s[60:61]
	s_waitcnt vmcnt(8)
	s_waitcnt lgkmcnt(0)
	s_barrier
; #define PG8_STAGE(bufoff, gbase, voff) do { _Pragma("unroll") for (int _i = 0; _i < 2; ++_i) \
;         __builtin_amdgcn_global_load_lds((const unsigned*)((const char*)(gbase) + (voff)[_i]), (PG8_LAS unsigned*)(lds + (bufoff) + ldsw + _i * 8192), 16, 0, 0); } while (0)
; #define PG8_LDA(dst, b, h) do { _Pragma("unroll") for (int m = 0; m < 4; ++m) _Pragma("unroll") for (int k = 0; k < 2; ++k) dst[m][k] = *(const PG8_LAS bf16x8*)(lds + PG8_SA(b, h) + aoff + m * 2048 + k * 1024); } while (0)
; #define PG8_MMA(ai, bj, At, Bt) do { __builtin_amdgcn_s_setprio(1); _Pragma("unroll") for (int m = 0; m < 4; ++m) _Pragma("unroll") for (int n = 0; n < 2; ++n) _Pragma("unroll") for (int k = 0; k < 2; ++k) \
;         acc[ai][bj][m][n] = __builtin_amdgcn_mfma_f32_16x16x32_bf16(Bt[n][k], At[m][k], acc[ai][bj][m][n], 0, 0, 0); __builtin_amdgcn_s_setprio(0); } while (0)
; #define PG8_WAIT_V(n) asm volatile("s_waitcnt vmcnt(" #n ")" ::: "memory")
; #define PG8_WAIT_L(n) asm volatile("s_waitcnt lgkmcnt(" #n ")" ::: "memory")
; #define PG8_BAR __builtin_amdgcn_s_barrier()
; #define PG8_SCHED __builtin_amdgcn_sched_barrier(0)
; template <class Epi, class Sched, bool ALIGN_EPI = false, bool SP2 = false>
; __device__ __forceinline__ void gemm_phase(PG8_LAS unsigned char* lds, const Gemm g, const Sched& S, const Epi& E) {
;     ...
;             PG8_WAIT_V(8); PG8_WAIT_L(0); PG8_BAR; PG8_MMA(0, 0, At, B0); PG8_MMA(0, 1, At, B1); PG8_BAR; PG8_SCHED;
;             PG8_LDA(At, 0, 1); PG8_STAGE(PG8_SB(0, 0), b2, voffB); PG8_STAGE(PG8_SB(0, 1), b2 + hstep, voffB); PG8_STAGE(PG8_SA(0, 0), a2, voffA);
;             PG8_WAIT_V(8); PG8_WAIT_L(0); PG8_BAR; PG8_MMA(1, 0, At, B0); PG8_MMA(1, 1, At, B1); PG8_BAR; PG8_SCHED;
	s_waitcnt lgkmcnt(0)
	v_mfma_f32_16x16x32_bf16 v[124:127], v[152:155], v[200:203], v[124:127]
	v_mfma_f32_16x16x32_bf16 v[120:123], v[166:169], v[200:203], v[120:123]
	v_mfma_f32_16x16x32_bf16 v[108:111], v[152:155], v[208:211], v[108:111]
	v_mfma_f32_16x16x32_bf16 v[104:107], v[166:169], v[208:211], v[104:107]
	v_mfma_f32_16x16x32_bf16 v[92:95], v[152:155], v[216:219], v[92:95]
	v_mfma_f32_16x16x32_bf16 v[88:91], v[166:169], v[216:219], v[88:91]
	v_mfma_f32_16x16x32_bf16 v[76:79], v[152:155], v[224:227], v[76:79]
	v_mfma_f32_16x16x32_bf16 v[72:75], v[166:169], v[224:227], v[72:75]
	v_mfma_f32_16x16x32_bf16 v[124:127], v[156:159], v[204:207], v[124:127]
	v_mfma_f32_16x16x32_bf16 v[120:123], v[176:179], v[204:207], v[120:123]
	v_mfma_f32_16x16x32_bf16 v[108:111], v[156:159], v[212:215], v[108:111]
	v_mfma_f32_16x16x32_bf16 v[104:107], v[176:179], v[212:215], v[104:107]
	v_mfma_f32_16x16x32_bf16 v[92:95], v[156:159], v[220:223], v[92:95]
	v_mfma_f32_16x16x32_bf16 v[88:91], v[176:179], v[220:223], v[88:91]
	v_mfma_f32_16x16x32_bf16 v[76:79], v[156:159], v[228:231], v[76:79]
	v_mfma_f32_16x16x32_bf16 v[72:75], v[176:179], v[228:231], v[72:75]
	v_mfma_f32_16x16x32_bf16 v[116:119], v[180:183], v[200:203], v[116:119]
	v_mfma_f32_16x16x32_bf16 v[112:115], v[188:191], v[200:203], v[112:115]
	v_mfma_f32_16x16x32_bf16 v[100:103], v[180:183], v[208:211], v[100:103]
	v_mfma_f32_16x16x32_bf16 v[96:99], v[188:191], v[208:211], v[96:99]
	v_mfma_f32_16x16x32_bf16 v[84:87], v[180:183], v[216:219], v[84:87]
	v_mfma_f32_16x16x32_bf16 v[80:83], v[188:191], v[216:219], v[80:83]
	v_mfma_f32_16x16x32_bf16 v[68:71], v[180:183], v[224:227], v[68:71]
	v_mfma_f32_16x16x32_bf16 v[64:67], v[188:191], v[224:227], v[64:67]
	v_mfma_f32_16x16x32_bf16 v[116:119], v[184:187], v[204:207], v[116:119]
	v_mfma_f32_16x16x32_bf16 v[112:115], v[196:199], v[204:207], v[112:115]
	v_mfma_f32_16x16x32_bf16 v[100:103], v[184:187], v[212:215], v[100:103]
	v_mfma_f32_16x16x32_bf16 v[96:99], v[196:199], v[212:215], v[96:99]
	v_mfma_f32_16x16x32_bf16 v[84:87], v[184:187], v[220:223], v[84:87]
	v_mfma_f32_16x16x32_bf16 v[80:83], v[196:199], v[220:223], v[80:83]
	v_mfma_f32_16x16x32_bf16 v[68:71], v[184:187], v[228:231], v[68:71]
	v_mfma_f32_16x16x32_bf16 v[64:67], v[196:199], v[228:231], v[64:67]
	s_barrier
	s_add_i32 s6, s69, s30
	s_mov_b32 m0, s6
	ds_read_b128 v[200:203], v174 offset:16384
	ds_read_b128 v[204:207], v174 offset:17408
	ds_read_b128 v[208:211], v174 offset:18432
	ds_read_b128 v[212:215], v174 offset:19456
	ds_read_b128 v[216:219], v174 offset:20480
	ds_read_b128 v[220:223], v174 offset:21504
	ds_read_b128 v[224:227], v174 offset:22528
	ds_read_b128 v[228:231], v174 offset:23552
	global_load_lds_dwordx4 v134, s[78:79]
	s_add_i32 m0, s6, 0x2000
	s_add_u32 s6, s78, 0x40000
	s_addc_u32 s7, s79, 0
	s_add_i32 s73, s74, s30
	global_load_lds_dwordx4 v138, s[78:79]
	s_mov_b32 m0, s73
	s_nop 0
	global_load_lds_dwordx4 v134, s[6:7]
	s_add_i32 m0, s73, 0x2000
	s_nop 0
	global_load_lds_dwordx4 v138, s[6:7]
	s_mov_b32 m0, s31
	s_nop 0
	global_load_lds_dwordx4 v132, s[80:81]
	s_mov_b32 m0, s36
	s_nop 0
	global_load_lds_dwordx4 v136, s[80:81]
	s_waitcnt vmcnt(8)
	s_waitcnt lgkmcnt(0)
	s_barrier
	s_waitcnt lgkmcnt(0)
	v_mfma_f32_16x16x32_bf16 v[60:63], v[152:155], v[200:203], v[60:63]
	v_mfma_f32_16x16x32_bf16 v[56:59], v[166:169], v[200:203], v[56:59]
	v_mfma_f32_16x16x32_bf16 v[44:47], v[152:155], v[208:211], v[44:47]
	v_mfma_f32_16x16x32_bf16 v[40:43], v[166:169], v[208:211], v[40:43]
	v_mfma_f32_16x16x32_bf16 v[28:31], v[152:155], v[216:219], v[28:31]
	v_mfma_f32_16x16x32_bf16 v[24:27], v[166:169], v[216:219], v[24:27]
	v_mfma_f32_16x16x32_bf16 v[12:15], v[152:155], v[224:227], v[12:15]
	v_mfma_f32_16x16x32_bf16 v[8:11], v[166:169], v[224:227], v[8:11]
	v_mfma_f32_16x16x32_bf16 v[60:63], v[156:159], v[204:207], v[60:63]
	v_mfma_f32_16x16x32_bf16 v[56:59], v[176:179], v[204:207], v[56:59]
	v_mfma_f32_16x16x32_bf16 v[44:47], v[156:159], v[212:215], v[44:47]
	v_mfma_f32_16x16x32_bf16 v[40:43], v[176:179], v[212:215], v[40:43]
	v_mfma_f32_16x16x32_bf16 v[28:31], v[156:159], v[220:223], v[28:31]
	v_mfma_f32_16x16x32_bf16 v[24:27], v[176:179], v[220:223], v[24:27]
	v_mfma_f32_16x16x32_bf16 v[12:15], v[156:159], v[228:231], v[12:15]
	v_mfma_f32_16x16x32_bf16 v[8:11], v[176:179], v[228:231], v[8:11]
	v_mfma_f32_16x16x32_bf16 v[52:55], v[180:183], v[200:203], v[52:55]
	v_mfma_f32_16x16x32_bf16 v[48:51], v[188:191], v[200:203], v[48:51]
	v_mfma_f32_16x16x32_bf16 v[36:39], v[180:183], v[208:211], v[36:39]
	v_mfma_f32_16x16x32_bf16 v[32:35], v[188:191], v[208:211], v[32:35]
	v_mfma_f32_16x16x32_bf16 v[20:23], v[180:183], v[216:219], v[20:23]
	v_mfma_f32_16x16x32_bf16 v[16:19], v[188:191], v[216:219], v[16:19]
	v_mfma_f32_16x16x32_bf16 v[4:7], v[180:183], v[224:227], v[4:7]
	v_mfma_f32_16x16x32_bf16 v[0:3], v[188:191], v[224:227], v[0:3]
	v_mfma_f32_16x16x32_bf16 v[52:55], v[184:187], v[204:207], v[52:55]
	v_mfma_f32_16x16x32_bf16 v[48:51], v[196:199], v[204:207], v[48:51]
	v_mfma_f32_16x16x32_bf16 v[36:39], v[184:187], v[212:215], v[36:39]
	v_mfma_f32_16x16x32_bf16 v[32:35], v[196:199], v[212:215], v[32:35]
	v_mfma_f32_16x16x32_bf16 v[20:23], v[184:187], v[220:223], v[20:23]
	v_mfma_f32_16x16x32_bf16 v[16:19], v[196:199], v[220:223], v[16:19]
	v_mfma_f32_16x16x32_bf16 v[4:7], v[184:187], v[228:231], v[4:7]
	v_mfma_f32_16x16x32_bf16 v[0:3], v[196:199], v[228:231], v[0:3]
	s_barrier
; #define PG8_STAGE(bufoff, gbase, voff) do { _Pragma("unroll") for (int _i = 0; _i < 2; ++_i) \
;         __builtin_amdgcn_global_load_lds((const unsigned*)((const char*)(gbase) + (voff)[_i]), (PG8_LAS unsigned*)(lds + (bufoff) + ldsw + _i * 8192), 16, 0, 0); } while (0)
; #define PG8_LDA(dst, b, h) do { _Pragma("unroll") for (int m = 0; m < 4; ++m) _Pragma("unroll") for (int k = 0; k < 2; ++k) dst[m][k] = *(const PG8_LAS bf16x8*)(lds + PG8_SA(b, h) + aoff + m * 2048 + k * 1024); } while (0)
; #define PG8_LDB(dst, b, h) do { _Pragma("unroll") for (int n = 0; n < 2; ++n) _Pragma("unroll") for (int k = 0; k < 2; ++k) dst[n][k] = *(const PG8_LAS bf16x8*)(lds + PG8_SB(b, h) + boff + n * 2048 + k * 1024); } while (0)
; #define PG8_MMA(ai, bj, At, Bt) do { __builtin_amdgcn_s_setprio(1); _Pragma("unroll") for (int m = 0; m < 4; ++m) _Pragma("unroll") for (int n = 0; n < 2; ++n) _Pragma("unroll") for (int k = 0; k < 2; ++k) \
;         acc[ai][bj][m][n] = __builtin_amdgcn_mfma_f32_16x16x32_bf16(Bt[n][k], At[m][k], acc[ai][bj][m][n], 0, 0, 0); __builtin_amdgcn_s_setprio(0); } while (0)
; #define PG8_WAIT_V(n) asm volatile("s_waitcnt vmcnt(" #n ")" ::: "memory")
; #define PG8_WAIT_L(n) asm volatile("s_waitcnt lgkmcnt(" #n ")" ::: "memory")
; #define PG8_BAR __builtin_amdgcn_s_barrier()
; #define PG8_SCHED __builtin_amdgcn_sched_barrier(0)
; template <class Epi, class Sched, bool ALIGN_EPI = false, bool SP2 = false>
; __device__ __forceinline__ void gemm_phase(PG8_LAS unsigned char* lds, const Gemm g, const Sched& S, const Epi& E) {
;     ...
;             PG8_LDB(B0, 1, 0); PG8_LDB(B1, 1, 1); PG8_SCHED; PG8_LDA(At, 1, 0); PG8_STAGE(PG8_SA(0, 1), a2 + hstep, voffA);
;             PG8_WAIT_V(8); PG8_WAIT_L(0); PG8_BAR; PG8_MMA(0, 0, At, B0); PG8_MMA(0, 1, At, B1); PG8_BAR; PG8_SCHED;
;             PG8_LDA(At, 1, 1); PG8_STAGE(PG8_SB(1, 0), b3, voffB); PG8_STAGE(PG8_SB(1, 1), b3 + hstep, voffB); PG8_STAGE(PG8_SA(1, 0), a3, voffA);
;             PG8_WAIT_V(8); PG8_WAIT_L(0); PG8_BAR; PG8_MMA(1, 0, At, B0); PG8_MMA(1, 1, At, B1); PG8_BAR; PG8_SCHED;
	s_add_i32 s73, 0, 0x18000
	s_add_i32 s82, 0, 0x1c000
	ds_read_b128 v[152:155], v244
	ds_read_b128 v[156:159], v244 offset:1024
	ds_read_b128 v[166:169], v244 offset:2048
	ds_read_b128 v[176:179], v244 offset:3072
	ds_read_b128 v[180:183], v245
	ds_read_b128 v[184:187], v245 offset:1024
	ds_read_b128 v[188:191], v245 offset:2048
	ds_read_b128 v[196:199], v245 offset:3072
	s_add_u32 s6, s80, 0x40000
	s_addc_u32 s7, s81, 0
	s_mov_b32 m0, s37
	ds_read_b128 v[200:203], v174 offset:32768
	ds_read_b128 v[204:207], v174 offset:33792
	ds_read_b128 v[208:211], v174 offset:34816
	ds_read_b128 v[212:215], v174 offset:35840
	ds_read_b128 v[216:219], v174 offset:36864
	ds_read_b128 v[220:223], v174 offset:37888
	ds_read_b128 v[224:227], v174 offset:38912
	ds_read_b128 v[228:231], v174 offset:39936
	global_load_lds_dwordx4 v132, s[6:7]
	s_mov_b32 m0, s42
	s_nop 0
	global_load_lds_dwordx4 v136, s[6:7]
	s_waitcnt vmcnt(8)
	s_waitcnt lgkmcnt(0)
	s_barrier
	s_waitcnt lgkmcnt(0)
	v_mfma_f32_16x16x32_bf16 v[124:127], v[152:155], v[200:203], v[124:127]
	v_mfma_f32_16x16x32_bf16 v[120:123], v[166:169], v[200:203], v[120:123]
	v_mfma_f32_16x16x32_bf16 v[108:111], v[152:155], v[208:211], v[108:111]
	v_mfma_f32_16x16x32_bf16 v[104:107], v[166:169], v[208:211], v[104:107]
	v_mfma_f32_16x16x32_bf16 v[92:95], v[152:155], v[216:219], v[92:95]
	v_mfma_f32_16x16x32_bf16 v[88:91], v[166:169], v[216:219], v[88:91]
	v_mfma_f32_16x16x32_bf16 v[76:79], v[152:155], v[224:227], v[76:79]
	v_mfma_f32_16x16x32_bf16 v[72:75], v[166:169], v[224:227], v[72:75]
	v_mfma_f32_16x16x32_bf16 v[124:127], v[156:159], v[204:207], v[124:127]
	v_mfma_f32_16x16x32_bf16 v[120:123], v[176:179], v[204:207], v[120:123]
	v_mfma_f32_16x16x32_bf16 v[108:111], v[156:159], v[212:215], v[108:111]
	v_mfma_f32_16x16x32_bf16 v[104:107], v[176:179], v[212:215], v[104:107]
	v_mfma_f32_16x16x32_bf16 v[92:95], v[156:159], v[220:223], v[92:95]
	v_mfma_f32_16x16x32_bf16 v[88:91], v[176:179], v[220:223], v[88:91]
	v_mfma_f32_16x16x32_bf16 v[76:79], v[156:159], v[228:231], v[76:79]
	v_mfma_f32_16x16x32_bf16 v[72:75], v[176:179], v[228:231], v[72:75]
	v_mfma_f32_16x16x32_bf16 v[116:119], v[180:183], v[200:203], v[116:119]
	v_mfma_f32_16x16x32_bf16 v[112:115], v[188:191], v[200:203], v[112:115]
	v_mfma_f32_16x16x32_bf16 v[100:103], v[180:183], v[208:211], v[100:103]
	v_mfma_f32_16x16x32_bf16 v[96:99], v[188:191], v[208:211], v[96:99]
	v_mfma_f32_16x16x32_bf16 v[84:87], v[180:183], v[216:219], v[84:87]
	v_mfma_f32_16x16x32_bf16 v[80:83], v[188:191], v[216:219], v[80:83]
	v_mfma_f32_16x16x32_bf16 v[68:71], v[180:183], v[224:227], v[68:71]
	v_mfma_f32_16x16x32_bf16 v[64:67], v[188:191], v[224:227], v[64:67]
	v_mfma_f32_16x16x32_bf16 v[116:119], v[184:187], v[204:207], v[116:119]
	v_mfma_f32_16x16x32_bf16 v[112:115], v[196:199], v[204:207], v[112:115]
	v_mfma_f32_16x16x32_bf16 v[100:103], v[184:187], v[212:215], v[100:103]
	v_mfma_f32_16x16x32_bf16 v[96:99], v[196:199], v[212:215], v[96:99]
	v_mfma_f32_16x16x32_bf16 v[84:87], v[184:187], v[220:223], v[84:87]
	v_mfma_f32_16x16x32_bf16 v[80:83], v[196:199], v[220:223], v[80:83]
	v_mfma_f32_16x16x32_bf16 v[68:71], v[184:187], v[228:231], v[68:71]
	v_mfma_f32_16x16x32_bf16 v[64:67], v[196:199], v[228:231], v[64:67]
	s_barrier
	s_add_i32 s6, s73, s30
	s_add_u32 s98, s78, 0x80
	s_addc_u32 s99, s79, 0
	s_add_u32 s100, s80, 0x80
	s_addc_u32 s101, s81, 0
	s_mov_b32 m0, s6
	ds_read_b128 v[200:203], v174 offset:49152
	ds_read_b128 v[204:207], v174 offset:50176
	ds_read_b128 v[208:211], v174 offset:51200
	ds_read_b128 v[212:215], v174 offset:52224
	ds_read_b128 v[216:219], v174 offset:53248
	ds_read_b128 v[220:223], v174 offset:54272
	ds_read_b128 v[224:227], v174 offset:55296
	ds_read_b128 v[228:231], v174 offset:56320
	global_load_lds_dwordx4 v134, s[98:99]
	s_add_i32 m0, s6, 0x2000
	s_add_u32 s6, s78, 0x40080
	s_addc_u32 s7, s79, 0
	s_add_i32 s73, s82, s30
	global_load_lds_dwordx4 v138, s[98:99]
	s_mov_b32 m0, s73
	s_nop 0
	global_load_lds_dwordx4 v134, s[6:7]
	s_add_i32 m0, s73, 0x2000
	s_nop 0
	global_load_lds_dwordx4 v138, s[6:7]
	s_mov_b32 m0, s67
	s_nop 0
	global_load_lds_dwordx4 v132, s[100:101]
	s_mov_b32 m0, s68
	s_nop 0
	global_load_lds_dwordx4 v136, s[100:101]
	s_waitcnt vmcnt(8)
	s_waitcnt lgkmcnt(0)
	s_barrier
	s_waitcnt lgkmcnt(0)
	v_mfma_f32_16x16x32_bf16 v[60:63], v[152:155], v[200:203], v[60:63]
	v_mfma_f32_16x16x32_bf16 v[56:59], v[166:169], v[200:203], v[56:59]
	v_mfma_f32_16x16x32_bf16 v[44:47], v[152:155], v[208:211], v[44:47]
	v_mfma_f32_16x16x32_bf16 v[40:43], v[166:169], v[208:211], v[40:43]
	v_mfma_f32_16x16x32_bf16 v[28:31], v[152:155], v[216:219], v[28:31]
	v_mfma_f32_16x16x32_bf16 v[24:27], v[166:169], v[216:219], v[24:27]
	v_mfma_f32_16x16x32_bf16 v[12:15], v[152:155], v[224:227], v[12:15]
	v_mfma_f32_16x16x32_bf16 v[8:11], v[166:169], v[224:227], v[8:11]
	v_mfma_f32_16x16x32_bf16 v[60:63], v[156:159], v[204:207], v[60:63]
	v_mfma_f32_16x16x32_bf16 v[56:59], v[176:179], v[204:207], v[56:59]
	v_mfma_f32_16x16x32_bf16 v[44:47], v[156:159], v[212:215], v[44:47]
	v_mfma_f32_16x16x32_bf16 v[40:43], v[176:179], v[212:215], v[40:43]
	v_mfma_f32_16x16x32_bf16 v[28:31], v[156:159], v[220:223], v[28:31]
	v_mfma_f32_16x16x32_bf16 v[24:27], v[176:179], v[220:223], v[24:27]
	v_mfma_f32_16x16x32_bf16 v[12:15], v[156:159], v[228:231], v[12:15]
	v_mfma_f32_16x16x32_bf16 v[8:11], v[176:179], v[228:231], v[8:11]
	v_mfma_f32_16x16x32_bf16 v[52:55], v[180:183], v[200:203], v[52:55]
	v_mfma_f32_16x16x32_bf16 v[48:51], v[188:191], v[200:203], v[48:51]
	v_mfma_f32_16x16x32_bf16 v[36:39], v[180:183], v[208:211], v[36:39]
	v_mfma_f32_16x16x32_bf16 v[32:35], v[188:191], v[208:211], v[32:35]
	v_mfma_f32_16x16x32_bf16 v[20:23], v[180:183], v[216:219], v[20:23]
	v_mfma_f32_16x16x32_bf16 v[16:19], v[188:191], v[216:219], v[16:19]
	v_mfma_f32_16x16x32_bf16 v[4:7], v[180:183], v[224:227], v[4:7]
	v_mfma_f32_16x16x32_bf16 v[0:3], v[188:191], v[224:227], v[0:3]
	v_mfma_f32_16x16x32_bf16 v[52:55], v[184:187], v[204:207], v[52:55]
	v_mfma_f32_16x16x32_bf16 v[48:51], v[196:199], v[204:207], v[48:51]
	v_mfma_f32_16x16x32_bf16 v[36:39], v[184:187], v[212:215], v[36:39]
	v_mfma_f32_16x16x32_bf16 v[32:35], v[196:199], v[212:215], v[32:35]
	v_mfma_f32_16x16x32_bf16 v[20:23], v[184:187], v[220:223], v[20:23]
	v_mfma_f32_16x16x32_bf16 v[16:19], v[196:199], v[220:223], v[16:19]
	v_mfma_f32_16x16x32_bf16 v[4:7], v[184:187], v[228:231], v[4:7]
	v_mfma_f32_16x16x32_bf16 v[0:3], v[196:199], v[228:231], v[0:3]
	s_barrier
	s_add_i32 s72, s72, 2
	s_add_u32 s60, s60, 0x100
	s_addc_u32 s61, s61, 0
	s_add_u32 vcc_hi, vcc_hi, 0x100
	s_addc_u32 s33, s33, 0
	s_cmp_gt_u32 s72, 13
	s_cbranch_scc0 .LBB0_463
	s_and_b64 vcc, exec, s[50:51]
	s_cbranch_vccz .LBB0_466
	s_barrier

; #define PG8_STAGE(bufoff, gbase, voff) do { _Pragma("unroll") for (int _i = 0; _i < 2; ++_i) \
;         __builtin_amdgcn_global_load_lds((const unsigned*)((const char*)(gbase) + (voff)[_i]), (PG8_LAS unsigned*)(lds + (bufoff) + ldsw + _i * 8192), 16, 0, 0); } while (0)
; #define PG8_LDA(dst, b, h) do { _Pragma("unroll") for (int m = 0; m < 4; ++m) _Pragma("unroll") for (int k = 0; k < 2; ++k) dst[m][k] = *(const PG8_LAS bf16x8*)(lds + PG8_SA(b, h) + aoff + m * 2048 + k * 1024); } while (0)
; #define PG8_LDB(dst, b, h) do { _Pragma("unroll") for (int n = 0; n < 2; ++n) _Pragma("unroll") for (int k = 0; k < 2; ++k) dst[n][k] = *(const PG8_LAS bf16x8*)(lds + PG8_SB(b, h) + boff + n * 2048 + k * 1024); } while (0)
; #define PG8_MMA(ai, bj, At, Bt) do { __builtin_amdgcn_s_setprio(1); _Pragma("unroll") for (int m = 0; m < 4; ++m) _Pragma("unroll") for (int n = 0; n < 2; ++n) _Pragma("unroll") for (int k = 0; k < 2; ++k) \
;         acc[ai][bj][m][n] = __builtin_amdgcn_mfma_f32_16x16x32_bf16(Bt[n][k], At[m][k], acc[ai][bj][m][n], 0, 0, 0); __builtin_amdgcn_s_setprio(0); } while (0)
; #define PG8_WAIT_V(n) asm volatile("s_waitcnt vmcnt(" #n ")" ::: "memory")
; #define PG8_WAIT_L(n) asm volatile("s_waitcnt lgkmcnt(" #n ")" ::: "memory")
; #define PG8_BAR __builtin_amdgcn_s_barrier()
; template <class Epi, class Sched, bool ALIGN_EPI = false, bool SP2 = false>
; __device__ __forceinline__ void gemm_phase(PG8_LAS unsigned char* lds, const Gemm g, const Sched& S, const Epi& E) {
;     ...
;             const char* a1 = cA + (size_t)(t + 1) * kstep;
;             const char* a2 = last ? nA : cA + (size_t)(t + 2) * kstep; const char* b2 = last ? nB : cB + (size_t)(t + 2) * kstep;
;             const char* a3 = a2 + kstep; const char* b3 = b2 + kstep;
;             if (last && has_next) S.a_ready(nxt);
;             if constexpr (SP2) {
;             PG8_LDB(B0, 0, 0); PG8_LDB(B1, 0, 1); PG8_SCHED; PG8_LDA(At, 0, 0); PG8_STAGE(PG8_SA(1, 1), a1 + hstep, voffA);
;             PG8_WAIT_V(8); PG8_WAIT_L(0); PG8_BAR; PG8_MMA(0, 0, At, B0); PG8_MMA(0, 1, At, B1); PG8_BAR; PG8_SCHED;
;     ...
; #pragma unroll
;         for (int a = 0; a < 2; ++a)
; #pragma unroll
;             for (int b = 0; b < 2; ++b)
; #pragma unroll
;                 for (int m = 0; m < 4; ++m)
; #pragma unroll
;                     for (int n = 0; n < 2; ++n) acc[a][b][m][n] = (f32x4){0.f, 0.f, 0.f, 0.f};
.LBB0_776:
	s_add_u32 s33, s60, 0x100
	v_mov_b32_e32 v0, 0
	s_addc_u32 vcc_lo, s61, 0
	s_mov_b32 s72, -2
	s_waitcnt lgkmcnt(0)
	v_mov_b32_e32 v1, v0
	v_mov_b32_e32 v2, v0
	v_mov_b32_e32 v3, v0
	v_mov_b32_e32 v4, v0
	v_mov_b32_e32 v5, v0
	v_mov_b32_e32 v6, v0
	v_mov_b32_e32 v7, v0
	v_mov_b32_e32 v16, v0
	v_mov_b32_e32 v17, v0
	v_mov_b32_e32 v18, v0
	v_mov_b32_e32 v19, v0
	v_mov_b32_e32 v20, v0
	v_mov_b32_e32 v21, v0
	v_mov_b32_e32 v22, v0
	v_mov_b32_e32 v23, v0
	v_mov_b32_e32 v32, v0
	v_mov_b32_e32 v33, v0
	v_mov_b32_e32 v34, v0
	v_mov_b32_e32 v35, v0
	v_mov_b32_e32 v36, v0
	v_mov_b32_e32 v37, v0
	v_mov_b32_e32 v38, v0
	v_mov_b32_e32 v39, v0
	v_mov_b32_e32 v48, v0
	v_mov_b32_e32 v49, v0
	v_mov_b32_e32 v50, v0
	v_mov_b32_e32 v51, v0
	v_mov_b32_e32 v52, v0
	v_mov_b32_e32 v53, v0
	v_mov_b32_e32 v54, v0
	v_mov_b32_e32 v55, v0
	v_mov_b32_e32 v8, v0
	v_mov_b32_e32 v9, v0
	v_mov_b32_e32 v10, v0
	v_mov_b32_e32 v11, v0
	v_mov_b32_e32 v12, v0
	v_mov_b32_e32 v13, v0
	v_mov_b32_e32 v14, v0
	v_mov_b32_e32 v15, v0
	v_mov_b32_e32 v24, v0
	v_mov_b32_e32 v25, v0
	v_mov_b32_e32 v26, v0
	v_mov_b32_e32 v27, v0
	v_mov_b32_e32 v28, v0
	v_mov_b32_e32 v29, v0
	v_mov_b32_e32 v30, v0
	v_mov_b32_e32 v31, v0
	v_mov_b32_e32 v40, v0
	v_mov_b32_e32 v41, v0
	v_mov_b32_e32 v42, v0
	v_mov_b32_e32 v43, v0
	v_mov_b32_e32 v44, v0
	v_mov_b32_e32 v45, v0
	v_mov_b32_e32 v46, v0
	v_mov_b32_e32 v47, v0
	v_mov_b32_e32 v56, v0
	v_mov_b32_e32 v57, v0
	v_mov_b32_e32 v58, v0
	v_mov_b32_e32 v59, v0
	v_mov_b32_e32 v60, v0
	v_mov_b32_e32 v61, v0
	v_mov_b32_e32 v62, v0
	v_mov_b32_e32 v63, v0
	v_mov_b32_e32 v64, v0
	v_mov_b32_e32 v65, v0
	v_mov_b32_e32 v66, v0
	v_mov_b32_e32 v67, v0
	v_mov_b32_e32 v68, v0
	v_mov_b32_e32 v69, v0
	v_mov_b32_e32 v70, v0
	v_mov_b32_e32 v71, v0
	v_mov_b32_e32 v80, v0
	v_mov_b32_e32 v81, v0
	v_mov_b32_e32 v82, v0
	v_mov_b32_e32 v83, v0
	v_mov_b32_e32 v84, v0
	v_mov_b32_e32 v85, v0
	v_mov_b32_e32 v86, v0
	v_mov_b32_e32 v87, v0
	v_mov_b32_e32 v96, v0
	v_mov_b32_e32 v97, v0
	v_mov_b32_e32 v98, v0
	v_mov_b32_e32 v99, v0
	v_mov_b32_e32 v100, v0
	v_mov_b32_e32 v101, v0
	v_mov_b32_e32 v102, v0
	v_mov_b32_e32 v103, v0
	v_mov_b32_e32 v112, v0
	v_mov_b32_e32 v113, v0
	v_mov_b32_e32 v114, v0
	v_mov_b32_e32 v115, v0
	v_mov_b32_e32 v116, v0
	v_mov_b32_e32 v117, v0
	v_mov_b32_e32 v118, v0
	v_mov_b32_e32 v119, v0
	v_mov_b32_e32 v72, v0
	v_mov_b32_e32 v73, v0
	v_mov_b32_e32 v74, v0
	v_mov_b32_e32 v75, v0
	v_mov_b32_e32 v76, v0
	v_mov_b32_e32 v77, v0
	v_mov_b32_e32 v78, v0
	v_mov_b32_e32 v79, v0
	v_mov_b32_e32 v88, v0
	v_mov_b32_e32 v89, v0
	v_mov_b32_e32 v90, v0
	v_mov_b32_e32 v91, v0
	v_mov_b32_e32 v92, v0
	v_mov_b32_e32 v93, v0
	v_mov_b32_e32 v94, v0
	v_mov_b32_e32 v95, v0
	v_mov_b32_e32 v104, v0
	v_mov_b32_e32 v105, v0
	v_mov_b32_e32 v106, v0
	v_mov_b32_e32 v107, v0
	v_mov_b32_e32 v108, v0
	v_mov_b32_e32 v109, v0
	v_mov_b32_e32 v110, v0
	v_mov_b32_e32 v111, v0
	v_mov_b32_e32 v120, v0
	v_mov_b32_e32 v121, v0
	v_mov_b32_e32 v122, v0
	v_mov_b32_e32 v123, v0
	v_mov_b32_e32 v124, v0
	v_mov_b32_e32 v125, v0
	v_mov_b32_e32 v126, v0
	v_mov_b32_e32 v127, v0
	v_add_u32_e32 v244, 0x18000, v156
	v_add_u32_e32 v245, 0x1c000, v156
.LBB0_777:
	ds_read_b128 v[144:147], v158
	ds_read_b128 v[168:171], v158 offset:1024
	ds_read_b128 v[172:175], v158 offset:2048
	ds_read_b128 v[176:179], v158 offset:3072
	ds_read_b128 v[180:183], v159
	ds_read_b128 v[184:187], v159 offset:1024
	ds_read_b128 v[188:191], v159 offset:2048
	ds_read_b128 v[196:199], v159 offset:3072
	s_add_u32 s60, s58, 0x100
	s_addc_u32 s61, s59, 0
	s_cmp_eq_u32 s72, 8
	s_cselect_b32 s81, s49, s61
	s_cselect_b32 s80, s48, s60
	s_cselect_b32 s79, s57, vcc_lo
	s_cselect_b32 s78, s56, s33
	s_add_i32 m0, s76, 0xc000
	ds_read_b128 v[200:203], v163
	ds_read_b128 v[204:207], v163 offset:1024
	ds_read_b128 v[208:211], v163 offset:2048
	ds_read_b128 v[212:215], v163 offset:3072
	ds_read_b128 v[216:219], v163 offset:4096
	ds_read_b128 v[220:223], v163 offset:5120
	ds_read_b128 v[224:227], v163 offset:6144
	ds_read_b128 v[228:231], v163 offset:7168
	global_load_lds_dwordx4 v136, s[58:59]
	s_add_i32 m0, s76, 0xe000
	s_nop 0
	global_load_lds_dwordx4 v138, s[58:59]
	s_waitcnt vmcnt(8)
	s_waitcnt lgkmcnt(0)
	s_barrier
	s_waitcnt lgkmcnt(0)
	v_mfma_f32_16x16x32_bf16 v[124:127], v[144:147], v[200:203], v[124:127]
	v_mfma_f32_16x16x32_bf16 v[120:123], v[172:175], v[200:203], v[120:123]
	v_mfma_f32_16x16x32_bf16 v[108:111], v[144:147], v[208:211], v[108:111]
	v_mfma_f32_16x16x32_bf16 v[104:107], v[172:175], v[208:211], v[104:107]
	v_mfma_f32_16x16x32_bf16 v[92:95], v[144:147], v[216:219], v[92:95]
	v_mfma_f32_16x16x32_bf16 v[88:91], v[172:175], v[216:219], v[88:91]
	v_mfma_f32_16x16x32_bf16 v[76:79], v[144:147], v[224:227], v[76:79]
	v_mfma_f32_16x16x32_bf16 v[72:75], v[172:175], v[224:227], v[72:75]
	v_mfma_f32_16x16x32_bf16 v[124:127], v[168:171], v[204:207], v[124:127]
	v_mfma_f32_16x16x32_bf16 v[120:123], v[176:179], v[204:207], v[120:123]
	v_mfma_f32_16x16x32_bf16 v[108:111], v[168:171], v[212:215], v[108:111]
	v_mfma_f32_16x16x32_bf16 v[104:107], v[176:179], v[212:215], v[104:107]
	v_mfma_f32_16x16x32_bf16 v[92:95], v[168:171], v[220:223], v[92:95]
	v_mfma_f32_16x16x32_bf16 v[88:91], v[176:179], v[220:223], v[88:91]
	v_mfma_f32_16x16x32_bf16 v[76:79], v[168:171], v[228:231], v[76:79]
	v_mfma_f32_16x16x32_bf16 v[72:75], v[176:179], v[228:231], v[72:75]
	v_mfma_f32_16x16x32_bf16 v[116:119], v[180:183], v[200:203], v[116:119]
	v_mfma_f32_16x16x32_bf16 v[112:115], v[188:191], v[200:203], v[112:115]
	v_mfma_f32_16x16x32_bf16 v[100:103], v[180:183], v[208:211], v[100:103]
	v_mfma_f32_16x16x32_bf16 v[96:99], v[188:191], v[208:211], v[96:99]
	v_mfma_f32_16x16x32_bf16 v[84:87], v[180:183], v[216:219], v[84:87]
	v_mfma_f32_16x16x32_bf16 v[80:83], v[188:191], v[216:219], v[80:83]
	v_mfma_f32_16x16x32_bf16 v[68:71], v[180:183], v[224:227], v[68:71]
	v_mfma_f32_16x16x32_bf16 v[64:67], v[188:191], v[224:227], v[64:67]
	v_mfma_f32_16x16x32_bf16 v[116:119], v[184:187], v[204:207], v[116:119]
	v_mfma_f32_16x16x32_bf16 v[112:115], v[196:199], v[204:207], v[112:115]
	v_mfma_f32_16x16x32_bf16 v[100:103], v[184:187], v[212:215], v[100:103]
	v_mfma_f32_16x16x32_bf16 v[96:99], v[196:199], v[212:215], v[96:99]
	v_mfma_f32_16x16x32_bf16 v[84:87], v[184:187], v[220:223], v[84:87]
	v_mfma_f32_16x16x32_bf16 v[80:83], v[196:199], v[220:223], v[80:83]
	v_mfma_f32_16x16x32_bf16 v[68:71], v[184:187], v[228:231], v[68:71]
	v_mfma_f32_16x16x32_bf16 v[64:67], v[196:199], v[228:231], v[64:67]
	s_barrier
; #define PG8_STAGE(bufoff, gbase, voff) do { _Pragma("unroll") for (int _i = 0; _i < 2; ++_i) \
;         __builtin_amdgcn_global_load_lds((const unsigned*)((const char*)(gbase) + (voff)[_i]), (PG8_LAS unsigned*)(lds + (bufoff) + ldsw + _i * 8192), 16, 0, 0); } while (0)
; #define PG8_LDA(dst, b, h) do { _Pragma("unroll") for (int m = 0; m < 4; ++m) _Pragma("unroll") for (int k = 0; k < 2; ++k) dst[m][k] = *(const PG8_LAS bf16x8*)(lds + PG8_SA(b, h) + aoff + m * 2048 + k * 1024); } while (0)
; #define PG8_LDB(dst, b, h) do { _Pragma("unroll") for (int n = 0; n < 2; ++n) _Pragma("unroll") for (int k = 0; k < 2; ++k) dst[n][k] = *(const PG8_LAS bf16x8*)(lds + PG8_SB(b, h) + boff + n * 2048 + k * 1024); } while (0)
; #define PG8_MMA(ai, bj, At, Bt) do { __builtin_amdgcn_s_setprio(1); _Pragma("unroll") for (int m = 0; m < 4; ++m) _Pragma("unroll") for (int n = 0; n < 2; ++n) _Pragma("unroll") for (int k = 0; k < 2; ++k) \
;         acc[ai][bj][m][n] = __builtin_amdgcn_mfma_f32_16x16x32_bf16(Bt[n][k], At[m][k], acc[ai][bj][m][n], 0, 0, 0); __builtin_amdgcn_s_setprio(0); } while (0)
; #define PG8_WAIT_V(n) asm volatile("s_waitcnt vmcnt(" #n ")" ::: "memory")
; #define PG8_WAIT_L(n) asm volatile("s_waitcnt lgkmcnt(" #n ")" ::: "memory")
; #define PG8_BAR __builtin_amdgcn_s_barrier()
; #define PG8_SCHED __builtin_amdgcn_sched_barrier(0)
; template <class Epi, class Sched, bool ALIGN_EPI = false, bool SP2 = false>
; __device__ __forceinline__ void gemm_phase(PG8_LAS unsigned char* lds, const Gemm g, const Sched& S, const Epi& E) {
;     ...
;             PG8_LDA(At, 0, 1); PG8_STAGE(PG8_SB(0, 0), b2, voffB); PG8_STAGE(PG8_SB(0, 1), b2 + hstep, voffB); PG8_STAGE(PG8_SA(0, 0), a2, voffA);
;             PG8_WAIT_V(8); PG8_WAIT_L(0); PG8_BAR; PG8_MMA(1, 0, At, B0); PG8_MMA(1, 1, At, B1); PG8_BAR; PG8_SCHED;
;             PG8_LDB(B0, 1, 0); PG8_LDB(B1, 1, 1); PG8_SCHED; PG8_LDA(At, 1, 0); PG8_STAGE(PG8_SA(0, 1), a2 + hstep, voffA);
	s_add_i32 s6, s26, s67
	s_mov_b32 m0, s6
	ds_read_b128 v[200:203], v163 offset:16384
	ds_read_b128 v[204:207], v163 offset:17408
	ds_read_b128 v[208:211], v163 offset:18432
	ds_read_b128 v[212:215], v163 offset:19456
	ds_read_b128 v[216:219], v163 offset:20480
	ds_read_b128 v[220:223], v163 offset:21504
	ds_read_b128 v[224:227], v163 offset:22528
	ds_read_b128 v[228:231], v163 offset:23552
	global_load_lds_dwordx4 v130, s[78:79]
	s_add_i32 m0, s6, 0x2000
	s_add_u32 s6, s78, 0x30000
	s_addc_u32 s7, s79, 0
	s_add_i32 s58, s74, s67
	global_load_lds_dwordx4 v134, s[78:79]
	s_mov_b32 m0, s58
	s_nop 0
	global_load_lds_dwordx4 v130, s[6:7]
	s_add_i32 m0, s58, 0x2000
	s_nop 0
	global_load_lds_dwordx4 v134, s[6:7]
	s_mov_b32 m0, s76
	s_nop 0
	global_load_lds_dwordx4 v128, s[80:81]
	s_mov_b32 m0, s77
	s_nop 0
	global_load_lds_dwordx4 v132, s[80:81]
	s_waitcnt vmcnt(8)
	s_waitcnt lgkmcnt(0)
	s_barrier
	s_waitcnt lgkmcnt(0)
	v_mfma_f32_16x16x32_bf16 v[60:63], v[144:147], v[200:203], v[60:63]
	v_mfma_f32_16x16x32_bf16 v[56:59], v[172:175], v[200:203], v[56:59]
	v_mfma_f32_16x16x32_bf16 v[44:47], v[144:147], v[208:211], v[44:47]
	v_mfma_f32_16x16x32_bf16 v[40:43], v[172:175], v[208:211], v[40:43]
	v_mfma_f32_16x16x32_bf16 v[28:31], v[144:147], v[216:219], v[28:31]
	v_mfma_f32_16x16x32_bf16 v[24:27], v[172:175], v[216:219], v[24:27]
	v_mfma_f32_16x16x32_bf16 v[12:15], v[144:147], v[224:227], v[12:15]
	v_mfma_f32_16x16x32_bf16 v[8:11], v[172:175], v[224:227], v[8:11]
	v_mfma_f32_16x16x32_bf16 v[60:63], v[168:171], v[204:207], v[60:63]
	v_mfma_f32_16x16x32_bf16 v[56:59], v[176:179], v[204:207], v[56:59]
	v_mfma_f32_16x16x32_bf16 v[44:47], v[168:171], v[212:215], v[44:47]
	v_mfma_f32_16x16x32_bf16 v[40:43], v[176:179], v[212:215], v[40:43]
	v_mfma_f32_16x16x32_bf16 v[28:31], v[168:171], v[220:223], v[28:31]
	v_mfma_f32_16x16x32_bf16 v[24:27], v[176:179], v[220:223], v[24:27]
	v_mfma_f32_16x16x32_bf16 v[12:15], v[168:171], v[228:231], v[12:15]
	v_mfma_f32_16x16x32_bf16 v[8:11], v[176:179], v[228:231], v[8:11]
	v_mfma_f32_16x16x32_bf16 v[52:55], v[180:183], v[200:203], v[52:55]
	v_mfma_f32_16x16x32_bf16 v[48:51], v[188:191], v[200:203], v[48:51]
	v_mfma_f32_16x16x32_bf16 v[36:39], v[180:183], v[208:211], v[36:39]
	v_mfma_f32_16x16x32_bf16 v[32:35], v[188:191], v[208:211], v[32:35]
	v_mfma_f32_16x16x32_bf16 v[20:23], v[180:183], v[216:219], v[20:23]
	v_mfma_f32_16x16x32_bf16 v[16:19], v[188:191], v[216:219], v[16:19]
	v_mfma_f32_16x16x32_bf16 v[4:7], v[180:183], v[224:227], v[4:7]
	v_mfma_f32_16x16x32_bf16 v[0:3], v[188:191], v[224:227], v[0:3]
	v_mfma_f32_16x16x32_bf16 v[52:55], v[184:187], v[204:207], v[52:55]
	v_mfma_f32_16x16x32_bf16 v[48:51], v[196:199], v[204:207], v[48:51]
	v_mfma_f32_16x16x32_bf16 v[36:39], v[184:187], v[212:215], v[36:39]
	v_mfma_f32_16x16x32_bf16 v[32:35], v[196:199], v[212:215], v[32:35]
	v_mfma_f32_16x16x32_bf16 v[20:23], v[184:187], v[220:223], v[20:23]
	v_mfma_f32_16x16x32_bf16 v[16:19], v[196:199], v[220:223], v[16:19]
	v_mfma_f32_16x16x32_bf16 v[4:7], v[184:187], v[228:231], v[4:7]
	v_mfma_f32_16x16x32_bf16 v[0:3], v[196:199], v[228:231], v[0:3]
	s_barrier
	s_add_i32 s58, 0, 0x18000
	s_add_i32 s59, 0, 0x1c000
	ds_read_b128 v[144:147], v244
	ds_read_b128 v[168:171], v244 offset:1024
	ds_read_b128 v[172:175], v244 offset:2048
	ds_read_b128 v[176:179], v244 offset:3072
	ds_read_b128 v[180:183], v245
	ds_read_b128 v[184:187], v245 offset:1024
	ds_read_b128 v[188:191], v245 offset:2048
	ds_read_b128 v[196:199], v245 offset:3072
	s_add_u32 s6, s80, 0x30000
	s_addc_u32 s7, s81, 0
	s_mov_b32 m0, s36
	ds_read_b128 v[200:203], v163 offset:32768
	ds_read_b128 v[204:207], v163 offset:33792
	ds_read_b128 v[208:211], v163 offset:34816
	ds_read_b128 v[212:215], v163 offset:35840
	ds_read_b128 v[216:219], v163 offset:36864
	ds_read_b128 v[220:223], v163 offset:37888
	ds_read_b128 v[224:227], v163 offset:38912
	ds_read_b128 v[228:231], v163 offset:39936
	global_load_lds_dwordx4 v128, s[6:7]
	s_mov_b32 m0, s37
	s_nop 0
	global_load_lds_dwordx4 v132, s[6:7]
	s_waitcnt vmcnt(8)
	s_waitcnt lgkmcnt(0)
	s_barrier
; #define PG8_STAGE(bufoff, gbase, voff) do { _Pragma("unroll") for (int _i = 0; _i < 2; ++_i) \
;         __builtin_amdgcn_global_load_lds((const unsigned*)((const char*)(gbase) + (voff)[_i]), (PG8_LAS unsigned*)(lds + (bufoff) + ldsw + _i * 8192), 16, 0, 0); } while (0)
; #define PG8_LDA(dst, b, h) do { _Pragma("unroll") for (int m = 0; m < 4; ++m) _Pragma("unroll") for (int k = 0; k < 2; ++k) dst[m][k] = *(const PG8_LAS bf16x8*)(lds + PG8_SA(b, h) + aoff + m * 2048 + k * 1024); } while (0)
; #define PG8_MMA(ai, bj, At, Bt) do { __builtin_amdgcn_s_setprio(1); _Pragma("unroll") for (int m = 0; m < 4; ++m) _Pragma("unroll") for (int n = 0; n < 2; ++n) _Pragma("unroll") for (int k = 0; k < 2; ++k) \
;         acc[ai][bj][m][n] = __builtin_amdgcn_mfma_f32_16x16x32_bf16(Bt[n][k], At[m][k], acc[ai][bj][m][n], 0, 0, 0); __builtin_amdgcn_s_setprio(0); } while (0)
; #define PG8_WAIT_V(n) asm volatile("s_waitcnt vmcnt(" #n ")" ::: "memory")
; #define PG8_WAIT_L(n) asm volatile("s_waitcnt lgkmcnt(" #n ")" ::: "memory")
; #define PG8_BAR __builtin_amdgcn_s_barrier()
; #define PG8_SCHED __builtin_amdgcn_sched_barrier(0)
; template <class Epi, class Sched, bool ALIGN_EPI = false, bool SP2 = false>
; __device__ __forceinline__ void gemm_phase(PG8_LAS unsigned char* lds, const Gemm g, const Sched& S, const Epi& E) {
;     ...
;             PG8_WAIT_V(8); PG8_WAIT_L(0); PG8_BAR; PG8_MMA(0, 0, At, B0); PG8_MMA(0, 1, At, B1); PG8_BAR; PG8_SCHED;
;             PG8_LDA(At, 1, 1); PG8_STAGE(PG8_SB(1, 0), b3, voffB); PG8_STAGE(PG8_SB(1, 1), b3 + hstep, voffB); PG8_STAGE(PG8_SA(1, 0), a3, voffA);
;             PG8_WAIT_V(8); PG8_WAIT_L(0); PG8_BAR; PG8_MMA(1, 0, At, B0); PG8_MMA(1, 1, At, B1); PG8_BAR; PG8_SCHED;
	s_waitcnt lgkmcnt(0)
	v_mfma_f32_16x16x32_bf16 v[124:127], v[144:147], v[200:203], v[124:127]
	v_mfma_f32_16x16x32_bf16 v[120:123], v[172:175], v[200:203], v[120:123]
	v_mfma_f32_16x16x32_bf16 v[108:111], v[144:147], v[208:211], v[108:111]
	v_mfma_f32_16x16x32_bf16 v[104:107], v[172:175], v[208:211], v[104:107]
	v_mfma_f32_16x16x32_bf16 v[92:95], v[144:147], v[216:219], v[92:95]
	v_mfma_f32_16x16x32_bf16 v[88:91], v[172:175], v[216:219], v[88:91]
	v_mfma_f32_16x16x32_bf16 v[76:79], v[144:147], v[224:227], v[76:79]
	v_mfma_f32_16x16x32_bf16 v[72:75], v[172:175], v[224:227], v[72:75]
	v_mfma_f32_16x16x32_bf16 v[124:127], v[168:171], v[204:207], v[124:127]
	v_mfma_f32_16x16x32_bf16 v[120:123], v[176:179], v[204:207], v[120:123]
	v_mfma_f32_16x16x32_bf16 v[108:111], v[168:171], v[212:215], v[108:111]
	v_mfma_f32_16x16x32_bf16 v[104:107], v[176:179], v[212:215], v[104:107]
	v_mfma_f32_16x16x32_bf16 v[92:95], v[168:171], v[220:223], v[92:95]
	v_mfma_f32_16x16x32_bf16 v[88:91], v[176:179], v[220:223], v[88:91]
	v_mfma_f32_16x16x32_bf16 v[76:79], v[168:171], v[228:231], v[76:79]
	v_mfma_f32_16x16x32_bf16 v[72:75], v[176:179], v[228:231], v[72:75]
	v_mfma_f32_16x16x32_bf16 v[116:119], v[180:183], v[200:203], v[116:119]
	v_mfma_f32_16x16x32_bf16 v[112:115], v[188:191], v[200:203], v[112:115]
	v_mfma_f32_16x16x32_bf16 v[100:103], v[180:183], v[208:211], v[100:103]
	v_mfma_f32_16x16x32_bf16 v[96:99], v[188:191], v[208:211], v[96:99]
	v_mfma_f32_16x16x32_bf16 v[84:87], v[180:183], v[216:219], v[84:87]
	v_mfma_f32_16x16x32_bf16 v[80:83], v[188:191], v[216:219], v[80:83]
	v_mfma_f32_16x16x32_bf16 v[68:71], v[180:183], v[224:227], v[68:71]
	v_mfma_f32_16x16x32_bf16 v[64:67], v[188:191], v[224:227], v[64:67]
	v_mfma_f32_16x16x32_bf16 v[116:119], v[184:187], v[204:207], v[116:119]
	v_mfma_f32_16x16x32_bf16 v[112:115], v[196:199], v[204:207], v[112:115]
	v_mfma_f32_16x16x32_bf16 v[100:103], v[184:187], v[212:215], v[100:103]
	v_mfma_f32_16x16x32_bf16 v[96:99], v[196:199], v[212:215], v[96:99]
	v_mfma_f32_16x16x32_bf16 v[84:87], v[184:187], v[220:223], v[84:87]
	v_mfma_f32_16x16x32_bf16 v[80:83], v[196:199], v[220:223], v[80:83]
	v_mfma_f32_16x16x32_bf16 v[68:71], v[184:187], v[228:231], v[68:71]
	v_mfma_f32_16x16x32_bf16 v[64:67], v[196:199], v[228:231], v[64:67]
	s_barrier
	s_add_i32 s6, s58, s67
	s_add_u32 s98, s78, 0x80
	s_addc_u32 s99, s79, 0
	s_add_u32 s100, s80, 0x80
	s_addc_u32 s101, s81, 0
	s_mov_b32 m0, s6
	ds_read_b128 v[200:203], v163 offset:49152
	ds_read_b128 v[204:207], v163 offset:50176
	ds_read_b128 v[208:211], v163 offset:51200
	ds_read_b128 v[212:215], v163 offset:52224
	ds_read_b128 v[216:219], v163 offset:53248
	ds_read_b128 v[220:223], v163 offset:54272
	ds_read_b128 v[224:227], v163 offset:55296
	ds_read_b128 v[228:231], v163 offset:56320
	global_load_lds_dwordx4 v130, s[98:99]
	s_add_i32 m0, s6, 0x2000
	s_add_u32 s6, s78, 0x30080
	s_addc_u32 s7, s79, 0
	s_add_i32 s58, s59, s67
	global_load_lds_dwordx4 v134, s[98:99]
	s_mov_b32 m0, s58
	s_nop 0
	global_load_lds_dwordx4 v130, s[6:7]
	s_add_i32 m0, s58, 0x2000
	s_nop 0
	global_load_lds_dwordx4 v134, s[6:7]
	s_mov_b32 m0, s31
	s_nop 0
	global_load_lds_dwordx4 v128, s[100:101]
	s_mov_b32 m0, s4
	s_nop 0
	global_load_lds_dwordx4 v132, s[100:101]
	s_waitcnt vmcnt(8)
	s_waitcnt lgkmcnt(0)
	s_barrier
	s_waitcnt lgkmcnt(0)
	v_mfma_f32_16x16x32_bf16 v[60:63], v[144:147], v[200:203], v[60:63]
	v_mfma_f32_16x16x32_bf16 v[56:59], v[172:175], v[200:203], v[56:59]
	v_mfma_f32_16x16x32_bf16 v[44:47], v[144:147], v[208:211], v[44:47]
	v_mfma_f32_16x16x32_bf16 v[40:43], v[172:175], v[208:211], v[40:43]
	v_mfma_f32_16x16x32_bf16 v[28:31], v[144:147], v[216:219], v[28:31]
	v_mfma_f32_16x16x32_bf16 v[24:27], v[172:175], v[216:219], v[24:27]
	v_mfma_f32_16x16x32_bf16 v[12:15], v[144:147], v[224:227], v[12:15]
	v_mfma_f32_16x16x32_bf16 v[8:11], v[172:175], v[224:227], v[8:11]
	v_mfma_f32_16x16x32_bf16 v[60:63], v[168:171], v[204:207], v[60:63]
	v_mfma_f32_16x16x32_bf16 v[56:59], v[176:179], v[204:207], v[56:59]
	v_mfma_f32_16x16x32_bf16 v[44:47], v[168:171], v[212:215], v[44:47]
	v_mfma_f32_16x16x32_bf16 v[40:43], v[176:179], v[212:215], v[40:43]
	v_mfma_f32_16x16x32_bf16 v[28:31], v[168:171], v[220:223], v[28:31]
	v_mfma_f32_16x16x32_bf16 v[24:27], v[176:179], v[220:223], v[24:27]
	v_mfma_f32_16x16x32_bf16 v[12:15], v[168:171], v[228:231], v[12:15]
	v_mfma_f32_16x16x32_bf16 v[8:11], v[176:179], v[228:231], v[8:11]
	v_mfma_f32_16x16x32_bf16 v[52:55], v[180:183], v[200:203], v[52:55]
	v_mfma_f32_16x16x32_bf16 v[48:51], v[188:191], v[200:203], v[48:51]
	v_mfma_f32_16x16x32_bf16 v[36:39], v[180:183], v[208:211], v[36:39]
	v_mfma_f32_16x16x32_bf16 v[32:35], v[188:191], v[208:211], v[32:35]
	v_mfma_f32_16x16x32_bf16 v[20:23], v[180:183], v[216:219], v[20:23]
	v_mfma_f32_16x16x32_bf16 v[16:19], v[188:191], v[216:219], v[16:19]
	v_mfma_f32_16x16x32_bf16 v[4:7], v[180:183], v[224:227], v[4:7]
	v_mfma_f32_16x16x32_bf16 v[0:3], v[188:191], v[224:227], v[0:3]
	v_mfma_f32_16x16x32_bf16 v[52:55], v[184:187], v[204:207], v[52:55]
	v_mfma_f32_16x16x32_bf16 v[48:51], v[196:199], v[204:207], v[48:51]
	v_mfma_f32_16x16x32_bf16 v[36:39], v[184:187], v[212:215], v[36:39]
	v_mfma_f32_16x16x32_bf16 v[32:35], v[196:199], v[212:215], v[32:35]
	v_mfma_f32_16x16x32_bf16 v[20:23], v[184:187], v[220:223], v[20:23]
	v_mfma_f32_16x16x32_bf16 v[16:19], v[196:199], v[220:223], v[16:19]
	v_mfma_f32_16x16x32_bf16 v[4:7], v[184:187], v[228:231], v[4:7]
	v_mfma_f32_16x16x32_bf16 v[0:3], v[196:199], v[228:231], v[0:3]
	s_barrier
	s_add_i32 s72, s72, 2
	s_add_u32 s33, s33, 0x100
	s_addc_u32 vcc_lo, vcc_lo, 0
	s_cmp_gt_u32 s72, 9
	s_mov_b64 s[58:59], s[60:61]
	s_cbranch_scc0 .LBB0_777
	s_and_b64 vcc, exec, s[54:55]
	s_cbranch_vccz .LBB0_780
	s_barrier

; #define PG8_STAGE(bufoff, gbase, voff) do { _Pragma("unroll") for (int _i = 0; _i < 2; ++_i) \
;         __builtin_amdgcn_global_load_lds((const unsigned*)((const char*)(gbase) + (voff)[_i]), (PG8_LAS unsigned*)(lds + (bufoff) + ldsw + _i * 8192), 16, 0, 0); } while (0)
; #define PG8_LDA(dst, b, h) do { _Pragma("unroll") for (int m = 0; m < 4; ++m) _Pragma("unroll") for (int k = 0; k < 2; ++k) dst[m][k] = *(const PG8_LAS bf16x8*)(lds + PG8_SA(b, h) + aoff + m * 2048 + k * 1024); } while (0)
; #define PG8_LDB(dst, b, h) do { _Pragma("unroll") for (int n = 0; n < 2; ++n) _Pragma("unroll") for (int k = 0; k < 2; ++k) dst[n][k] = *(const PG8_LAS bf16x8*)(lds + PG8_SB(b, h) + boff + n * 2048 + k * 1024); } while (0)
; #define PG8_SCHED __builtin_amdgcn_sched_barrier(0)
; template <class Epi, class Sched, bool ALIGN_EPI = false, bool SP2 = false>
; __device__ __forceinline__ void gemm_phase(PG8_LAS unsigned char* lds, const Gemm g, const Sched& S, const Epi& E) {
;     ...
;         const bool has_next = S.next(ui + 1, nxt);
;         const char* nA = has_next ? (const char*)g.A + (size_t)nxt.pm * tstep : cA; const char* nB = has_next ? (const char*)g.Bt + (size_t)nxt.pn * tstep : cB;
;         for (int t = 0; t < nt; t += 2) {
;             const bool last = (t == nt - 2);
;             const char* a1 = cA + (size_t)(t + 1) * kstep;
;             const char* a2 = last ? nA : cA + (size_t)(t + 2) * kstep; const char* b2 = last ? nB : cB + (size_t)(t + 2) * kstep;
;             const char* a3 = a2 + kstep; const char* b3 = b2 + kstep;
;             if (last && has_next) S.a_ready(nxt);
;             if constexpr (SP2) {
;             PG8_LDB(B0, 0, 0); PG8_LDB(B1, 0, 1); PG8_SCHED; PG8_LDA(At, 0, 0); PG8_STAGE(PG8_SA(1, 1), a1 + hstep, voffA);
;     ...
; #pragma unroll
;         for (int a = 0; a < 2; ++a)
; #pragma unroll
;             for (int b = 0; b < 2; ++b)
; #pragma unroll
;                 for (int m = 0; m < 4; ++m)
; #pragma unroll
;                     for (int n = 0; n < 2; ++n) acc[a][b][m][n] = (f32x4){0.f, 0.f, 0.f, 0.f};
.LBB0_900:
	s_ashr_i32 s49, s48, 31
	s_lshl_b64 s[6:7], s[48:49], 19
	s_add_u32 s50, s22, s6
	s_addc_u32 s51, s23, s7
	s_and_b64 s[6:7], s[46:47], exec
	s_cselect_b32 s49, s51, s57
	s_cselect_b32 s76, s50, s56
	s_ashr_i32 s41, s40, 31
	s_lshl_b64 s[6:7], s[40:41], 19
	s_add_u32 s52, s4, s6
	s_addc_u32 s53, s26, s7
	s_and_b64 s[6:7], s[46:47], exec
	s_cselect_b32 s41, s53, s59
	s_cselect_b32 s77, s52, s58
	s_add_u32 s56, s56, 0x40080
	s_addc_u32 s57, s57, 0
	s_add_u32 s78, s58, 0x100
	v_mov_b32_e32 v0, 0
	s_addc_u32 s33, s59, 0
	s_mov_b32 s72, -2
	v_mov_b32_e32 v1, v0
	v_mov_b32_e32 v2, v0
	v_mov_b32_e32 v3, v0
	v_mov_b32_e32 v8, v0
	v_mov_b32_e32 v9, v0
	v_mov_b32_e32 v10, v0
	v_mov_b32_e32 v11, v0
	v_mov_b32_e32 v16, v0
	v_mov_b32_e32 v17, v0
	v_mov_b32_e32 v18, v0
	v_mov_b32_e32 v19, v0
	v_mov_b32_e32 v24, v0
	v_mov_b32_e32 v25, v0
	v_mov_b32_e32 v26, v0
	v_mov_b32_e32 v27, v0
	v_mov_b32_e32 v32, v0
	v_mov_b32_e32 v33, v0
	v_mov_b32_e32 v34, v0
	v_mov_b32_e32 v35, v0
	v_mov_b32_e32 v40, v0
	v_mov_b32_e32 v41, v0
	v_mov_b32_e32 v42, v0
	v_mov_b32_e32 v43, v0
	v_mov_b32_e32 v48, v0
	v_mov_b32_e32 v49, v0
	v_mov_b32_e32 v50, v0
	v_mov_b32_e32 v51, v0
	v_mov_b32_e32 v56, v0
	v_mov_b32_e32 v57, v0
	v_mov_b32_e32 v58, v0
	v_mov_b32_e32 v59, v0
	v_mov_b32_e32 v4, v0
	v_mov_b32_e32 v5, v0
	v_mov_b32_e32 v6, v0
	v_mov_b32_e32 v7, v0
	v_mov_b32_e32 v12, v0
	v_mov_b32_e32 v13, v0
	v_mov_b32_e32 v14, v0
	v_mov_b32_e32 v15, v0
	v_mov_b32_e32 v20, v0
	v_mov_b32_e32 v21, v0
	v_mov_b32_e32 v22, v0
	v_mov_b32_e32 v23, v0
	v_mov_b32_e32 v28, v0
	v_mov_b32_e32 v29, v0
	v_mov_b32_e32 v30, v0
	v_mov_b32_e32 v31, v0
	v_mov_b32_e32 v36, v0
	v_mov_b32_e32 v37, v0
	v_mov_b32_e32 v38, v0
	v_mov_b32_e32 v39, v0
	v_mov_b32_e32 v44, v0
	v_mov_b32_e32 v45, v0
	v_mov_b32_e32 v46, v0
	v_mov_b32_e32 v47, v0
	v_mov_b32_e32 v52, v0
	v_mov_b32_e32 v53, v0
	v_mov_b32_e32 v54, v0
	v_mov_b32_e32 v55, v0
	v_mov_b32_e32 v60, v0
	v_mov_b32_e32 v61, v0
	v_mov_b32_e32 v62, v0
	v_mov_b32_e32 v63, v0
	v_mov_b32_e32 v64, v0
	v_mov_b32_e32 v65, v0
	v_mov_b32_e32 v66, v0
	v_mov_b32_e32 v67, v0
	v_mov_b32_e32 v72, v0
	v_mov_b32_e32 v73, v0
	v_mov_b32_e32 v74, v0
	v_mov_b32_e32 v75, v0
	v_mov_b32_e32 v80, v0
	v_mov_b32_e32 v81, v0
	v_mov_b32_e32 v82, v0
	v_mov_b32_e32 v83, v0
	v_mov_b32_e32 v88, v0
	v_mov_b32_e32 v89, v0
	v_mov_b32_e32 v90, v0
	v_mov_b32_e32 v91, v0
	v_mov_b32_e32 v96, v0
	v_mov_b32_e32 v97, v0
	v_mov_b32_e32 v98, v0
	v_mov_b32_e32 v99, v0
	v_mov_b32_e32 v104, v0
	v_mov_b32_e32 v105, v0
	v_mov_b32_e32 v106, v0
	v_mov_b32_e32 v107, v0
	v_mov_b32_e32 v112, v0
	v_mov_b32_e32 v113, v0
	v_mov_b32_e32 v114, v0
	v_mov_b32_e32 v115, v0
	v_mov_b32_e32 v120, v0
	v_mov_b32_e32 v121, v0
	v_mov_b32_e32 v122, v0
	v_mov_b32_e32 v123, v0
	v_mov_b32_e32 v68, v0
	v_mov_b32_e32 v69, v0
	v_mov_b32_e32 v70, v0
	v_mov_b32_e32 v71, v0
	v_mov_b32_e32 v76, v0
	v_mov_b32_e32 v77, v0
	v_mov_b32_e32 v78, v0
	v_mov_b32_e32 v79, v0
	v_mov_b32_e32 v84, v0
	v_mov_b32_e32 v85, v0
	v_mov_b32_e32 v86, v0
	v_mov_b32_e32 v87, v0
	v_mov_b32_e32 v92, v0
	v_mov_b32_e32 v93, v0
	v_mov_b32_e32 v94, v0
	v_mov_b32_e32 v95, v0
	v_mov_b32_e32 v100, v0
	v_mov_b32_e32 v101, v0
	v_mov_b32_e32 v102, v0
	v_mov_b32_e32 v103, v0
	v_mov_b32_e32 v108, v0
	v_mov_b32_e32 v109, v0
	v_mov_b32_e32 v110, v0
	v_mov_b32_e32 v111, v0
	v_mov_b32_e32 v116, v0
	v_mov_b32_e32 v117, v0
	v_mov_b32_e32 v118, v0
	v_mov_b32_e32 v119, v0
	v_mov_b32_e32 v124, v0
	v_mov_b32_e32 v125, v0
	v_mov_b32_e32 v126, v0
	v_mov_b32_e32 v127, v0
	v_add_u32_e32 v244, 0x18000, v156
	v_add_u32_e32 v245, 0x1c000, v156
.LBB0_901:
	ds_read_b128 v[144:147], v159
	ds_read_b128 v[168:171], v159 offset:1024
	ds_read_b128 v[172:175], v159 offset:2048
	ds_read_b128 v[176:179], v159 offset:3072
	ds_read_b128 v[180:183], v163
	ds_read_b128 v[184:187], v163 offset:1024
	ds_read_b128 v[188:191], v163 offset:2048
	ds_read_b128 v[196:199], v163 offset:3072
	s_add_u32 s6, s56, 0xfffc0080
	s_addc_u32 s7, s57, -1
	s_cmp_eq_u32 s72, 12
	s_cselect_b32 s61, s49, s7
	s_cselect_b32 s60, s76, s6
	s_cselect_b32 s59, s41, s33
	s_cselect_b32 s58, s77, s78
	s_add_i32 m0, s30, 0xc000
	ds_read_b128 v[200:203], v166
	ds_read_b128 v[204:207], v166 offset:1024
	ds_read_b128 v[208:211], v166 offset:2048
	ds_read_b128 v[212:215], v166 offset:3072
	ds_read_b128 v[216:219], v166 offset:4096
	ds_read_b128 v[220:223], v166 offset:5120
	ds_read_b128 v[224:227], v166 offset:6144
	ds_read_b128 v[228:231], v166 offset:7168
	global_load_lds_dwordx4 v136, s[56:57]
	s_add_i32 m0, s30, 0xe000
	s_nop 0
	global_load_lds_dwordx4 v138, s[56:57]
	s_waitcnt vmcnt(8)
	s_waitcnt lgkmcnt(0)
	s_barrier
; #define PG8_STAGE(bufoff, gbase, voff) do { _Pragma("unroll") for (int _i = 0; _i < 2; ++_i) \
;         __builtin_amdgcn_global_load_lds((const unsigned*)((const char*)(gbase) + (voff)[_i]), (PG8_LAS unsigned*)(lds + (bufoff) + ldsw + _i * 8192), 16, 0, 0); } while (0)
; #define PG8_LDA(dst, b, h) do { _Pragma("unroll") for (int m = 0; m < 4; ++m) _Pragma("unroll") for (int k = 0; k < 2; ++k) dst[m][k] = *(const PG8_LAS bf16x8*)(lds + PG8_SA(b, h) + aoff + m * 2048 + k * 1024); } while (0)
; #define PG8_MMA(ai, bj, At, Bt) do { __builtin_amdgcn_s_setprio(1); _Pragma("unroll") for (int m = 0; m < 4; ++m) _Pragma("unroll") for (int n = 0; n < 2; ++n) _Pragma("unroll") for (int k = 0; k < 2; ++k) \
;         acc[ai][bj][m][n] = __builtin_amdgcn_mfma_f32_16x16x32_bf16(Bt[n][k], At[m][k], acc[ai][bj][m][n], 0, 0, 0); __builtin_amdgcn_s_setprio(0); } while (0)
; #define PG8_WAIT_V(n) asm volatile("s_waitcnt vmcnt(" #n ")" ::: "memory")
; #define PG8_WAIT_L(n) asm volatile("s_waitcnt lgkmcnt(" #n ")" ::: "memory")
; #define PG8_BAR __builtin_amdgcn_s_barrier()
; #define PG8_SCHED __builtin_amdgcn_sched_barrier(0)
; template <class Epi, class Sched, bool ALIGN_EPI = false, bool SP2 = false>
; __device__ __forceinline__ void gemm_phase(PG8_LAS unsigned char* lds, const Gemm g, const Sched& S, const Epi& E) {
;     ...
;             PG8_WAIT_V(8); PG8_WAIT_L(0); PG8_BAR; PG8_MMA(0, 0, At, B0); PG8_MMA(0, 1, At, B1); PG8_BAR; PG8_SCHED;
;             PG8_LDA(At, 0, 1); PG8_STAGE(PG8_SB(0, 0), b2, voffB); PG8_STAGE(PG8_SB(0, 1), b2 + hstep, voffB); PG8_STAGE(PG8_SA(0, 0), a2, voffA);
;             PG8_WAIT_V(8); PG8_WAIT_L(0); PG8_BAR; PG8_MMA(1, 0, At, B0); PG8_MMA(1, 1, At, B1); PG8_BAR; PG8_SCHED;
	s_waitcnt lgkmcnt(0)
	v_mfma_f32_16x16x32_bf16 v[124:127], v[144:147], v[200:203], v[124:127]
	v_mfma_f32_16x16x32_bf16 v[116:119], v[172:175], v[200:203], v[116:119]
	v_mfma_f32_16x16x32_bf16 v[108:111], v[144:147], v[208:211], v[108:111]
	v_mfma_f32_16x16x32_bf16 v[100:103], v[172:175], v[208:211], v[100:103]
	v_mfma_f32_16x16x32_bf16 v[92:95], v[144:147], v[216:219], v[92:95]
	v_mfma_f32_16x16x32_bf16 v[84:87], v[172:175], v[216:219], v[84:87]
	v_mfma_f32_16x16x32_bf16 v[76:79], v[144:147], v[224:227], v[76:79]
	v_mfma_f32_16x16x32_bf16 v[68:71], v[172:175], v[224:227], v[68:71]
	v_mfma_f32_16x16x32_bf16 v[124:127], v[168:171], v[204:207], v[124:127]
	v_mfma_f32_16x16x32_bf16 v[116:119], v[176:179], v[204:207], v[116:119]
	v_mfma_f32_16x16x32_bf16 v[108:111], v[168:171], v[212:215], v[108:111]
	v_mfma_f32_16x16x32_bf16 v[100:103], v[176:179], v[212:215], v[100:103]
	v_mfma_f32_16x16x32_bf16 v[92:95], v[168:171], v[220:223], v[92:95]
	v_mfma_f32_16x16x32_bf16 v[84:87], v[176:179], v[220:223], v[84:87]
	v_mfma_f32_16x16x32_bf16 v[76:79], v[168:171], v[228:231], v[76:79]
	v_mfma_f32_16x16x32_bf16 v[68:71], v[176:179], v[228:231], v[68:71]
	v_mfma_f32_16x16x32_bf16 v[120:123], v[180:183], v[200:203], v[120:123]
	v_mfma_f32_16x16x32_bf16 v[112:115], v[188:191], v[200:203], v[112:115]
	v_mfma_f32_16x16x32_bf16 v[104:107], v[180:183], v[208:211], v[104:107]
	v_mfma_f32_16x16x32_bf16 v[96:99], v[188:191], v[208:211], v[96:99]
	v_mfma_f32_16x16x32_bf16 v[88:91], v[180:183], v[216:219], v[88:91]
	v_mfma_f32_16x16x32_bf16 v[80:83], v[188:191], v[216:219], v[80:83]
	v_mfma_f32_16x16x32_bf16 v[72:75], v[180:183], v[224:227], v[72:75]
	v_mfma_f32_16x16x32_bf16 v[64:67], v[188:191], v[224:227], v[64:67]
	v_mfma_f32_16x16x32_bf16 v[120:123], v[184:187], v[204:207], v[120:123]
	v_mfma_f32_16x16x32_bf16 v[112:115], v[196:199], v[204:207], v[112:115]
	v_mfma_f32_16x16x32_bf16 v[104:107], v[184:187], v[212:215], v[104:107]
	v_mfma_f32_16x16x32_bf16 v[96:99], v[196:199], v[212:215], v[96:99]
	v_mfma_f32_16x16x32_bf16 v[88:91], v[184:187], v[220:223], v[88:91]
	v_mfma_f32_16x16x32_bf16 v[80:83], v[196:199], v[220:223], v[80:83]
	v_mfma_f32_16x16x32_bf16 v[72:75], v[184:187], v[228:231], v[72:75]
	v_mfma_f32_16x16x32_bf16 v[64:67], v[196:199], v[228:231], v[64:67]
	s_barrier
	s_add_i32 s6, s67, s27
	s_mov_b32 m0, s6
	ds_read_b128 v[200:203], v166 offset:16384
	ds_read_b128 v[204:207], v166 offset:17408
	ds_read_b128 v[208:211], v166 offset:18432
	ds_read_b128 v[212:215], v166 offset:19456
	ds_read_b128 v[216:219], v166 offset:20480
	ds_read_b128 v[220:223], v166 offset:21504
	ds_read_b128 v[224:227], v166 offset:22528
	ds_read_b128 v[228:231], v166 offset:23552
	global_load_lds_dwordx4 v132, s[58:59]
	s_add_i32 m0, s6, 0x2000
	s_add_u32 s6, s58, 0x40000
	s_addc_u32 s7, s59, 0
	s_add_i32 s73, s68, s27
	global_load_lds_dwordx4 v128, s[58:59]
	s_mov_b32 m0, s73
	s_nop 0
	global_load_lds_dwordx4 v132, s[6:7]
	s_add_i32 m0, s73, 0x2000
	s_nop 0
	global_load_lds_dwordx4 v128, s[6:7]
	s_mov_b32 m0, s30
	s_nop 0
	global_load_lds_dwordx4 v134, s[60:61]
	s_mov_b32 m0, s31
	s_nop 0
	global_load_lds_dwordx4 v130, s[60:61]
	s_waitcnt vmcnt(8)
	s_waitcnt lgkmcnt(0)
	s_barrier
	s_waitcnt lgkmcnt(0)
	v_mfma_f32_16x16x32_bf16 v[60:63], v[144:147], v[200:203], v[60:63]
	v_mfma_f32_16x16x32_bf16 v[52:55], v[172:175], v[200:203], v[52:55]
	v_mfma_f32_16x16x32_bf16 v[44:47], v[144:147], v[208:211], v[44:47]
	v_mfma_f32_16x16x32_bf16 v[36:39], v[172:175], v[208:211], v[36:39]
	v_mfma_f32_16x16x32_bf16 v[28:31], v[144:147], v[216:219], v[28:31]
	v_mfma_f32_16x16x32_bf16 v[20:23], v[172:175], v[216:219], v[20:23]
	v_mfma_f32_16x16x32_bf16 v[12:15], v[144:147], v[224:227], v[12:15]
	v_mfma_f32_16x16x32_bf16 v[4:7], v[172:175], v[224:227], v[4:7]
	v_mfma_f32_16x16x32_bf16 v[60:63], v[168:171], v[204:207], v[60:63]
	v_mfma_f32_16x16x32_bf16 v[52:55], v[176:179], v[204:207], v[52:55]
	v_mfma_f32_16x16x32_bf16 v[44:47], v[168:171], v[212:215], v[44:47]
	v_mfma_f32_16x16x32_bf16 v[36:39], v[176:179], v[212:215], v[36:39]
	v_mfma_f32_16x16x32_bf16 v[28:31], v[168:171], v[220:223], v[28:31]
	v_mfma_f32_16x16x32_bf16 v[20:23], v[176:179], v[220:223], v[20:23]
	v_mfma_f32_16x16x32_bf16 v[12:15], v[168:171], v[228:231], v[12:15]
	v_mfma_f32_16x16x32_bf16 v[4:7], v[176:179], v[228:231], v[4:7]
	v_mfma_f32_16x16x32_bf16 v[56:59], v[180:183], v[200:203], v[56:59]
	v_mfma_f32_16x16x32_bf16 v[48:51], v[188:191], v[200:203], v[48:51]
	v_mfma_f32_16x16x32_bf16 v[40:43], v[180:183], v[208:211], v[40:43]
	v_mfma_f32_16x16x32_bf16 v[32:35], v[188:191], v[208:211], v[32:35]
	v_mfma_f32_16x16x32_bf16 v[24:27], v[180:183], v[216:219], v[24:27]
	v_mfma_f32_16x16x32_bf16 v[16:19], v[188:191], v[216:219], v[16:19]
	v_mfma_f32_16x16x32_bf16 v[8:11], v[180:183], v[224:227], v[8:11]
	v_mfma_f32_16x16x32_bf16 v[0:3], v[188:191], v[224:227], v[0:3]
	v_mfma_f32_16x16x32_bf16 v[56:59], v[184:187], v[204:207], v[56:59]
	v_mfma_f32_16x16x32_bf16 v[48:51], v[196:199], v[204:207], v[48:51]
	v_mfma_f32_16x16x32_bf16 v[40:43], v[184:187], v[212:215], v[40:43]
	v_mfma_f32_16x16x32_bf16 v[32:35], v[196:199], v[212:215], v[32:35]
	v_mfma_f32_16x16x32_bf16 v[24:27], v[184:187], v[220:223], v[24:27]
	v_mfma_f32_16x16x32_bf16 v[16:19], v[196:199], v[220:223], v[16:19]
	v_mfma_f32_16x16x32_bf16 v[8:11], v[184:187], v[228:231], v[8:11]
	v_mfma_f32_16x16x32_bf16 v[0:3], v[196:199], v[228:231], v[0:3]
	s_barrier
; #define PG8_STAGE(bufoff, gbase, voff) do { _Pragma("unroll") for (int _i = 0; _i < 2; ++_i) \
;         __builtin_amdgcn_global_load_lds((const unsigned*)((const char*)(gbase) + (voff)[_i]), (PG8_LAS unsigned*)(lds + (bufoff) + ldsw + _i * 8192), 16, 0, 0); } while (0)
; #define PG8_LDA(dst, b, h) do { _Pragma("unroll") for (int m = 0; m < 4; ++m) _Pragma("unroll") for (int k = 0; k < 2; ++k) dst[m][k] = *(const PG8_LAS bf16x8*)(lds + PG8_SA(b, h) + aoff + m * 2048 + k * 1024); } while (0)
; #define PG8_LDB(dst, b, h) do { _Pragma("unroll") for (int n = 0; n < 2; ++n) _Pragma("unroll") for (int k = 0; k < 2; ++k) dst[n][k] = *(const PG8_LAS bf16x8*)(lds + PG8_SB(b, h) + boff + n * 2048 + k * 1024); } while (0)
; #define PG8_MMA(ai, bj, At, Bt) do { __builtin_amdgcn_s_setprio(1); _Pragma("unroll") for (int m = 0; m < 4; ++m) _Pragma("unroll") for (int n = 0; n < 2; ++n) _Pragma("unroll") for (int k = 0; k < 2; ++k) \
;         acc[ai][bj][m][n] = __builtin_amdgcn_mfma_f32_16x16x32_bf16(Bt[n][k], At[m][k], acc[ai][bj][m][n], 0, 0, 0); __builtin_amdgcn_s_setprio(0); } while (0)
; #define PG8_WAIT_V(n) asm volatile("s_waitcnt vmcnt(" #n ")" ::: "memory")
; #define PG8_WAIT_L(n) asm volatile("s_waitcnt lgkmcnt(" #n ")" ::: "memory")
; #define PG8_BAR __builtin_amdgcn_s_barrier()
; #define PG8_SCHED __builtin_amdgcn_sched_barrier(0)
; template <class Epi, class Sched, bool ALIGN_EPI = false, bool SP2 = false>
; __device__ __forceinline__ void gemm_phase(PG8_LAS unsigned char* lds, const Gemm g, const Sched& S, const Epi& E) {
;     ...
;             PG8_LDB(B0, 1, 0); PG8_LDB(B1, 1, 1); PG8_SCHED; PG8_LDA(At, 1, 0); PG8_STAGE(PG8_SA(0, 1), a2 + hstep, voffA);
;             PG8_WAIT_V(8); PG8_WAIT_L(0); PG8_BAR; PG8_MMA(0, 0, At, B0); PG8_MMA(0, 1, At, B1); PG8_BAR; PG8_SCHED;
;             PG8_LDA(At, 1, 1); PG8_STAGE(PG8_SB(1, 0), b3, voffB); PG8_STAGE(PG8_SB(1, 1), b3 + hstep, voffB); PG8_STAGE(PG8_SA(1, 0), a3, voffA);
;             PG8_WAIT_V(8); PG8_WAIT_L(0); PG8_BAR; PG8_MMA(1, 0, At, B0); PG8_MMA(1, 1, At, B1); PG8_BAR; PG8_SCHED;
	s_add_i32 s73, 0, 0x18000
	s_add_i32 s79, 0, 0x1c000
	ds_read_b128 v[144:147], v244
	ds_read_b128 v[168:171], v244 offset:1024
	ds_read_b128 v[172:175], v244 offset:2048
	ds_read_b128 v[176:179], v244 offset:3072
	ds_read_b128 v[180:183], v245
	ds_read_b128 v[184:187], v245 offset:1024
	ds_read_b128 v[188:191], v245 offset:2048
	ds_read_b128 v[196:199], v245 offset:3072
	s_add_u32 s6, s60, 0x40000
	s_addc_u32 s7, s61, 0
	s_mov_b32 m0, s42
	ds_read_b128 v[200:203], v166 offset:32768
	ds_read_b128 v[204:207], v166 offset:33792
	ds_read_b128 v[208:211], v166 offset:34816
	ds_read_b128 v[212:215], v166 offset:35840
	ds_read_b128 v[216:219], v166 offset:36864
	ds_read_b128 v[220:223], v166 offset:37888
	ds_read_b128 v[224:227], v166 offset:38912
	ds_read_b128 v[228:231], v166 offset:39936
	global_load_lds_dwordx4 v134, s[6:7]
	s_mov_b32 m0, s43
	s_nop 0
	global_load_lds_dwordx4 v130, s[6:7]
	s_waitcnt vmcnt(8)
	s_waitcnt lgkmcnt(0)
	s_barrier
	s_waitcnt lgkmcnt(0)
	v_mfma_f32_16x16x32_bf16 v[124:127], v[144:147], v[200:203], v[124:127]
	v_mfma_f32_16x16x32_bf16 v[116:119], v[172:175], v[200:203], v[116:119]
	v_mfma_f32_16x16x32_bf16 v[108:111], v[144:147], v[208:211], v[108:111]
	v_mfma_f32_16x16x32_bf16 v[100:103], v[172:175], v[208:211], v[100:103]
	v_mfma_f32_16x16x32_bf16 v[92:95], v[144:147], v[216:219], v[92:95]
	v_mfma_f32_16x16x32_bf16 v[84:87], v[172:175], v[216:219], v[84:87]
	v_mfma_f32_16x16x32_bf16 v[76:79], v[144:147], v[224:227], v[76:79]
	v_mfma_f32_16x16x32_bf16 v[68:71], v[172:175], v[224:227], v[68:71]
	v_mfma_f32_16x16x32_bf16 v[124:127], v[168:171], v[204:207], v[124:127]
	v_mfma_f32_16x16x32_bf16 v[116:119], v[176:179], v[204:207], v[116:119]
	v_mfma_f32_16x16x32_bf16 v[108:111], v[168:171], v[212:215], v[108:111]
	v_mfma_f32_16x16x32_bf16 v[100:103], v[176:179], v[212:215], v[100:103]
	v_mfma_f32_16x16x32_bf16 v[92:95], v[168:171], v[220:223], v[92:95]
	v_mfma_f32_16x16x32_bf16 v[84:87], v[176:179], v[220:223], v[84:87]
	v_mfma_f32_16x16x32_bf16 v[76:79], v[168:171], v[228:231], v[76:79]
	v_mfma_f32_16x16x32_bf16 v[68:71], v[176:179], v[228:231], v[68:71]
	v_mfma_f32_16x16x32_bf16 v[120:123], v[180:183], v[200:203], v[120:123]
	v_mfma_f32_16x16x32_bf16 v[112:115], v[188:191], v[200:203], v[112:115]
	v_mfma_f32_16x16x32_bf16 v[104:107], v[180:183], v[208:211], v[104:107]
	v_mfma_f32_16x16x32_bf16 v[96:99], v[188:191], v[208:211], v[96:99]
	v_mfma_f32_16x16x32_bf16 v[88:91], v[180:183], v[216:219], v[88:91]
	v_mfma_f32_16x16x32_bf16 v[80:83], v[188:191], v[216:219], v[80:83]
	v_mfma_f32_16x16x32_bf16 v[72:75], v[180:183], v[224:227], v[72:75]
	v_mfma_f32_16x16x32_bf16 v[64:67], v[188:191], v[224:227], v[64:67]
	v_mfma_f32_16x16x32_bf16 v[120:123], v[184:187], v[204:207], v[120:123]
	v_mfma_f32_16x16x32_bf16 v[112:115], v[196:199], v[204:207], v[112:115]
	v_mfma_f32_16x16x32_bf16 v[104:107], v[184:187], v[212:215], v[104:107]
	v_mfma_f32_16x16x32_bf16 v[96:99], v[196:199], v[212:215], v[96:99]
	v_mfma_f32_16x16x32_bf16 v[88:91], v[184:187], v[220:223], v[88:91]
	v_mfma_f32_16x16x32_bf16 v[80:83], v[196:199], v[220:223], v[80:83]
	v_mfma_f32_16x16x32_bf16 v[72:75], v[184:187], v[228:231], v[72:75]
	v_mfma_f32_16x16x32_bf16 v[64:67], v[196:199], v[228:231], v[64:67]
	s_barrier
	s_add_i32 s6, s73, s27
	s_add_u32 s98, s58, 0x80
	s_addc_u32 s99, s59, 0
	s_add_u32 s100, s60, 0x80
	s_addc_u32 s101, s61, 0
	s_mov_b32 m0, s6
	ds_read_b128 v[200:203], v166 offset:49152
	ds_read_b128 v[204:207], v166 offset:50176
	ds_read_b128 v[208:211], v166 offset:51200
	ds_read_b128 v[212:215], v166 offset:52224
	ds_read_b128 v[216:219], v166 offset:53248
	ds_read_b128 v[220:223], v166 offset:54272
	ds_read_b128 v[224:227], v166 offset:55296
	ds_read_b128 v[228:231], v166 offset:56320
	global_load_lds_dwordx4 v132, s[98:99]
	s_add_i32 m0, s6, 0x2000
	s_add_u32 s6, s58, 0x40080
	s_addc_u32 s7, s59, 0
	s_add_i32 s58, s79, s27
	global_load_lds_dwordx4 v128, s[98:99]
	s_mov_b32 m0, s58
	s_nop 0
	global_load_lds_dwordx4 v132, s[6:7]
	s_add_i32 m0, s58, 0x2000
	s_nop 0
	global_load_lds_dwordx4 v128, s[6:7]
	s_mov_b32 m0, s44
	s_nop 0
	global_load_lds_dwordx4 v134, s[100:101]
	s_mov_b32 m0, s45
	s_nop 0
	global_load_lds_dwordx4 v130, s[100:101]
	s_waitcnt vmcnt(8)
	s_waitcnt lgkmcnt(0)
	s_barrier
	s_waitcnt lgkmcnt(0)
	v_mfma_f32_16x16x32_bf16 v[60:63], v[144:147], v[200:203], v[60:63]
	v_mfma_f32_16x16x32_bf16 v[52:55], v[172:175], v[200:203], v[52:55]
	v_mfma_f32_16x16x32_bf16 v[44:47], v[144:147], v[208:211], v[44:47]
	v_mfma_f32_16x16x32_bf16 v[36:39], v[172:175], v[208:211], v[36:39]
	v_mfma_f32_16x16x32_bf16 v[28:31], v[144:147], v[216:219], v[28:31]
	v_mfma_f32_16x16x32_bf16 v[20:23], v[172:175], v[216:219], v[20:23]
	v_mfma_f32_16x16x32_bf16 v[12:15], v[144:147], v[224:227], v[12:15]
	v_mfma_f32_16x16x32_bf16 v[4:7], v[172:175], v[224:227], v[4:7]
	v_mfma_f32_16x16x32_bf16 v[60:63], v[168:171], v[204:207], v[60:63]
	v_mfma_f32_16x16x32_bf16 v[52:55], v[176:179], v[204:207], v[52:55]
	v_mfma_f32_16x16x32_bf16 v[44:47], v[168:171], v[212:215], v[44:47]
	v_mfma_f32_16x16x32_bf16 v[36:39], v[176:179], v[212:215], v[36:39]
	v_mfma_f32_16x16x32_bf16 v[28:31], v[168:171], v[220:223], v[28:31]
	v_mfma_f32_16x16x32_bf16 v[20:23], v[176:179], v[220:223], v[20:23]
	v_mfma_f32_16x16x32_bf16 v[12:15], v[168:171], v[228:231], v[12:15]
	v_mfma_f32_16x16x32_bf16 v[4:7], v[176:179], v[228:231], v[4:7]
	v_mfma_f32_16x16x32_bf16 v[56:59], v[180:183], v[200:203], v[56:59]
	v_mfma_f32_16x16x32_bf16 v[48:51], v[188:191], v[200:203], v[48:51]
	v_mfma_f32_16x16x32_bf16 v[40:43], v[180:183], v[208:211], v[40:43]
	v_mfma_f32_16x16x32_bf16 v[32:35], v[188:191], v[208:211], v[32:35]
	v_mfma_f32_16x16x32_bf16 v[24:27], v[180:183], v[216:219], v[24:27]
	v_mfma_f32_16x16x32_bf16 v[16:19], v[188:191], v[216:219], v[16:19]
	v_mfma_f32_16x16x32_bf16 v[8:11], v[180:183], v[224:227], v[8:11]
	v_mfma_f32_16x16x32_bf16 v[0:3], v[188:191], v[224:227], v[0:3]
	v_mfma_f32_16x16x32_bf16 v[56:59], v[184:187], v[204:207], v[56:59]
	v_mfma_f32_16x16x32_bf16 v[48:51], v[196:199], v[204:207], v[48:51]
	v_mfma_f32_16x16x32_bf16 v[40:43], v[184:187], v[212:215], v[40:43]
	v_mfma_f32_16x16x32_bf16 v[32:35], v[196:199], v[212:215], v[32:35]
	v_mfma_f32_16x16x32_bf16 v[24:27], v[184:187], v[220:223], v[24:27]
	v_mfma_f32_16x16x32_bf16 v[16:19], v[196:199], v[220:223], v[16:19]
	v_mfma_f32_16x16x32_bf16 v[8:11], v[184:187], v[228:231], v[8:11]
	v_mfma_f32_16x16x32_bf16 v[0:3], v[196:199], v[228:231], v[0:3]
	s_barrier
	s_add_i32 s72, s72, 2
	s_add_u32 s56, s56, 0x100
	s_addc_u32 s57, s57, 0
	s_add_u32 s78, s78, 0x100
	s_addc_u32 s33, s33, 0
	s_cmp_gt_u32 s72, 13
	s_cbranch_scc0 .LBB0_901
	s_and_b64 vcc, exec, s[38:39]
	s_cbranch_vccz .LBB0_904
	s_barrier

; #define PG8_STAGE(bufoff, gbase, voff) do { _Pragma("unroll") for (int _i = 0; _i < 2; ++_i) \
;         __builtin_amdgcn_global_load_lds((const unsigned*)((const char*)(gbase) + (voff)[_i]), (PG8_LAS unsigned*)(lds + (bufoff) + ldsw + _i * 8192), 16, 0, 0); } while (0)
; #define PG8_LDA(dst, b, h) do { _Pragma("unroll") for (int m = 0; m < 4; ++m) _Pragma("unroll") for (int k = 0; k < 2; ++k) dst[m][k] = *(const PG8_LAS bf16x8*)(lds + PG8_SA(b, h) + aoff + m * 2048 + k * 1024); } while (0)
; #define PG8_LDB(dst, b, h) do { _Pragma("unroll") for (int n = 0; n < 2; ++n) _Pragma("unroll") for (int k = 0; k < 2; ++k) dst[n][k] = *(const PG8_LAS bf16x8*)(lds + PG8_SB(b, h) + boff + n * 2048 + k * 1024); } while (0)
; #define PG8_MMA(ai, bj, At, Bt) do { __builtin_amdgcn_s_setprio(1); _Pragma("unroll") for (int m = 0; m < 4; ++m) _Pragma("unroll") for (int n = 0; n < 2; ++n) _Pragma("unroll") for (int k = 0; k < 2; ++k) \
;         acc[ai][bj][m][n] = __builtin_amdgcn_mfma_f32_16x16x32_bf16(Bt[n][k], At[m][k], acc[ai][bj][m][n], 0, 0, 0); __builtin_amdgcn_s_setprio(0); } while (0)
; #define PG8_WAIT_V(n) asm volatile("s_waitcnt vmcnt(" #n ")" ::: "memory")
; #define PG8_WAIT_L(n) asm volatile("s_waitcnt lgkmcnt(" #n ")" ::: "memory")
; #define PG8_BAR __builtin_amdgcn_s_barrier()
; template <class Epi, class Sched, bool ALIGN_EPI = false, bool SP2 = false>
; __device__ __forceinline__ void gemm_phase(PG8_LAS unsigned char* lds, const Gemm g, const Sched& S, const Epi& E) {
;     ...
;             const char* a1 = cA + (size_t)(t + 1) * kstep;
;             const char* a2 = last ? nA : cA + (size_t)(t + 2) * kstep; const char* b2 = last ? nB : cB + (size_t)(t + 2) * kstep;
;             const char* a3 = a2 + kstep; const char* b3 = b2 + kstep;
;             if (last && has_next) S.a_ready(nxt);
;             if constexpr (SP2) {
;             PG8_LDB(B0, 0, 0); PG8_LDB(B1, 0, 1); PG8_SCHED; PG8_LDA(At, 0, 0); PG8_STAGE(PG8_SA(1, 1), a1 + hstep, voffA);
;             PG8_WAIT_V(8); PG8_WAIT_L(0); PG8_BAR; PG8_MMA(0, 0, At, B0); PG8_MMA(0, 1, At, B1); PG8_BAR; PG8_SCHED;
;     ...
; #pragma unroll
;         for (int a = 0; a < 2; ++a)
; #pragma unroll
;             for (int b = 0; b < 2; ++b)
; #pragma unroll
;                 for (int m = 0; m < 4; ++m)
; #pragma unroll
;                     for (int n = 0; n < 2; ++n) acc[a][b][m][n] = (f32x4){0.f, 0.f, 0.f, 0.f};
.LBB0_1013:
	s_add_u32 s33, s58, 0x100
	v_mov_b32_e32 v0, 0
	s_addc_u32 s80, s59, 0
	s_mov_b32 s72, -2
	s_waitcnt lgkmcnt(0)
	v_mov_b32_e32 v1, v0
	v_mov_b32_e32 v2, v0
	v_mov_b32_e32 v3, v0
	v_mov_b32_e32 v4, v0
	v_mov_b32_e32 v5, v0
	v_mov_b32_e32 v6, v0
	v_mov_b32_e32 v7, v0
	v_mov_b32_e32 v16, v0
	v_mov_b32_e32 v17, v0
	v_mov_b32_e32 v18, v0
	v_mov_b32_e32 v19, v0
	v_mov_b32_e32 v20, v0
	v_mov_b32_e32 v21, v0
	v_mov_b32_e32 v22, v0
	v_mov_b32_e32 v23, v0
	v_mov_b32_e32 v32, v0
	v_mov_b32_e32 v33, v0
	v_mov_b32_e32 v34, v0
	v_mov_b32_e32 v35, v0
	v_mov_b32_e32 v36, v0
	v_mov_b32_e32 v37, v0
	v_mov_b32_e32 v38, v0
	v_mov_b32_e32 v39, v0
	v_mov_b32_e32 v48, v0
	v_mov_b32_e32 v49, v0
	v_mov_b32_e32 v50, v0
	v_mov_b32_e32 v51, v0
	v_mov_b32_e32 v52, v0
	v_mov_b32_e32 v53, v0
	v_mov_b32_e32 v54, v0
	v_mov_b32_e32 v55, v0
	v_mov_b32_e32 v8, v0
	v_mov_b32_e32 v9, v0
	v_mov_b32_e32 v10, v0
	v_mov_b32_e32 v11, v0
	v_mov_b32_e32 v12, v0
	v_mov_b32_e32 v13, v0
	v_mov_b32_e32 v14, v0
	v_mov_b32_e32 v15, v0
	v_mov_b32_e32 v24, v0
	v_mov_b32_e32 v25, v0
	v_mov_b32_e32 v26, v0
	v_mov_b32_e32 v27, v0
	v_mov_b32_e32 v28, v0
	v_mov_b32_e32 v29, v0
	v_mov_b32_e32 v30, v0
	v_mov_b32_e32 v31, v0
	v_mov_b32_e32 v40, v0
	v_mov_b32_e32 v41, v0
	v_mov_b32_e32 v42, v0
	v_mov_b32_e32 v43, v0
	v_mov_b32_e32 v44, v0
	v_mov_b32_e32 v45, v0
	v_mov_b32_e32 v46, v0
	v_mov_b32_e32 v47, v0
	v_mov_b32_e32 v56, v0
	v_mov_b32_e32 v57, v0
	v_mov_b32_e32 v58, v0
	v_mov_b32_e32 v59, v0
	v_mov_b32_e32 v60, v0
	v_mov_b32_e32 v61, v0
	v_mov_b32_e32 v62, v0
	v_mov_b32_e32 v63, v0
	v_mov_b32_e32 v64, v0
	v_mov_b32_e32 v65, v0
	v_mov_b32_e32 v66, v0
	v_mov_b32_e32 v67, v0
	v_mov_b32_e32 v68, v0
	v_mov_b32_e32 v69, v0
	v_mov_b32_e32 v70, v0
	v_mov_b32_e32 v71, v0
	v_mov_b32_e32 v80, v0
	v_mov_b32_e32 v81, v0
	v_mov_b32_e32 v82, v0
	v_mov_b32_e32 v83, v0
	v_mov_b32_e32 v84, v0
	v_mov_b32_e32 v85, v0
	v_mov_b32_e32 v86, v0
	v_mov_b32_e32 v87, v0
	v_mov_b32_e32 v96, v0
	v_mov_b32_e32 v97, v0
	v_mov_b32_e32 v98, v0
	v_mov_b32_e32 v99, v0
	v_mov_b32_e32 v100, v0
	v_mov_b32_e32 v101, v0
	v_mov_b32_e32 v102, v0
	v_mov_b32_e32 v103, v0
	v_mov_b32_e32 v112, v0
	v_mov_b32_e32 v113, v0
	v_mov_b32_e32 v114, v0
	v_mov_b32_e32 v115, v0
	v_mov_b32_e32 v116, v0
	v_mov_b32_e32 v117, v0
	v_mov_b32_e32 v118, v0
	v_mov_b32_e32 v119, v0
	v_mov_b32_e32 v72, v0
	v_mov_b32_e32 v73, v0
	v_mov_b32_e32 v74, v0
	v_mov_b32_e32 v75, v0
	v_mov_b32_e32 v76, v0
	v_mov_b32_e32 v77, v0
	v_mov_b32_e32 v78, v0
	v_mov_b32_e32 v79, v0
	v_mov_b32_e32 v88, v0
	v_mov_b32_e32 v89, v0
	v_mov_b32_e32 v90, v0
	v_mov_b32_e32 v91, v0
	v_mov_b32_e32 v92, v0
	v_mov_b32_e32 v93, v0
	v_mov_b32_e32 v94, v0
	v_mov_b32_e32 v95, v0
	v_mov_b32_e32 v104, v0
	v_mov_b32_e32 v105, v0
	v_mov_b32_e32 v106, v0
	v_mov_b32_e32 v107, v0
	v_mov_b32_e32 v108, v0
	v_mov_b32_e32 v109, v0
	v_mov_b32_e32 v110, v0
	v_mov_b32_e32 v111, v0
	v_mov_b32_e32 v120, v0
	v_mov_b32_e32 v121, v0
	v_mov_b32_e32 v122, v0
	v_mov_b32_e32 v123, v0
	v_mov_b32_e32 v124, v0
	v_mov_b32_e32 v125, v0
	v_mov_b32_e32 v126, v0
	v_mov_b32_e32 v127, v0
	v_add_u32_e32 v244, 0x18000, v156
	v_add_u32_e32 v245, 0x1c000, v156
.LBB0_1014:
	ds_read_b128 v[144:147], v158
	ds_read_b128 v[168:171], v158 offset:1024
	ds_read_b128 v[172:175], v158 offset:2048
	ds_read_b128 v[176:179], v158 offset:3072
	ds_read_b128 v[180:183], v159
	ds_read_b128 v[184:187], v159 offset:1024
	ds_read_b128 v[188:191], v159 offset:2048
	ds_read_b128 v[196:199], v159 offset:3072
	s_add_u32 s58, s56, 0x100
	s_addc_u32 s59, s57, 0
	s_cmp_eq_u32 s72, 40
	s_cselect_b32 s79, s51, s59
	s_cselect_b32 s78, s50, s58
	s_cselect_b32 s61, s55, s80
	s_cselect_b32 s60, s54, s33
	s_add_i32 m0, s45, 0xc000
	ds_read_b128 v[200:203], v163
	ds_read_b128 v[204:207], v163 offset:1024
	ds_read_b128 v[208:211], v163 offset:2048
	ds_read_b128 v[212:215], v163 offset:3072
	ds_read_b128 v[216:219], v163 offset:4096
	ds_read_b128 v[220:223], v163 offset:5120
	ds_read_b128 v[224:227], v163 offset:6144
	ds_read_b128 v[228:231], v163 offset:7168
	global_load_lds_dwordx4 v136, s[56:57]
	s_add_i32 m0, s45, 0xe000
	s_nop 0
	global_load_lds_dwordx4 v138, s[56:57]
	s_waitcnt vmcnt(8)
	s_waitcnt lgkmcnt(0)
	s_barrier
	s_waitcnt lgkmcnt(0)
	v_mfma_f32_16x16x32_bf16 v[124:127], v[144:147], v[200:203], v[124:127]
	v_mfma_f32_16x16x32_bf16 v[120:123], v[172:175], v[200:203], v[120:123]
	v_mfma_f32_16x16x32_bf16 v[108:111], v[144:147], v[208:211], v[108:111]
	v_mfma_f32_16x16x32_bf16 v[104:107], v[172:175], v[208:211], v[104:107]
	v_mfma_f32_16x16x32_bf16 v[92:95], v[144:147], v[216:219], v[92:95]
	v_mfma_f32_16x16x32_bf16 v[88:91], v[172:175], v[216:219], v[88:91]
	v_mfma_f32_16x16x32_bf16 v[76:79], v[144:147], v[224:227], v[76:79]
	v_mfma_f32_16x16x32_bf16 v[72:75], v[172:175], v[224:227], v[72:75]
	v_mfma_f32_16x16x32_bf16 v[124:127], v[168:171], v[204:207], v[124:127]
	v_mfma_f32_16x16x32_bf16 v[120:123], v[176:179], v[204:207], v[120:123]
	v_mfma_f32_16x16x32_bf16 v[108:111], v[168:171], v[212:215], v[108:111]
	v_mfma_f32_16x16x32_bf16 v[104:107], v[176:179], v[212:215], v[104:107]
	v_mfma_f32_16x16x32_bf16 v[92:95], v[168:171], v[220:223], v[92:95]
	v_mfma_f32_16x16x32_bf16 v[88:91], v[176:179], v[220:223], v[88:91]
	v_mfma_f32_16x16x32_bf16 v[76:79], v[168:171], v[228:231], v[76:79]
	v_mfma_f32_16x16x32_bf16 v[72:75], v[176:179], v[228:231], v[72:75]
	v_mfma_f32_16x16x32_bf16 v[116:119], v[180:183], v[200:203], v[116:119]
	v_mfma_f32_16x16x32_bf16 v[112:115], v[188:191], v[200:203], v[112:115]
	v_mfma_f32_16x16x32_bf16 v[100:103], v[180:183], v[208:211], v[100:103]
	v_mfma_f32_16x16x32_bf16 v[96:99], v[188:191], v[208:211], v[96:99]
	v_mfma_f32_16x16x32_bf16 v[84:87], v[180:183], v[216:219], v[84:87]
	v_mfma_f32_16x16x32_bf16 v[80:83], v[188:191], v[216:219], v[80:83]
	v_mfma_f32_16x16x32_bf16 v[68:71], v[180:183], v[224:227], v[68:71]
	v_mfma_f32_16x16x32_bf16 v[64:67], v[188:191], v[224:227], v[64:67]
	v_mfma_f32_16x16x32_bf16 v[116:119], v[184:187], v[204:207], v[116:119]
	v_mfma_f32_16x16x32_bf16 v[112:115], v[196:199], v[204:207], v[112:115]
	v_mfma_f32_16x16x32_bf16 v[100:103], v[184:187], v[212:215], v[100:103]
	v_mfma_f32_16x16x32_bf16 v[96:99], v[196:199], v[212:215], v[96:99]
	v_mfma_f32_16x16x32_bf16 v[84:87], v[184:187], v[220:223], v[84:87]
	v_mfma_f32_16x16x32_bf16 v[80:83], v[196:199], v[220:223], v[80:83]
	v_mfma_f32_16x16x32_bf16 v[68:71], v[184:187], v[228:231], v[68:71]
	v_mfma_f32_16x16x32_bf16 v[64:67], v[196:199], v[228:231], v[64:67]
	s_barrier
; #define PG8_STAGE(bufoff, gbase, voff) do { _Pragma("unroll") for (int _i = 0; _i < 2; ++_i) \
;         __builtin_amdgcn_global_load_lds((const unsigned*)((const char*)(gbase) + (voff)[_i]), (PG8_LAS unsigned*)(lds + (bufoff) + ldsw + _i * 8192), 16, 0, 0); } while (0)
; #define PG8_LDA(dst, b, h) do { _Pragma("unroll") for (int m = 0; m < 4; ++m) _Pragma("unroll") for (int k = 0; k < 2; ++k) dst[m][k] = *(const PG8_LAS bf16x8*)(lds + PG8_SA(b, h) + aoff + m * 2048 + k * 1024); } while (0)
; #define PG8_LDB(dst, b, h) do { _Pragma("unroll") for (int n = 0; n < 2; ++n) _Pragma("unroll") for (int k = 0; k < 2; ++k) dst[n][k] = *(const PG8_LAS bf16x8*)(lds + PG8_SB(b, h) + boff + n * 2048 + k * 1024); } while (0)
; #define PG8_MMA(ai, bj, At, Bt) do { __builtin_amdgcn_s_setprio(1); _Pragma("unroll") for (int m = 0; m < 4; ++m) _Pragma("unroll") for (int n = 0; n < 2; ++n) _Pragma("unroll") for (int k = 0; k < 2; ++k) \
;         acc[ai][bj][m][n] = __builtin_amdgcn_mfma_f32_16x16x32_bf16(Bt[n][k], At[m][k], acc[ai][bj][m][n], 0, 0, 0); __builtin_amdgcn_s_setprio(0); } while (0)
; #define PG8_WAIT_V(n) asm volatile("s_waitcnt vmcnt(" #n ")" ::: "memory")
; #define PG8_WAIT_L(n) asm volatile("s_waitcnt lgkmcnt(" #n ")" ::: "memory")
; #define PG8_BAR __builtin_amdgcn_s_barrier()
; #define PG8_SCHED __builtin_amdgcn_sched_barrier(0)
; template <class Epi, class Sched, bool ALIGN_EPI = false, bool SP2 = false>
; __device__ __forceinline__ void gemm_phase(PG8_LAS unsigned char* lds, const Gemm g, const Sched& S, const Epi& E) {
;     ...
;             PG8_LDA(At, 0, 1); PG8_STAGE(PG8_SB(0, 0), b2, voffB); PG8_STAGE(PG8_SB(0, 1), b2 + hstep, voffB); PG8_STAGE(PG8_SA(0, 0), a2, voffA);
;             PG8_WAIT_V(8); PG8_WAIT_L(0); PG8_BAR; PG8_MMA(1, 0, At, B0); PG8_MMA(1, 1, At, B1); PG8_BAR; PG8_SCHED;
;             PG8_LDB(B0, 1, 0); PG8_LDB(B1, 1, 1); PG8_SCHED; PG8_LDA(At, 1, 0); PG8_STAGE(PG8_SA(0, 1), a2 + hstep, voffA);
	s_add_i32 s6, s26, s44
	s_mov_b32 m0, s6
	ds_read_b128 v[200:203], v163 offset:16384
	ds_read_b128 v[204:207], v163 offset:17408
	ds_read_b128 v[208:211], v163 offset:18432
	ds_read_b128 v[212:215], v163 offset:19456
	ds_read_b128 v[216:219], v163 offset:20480
	ds_read_b128 v[220:223], v163 offset:21504
	ds_read_b128 v[224:227], v163 offset:22528
	ds_read_b128 v[228:231], v163 offset:23552
	global_load_lds_dwordx4 v130, s[60:61]
	s_add_i32 m0, s6, 0x2000
	s_add_u32 s6, s60, 0xb0000
	s_addc_u32 s7, s61, 0
	s_add_i32 s56, s74, s44
	global_load_lds_dwordx4 v134, s[60:61]
	s_mov_b32 m0, s56
	s_nop 0
	global_load_lds_dwordx4 v130, s[6:7]
	s_add_i32 m0, s56, 0x2000
	s_nop 0
	global_load_lds_dwordx4 v134, s[6:7]
	s_mov_b32 m0, s45
	s_nop 0
	global_load_lds_dwordx4 v128, s[78:79]
	s_mov_b32 m0, s67
	s_nop 0
	global_load_lds_dwordx4 v132, s[78:79]
	s_waitcnt vmcnt(8)
	s_waitcnt lgkmcnt(0)
	s_barrier
	s_waitcnt lgkmcnt(0)
	v_mfma_f32_16x16x32_bf16 v[60:63], v[144:147], v[200:203], v[60:63]
	v_mfma_f32_16x16x32_bf16 v[56:59], v[172:175], v[200:203], v[56:59]
	v_mfma_f32_16x16x32_bf16 v[44:47], v[144:147], v[208:211], v[44:47]
	v_mfma_f32_16x16x32_bf16 v[40:43], v[172:175], v[208:211], v[40:43]
	v_mfma_f32_16x16x32_bf16 v[28:31], v[144:147], v[216:219], v[28:31]
	v_mfma_f32_16x16x32_bf16 v[24:27], v[172:175], v[216:219], v[24:27]
	v_mfma_f32_16x16x32_bf16 v[12:15], v[144:147], v[224:227], v[12:15]
	v_mfma_f32_16x16x32_bf16 v[8:11], v[172:175], v[224:227], v[8:11]
	v_mfma_f32_16x16x32_bf16 v[60:63], v[168:171], v[204:207], v[60:63]
	v_mfma_f32_16x16x32_bf16 v[56:59], v[176:179], v[204:207], v[56:59]
	v_mfma_f32_16x16x32_bf16 v[44:47], v[168:171], v[212:215], v[44:47]
	v_mfma_f32_16x16x32_bf16 v[40:43], v[176:179], v[212:215], v[40:43]
	v_mfma_f32_16x16x32_bf16 v[28:31], v[168:171], v[220:223], v[28:31]
	v_mfma_f32_16x16x32_bf16 v[24:27], v[176:179], v[220:223], v[24:27]
	v_mfma_f32_16x16x32_bf16 v[12:15], v[168:171], v[228:231], v[12:15]
	v_mfma_f32_16x16x32_bf16 v[8:11], v[176:179], v[228:231], v[8:11]
	v_mfma_f32_16x16x32_bf16 v[52:55], v[180:183], v[200:203], v[52:55]
	v_mfma_f32_16x16x32_bf16 v[48:51], v[188:191], v[200:203], v[48:51]
	v_mfma_f32_16x16x32_bf16 v[36:39], v[180:183], v[208:211], v[36:39]
	v_mfma_f32_16x16x32_bf16 v[32:35], v[188:191], v[208:211], v[32:35]
	v_mfma_f32_16x16x32_bf16 v[20:23], v[180:183], v[216:219], v[20:23]
	v_mfma_f32_16x16x32_bf16 v[16:19], v[188:191], v[216:219], v[16:19]
	v_mfma_f32_16x16x32_bf16 v[4:7], v[180:183], v[224:227], v[4:7]
	v_mfma_f32_16x16x32_bf16 v[0:3], v[188:191], v[224:227], v[0:3]
	v_mfma_f32_16x16x32_bf16 v[52:55], v[184:187], v[204:207], v[52:55]
	v_mfma_f32_16x16x32_bf16 v[48:51], v[196:199], v[204:207], v[48:51]
	v_mfma_f32_16x16x32_bf16 v[36:39], v[184:187], v[212:215], v[36:39]
	v_mfma_f32_16x16x32_bf16 v[32:35], v[196:199], v[212:215], v[32:35]
	v_mfma_f32_16x16x32_bf16 v[20:23], v[184:187], v[220:223], v[20:23]
	v_mfma_f32_16x16x32_bf16 v[16:19], v[196:199], v[220:223], v[16:19]
	v_mfma_f32_16x16x32_bf16 v[4:7], v[184:187], v[228:231], v[4:7]
	v_mfma_f32_16x16x32_bf16 v[0:3], v[196:199], v[228:231], v[0:3]
	s_barrier
	s_add_i32 s56, 0, 0x18000
	s_add_i32 s57, 0, 0x1c000
	ds_read_b128 v[144:147], v244
	ds_read_b128 v[168:171], v244 offset:1024
	ds_read_b128 v[172:175], v244 offset:2048
	ds_read_b128 v[176:179], v244 offset:3072
	ds_read_b128 v[180:183], v245
	ds_read_b128 v[184:187], v245 offset:1024
	ds_read_b128 v[188:191], v245 offset:2048
	ds_read_b128 v[196:199], v245 offset:3072
	s_add_u32 s6, s78, 0xb0000
	s_addc_u32 s7, s79, 0
	s_mov_b32 m0, s76
	ds_read_b128 v[200:203], v163 offset:32768
	ds_read_b128 v[204:207], v163 offset:33792
	ds_read_b128 v[208:211], v163 offset:34816
	ds_read_b128 v[212:215], v163 offset:35840
	ds_read_b128 v[216:219], v163 offset:36864
	ds_read_b128 v[220:223], v163 offset:37888
	ds_read_b128 v[224:227], v163 offset:38912
	ds_read_b128 v[228:231], v163 offset:39936
	global_load_lds_dwordx4 v128, s[6:7]
	s_mov_b32 m0, s77
	s_nop 0
	global_load_lds_dwordx4 v132, s[6:7]
	s_waitcnt vmcnt(8)
	s_waitcnt lgkmcnt(0)
	s_barrier
; #define PG8_STAGE(bufoff, gbase, voff) do { _Pragma("unroll") for (int _i = 0; _i < 2; ++_i) \
;         __builtin_amdgcn_global_load_lds((const unsigned*)((const char*)(gbase) + (voff)[_i]), (PG8_LAS unsigned*)(lds + (bufoff) + ldsw + _i * 8192), 16, 0, 0); } while (0)
; #define PG8_LDA(dst, b, h) do { _Pragma("unroll") for (int m = 0; m < 4; ++m) _Pragma("unroll") for (int k = 0; k < 2; ++k) dst[m][k] = *(const PG8_LAS bf16x8*)(lds + PG8_SA(b, h) + aoff + m * 2048 + k * 1024); } while (0)
; #define PG8_MMA(ai, bj, At, Bt) do { __builtin_amdgcn_s_setprio(1); _Pragma("unroll") for (int m = 0; m < 4; ++m) _Pragma("unroll") for (int n = 0; n < 2; ++n) _Pragma("unroll") for (int k = 0; k < 2; ++k) \
;         acc[ai][bj][m][n] = __builtin_amdgcn_mfma_f32_16x16x32_bf16(Bt[n][k], At[m][k], acc[ai][bj][m][n], 0, 0, 0); __builtin_amdgcn_s_setprio(0); } while (0)
; #define PG8_WAIT_V(n) asm volatile("s_waitcnt vmcnt(" #n ")" ::: "memory")
; #define PG8_WAIT_L(n) asm volatile("s_waitcnt lgkmcnt(" #n ")" ::: "memory")
; #define PG8_BAR __builtin_amdgcn_s_barrier()
; #define PG8_SCHED __builtin_amdgcn_sched_barrier(0)
; template <class Epi, class Sched, bool ALIGN_EPI = false, bool SP2 = false>
; __device__ __forceinline__ void gemm_phase(PG8_LAS unsigned char* lds, const Gemm g, const Sched& S, const Epi& E) {
;     ...
;             PG8_WAIT_V(8); PG8_WAIT_L(0); PG8_BAR; PG8_MMA(0, 0, At, B0); PG8_MMA(0, 1, At, B1); PG8_BAR; PG8_SCHED;
;             PG8_LDA(At, 1, 1); PG8_STAGE(PG8_SB(1, 0), b3, voffB); PG8_STAGE(PG8_SB(1, 1), b3 + hstep, voffB); PG8_STAGE(PG8_SA(1, 0), a3, voffA);
;             PG8_WAIT_V(8); PG8_WAIT_L(0); PG8_BAR; PG8_MMA(1, 0, At, B0); PG8_MMA(1, 1, At, B1); PG8_BAR; PG8_SCHED;
	s_waitcnt lgkmcnt(0)
	v_mfma_f32_16x16x32_bf16 v[124:127], v[144:147], v[200:203], v[124:127]
	v_mfma_f32_16x16x32_bf16 v[120:123], v[172:175], v[200:203], v[120:123]
	v_mfma_f32_16x16x32_bf16 v[108:111], v[144:147], v[208:211], v[108:111]
	v_mfma_f32_16x16x32_bf16 v[104:107], v[172:175], v[208:211], v[104:107]
	v_mfma_f32_16x16x32_bf16 v[92:95], v[144:147], v[216:219], v[92:95]
	v_mfma_f32_16x16x32_bf16 v[88:91], v[172:175], v[216:219], v[88:91]
	v_mfma_f32_16x16x32_bf16 v[76:79], v[144:147], v[224:227], v[76:79]
	v_mfma_f32_16x16x32_bf16 v[72:75], v[172:175], v[224:227], v[72:75]
	v_mfma_f32_16x16x32_bf16 v[124:127], v[168:171], v[204:207], v[124:127]
	v_mfma_f32_16x16x32_bf16 v[120:123], v[176:179], v[204:207], v[120:123]
	v_mfma_f32_16x16x32_bf16 v[108:111], v[168:171], v[212:215], v[108:111]
	v_mfma_f32_16x16x32_bf16 v[104:107], v[176:179], v[212:215], v[104:107]
	v_mfma_f32_16x16x32_bf16 v[92:95], v[168:171], v[220:223], v[92:95]
	v_mfma_f32_16x16x32_bf16 v[88:91], v[176:179], v[220:223], v[88:91]
	v_mfma_f32_16x16x32_bf16 v[76:79], v[168:171], v[228:231], v[76:79]
	v_mfma_f32_16x16x32_bf16 v[72:75], v[176:179], v[228:231], v[72:75]
	v_mfma_f32_16x16x32_bf16 v[116:119], v[180:183], v[200:203], v[116:119]
	v_mfma_f32_16x16x32_bf16 v[112:115], v[188:191], v[200:203], v[112:115]
	v_mfma_f32_16x16x32_bf16 v[100:103], v[180:183], v[208:211], v[100:103]
	v_mfma_f32_16x16x32_bf16 v[96:99], v[188:191], v[208:211], v[96:99]
	v_mfma_f32_16x16x32_bf16 v[84:87], v[180:183], v[216:219], v[84:87]
	v_mfma_f32_16x16x32_bf16 v[80:83], v[188:191], v[216:219], v[80:83]
	v_mfma_f32_16x16x32_bf16 v[68:71], v[180:183], v[224:227], v[68:71]
	v_mfma_f32_16x16x32_bf16 v[64:67], v[188:191], v[224:227], v[64:67]
	v_mfma_f32_16x16x32_bf16 v[116:119], v[184:187], v[204:207], v[116:119]
	v_mfma_f32_16x16x32_bf16 v[112:115], v[196:199], v[204:207], v[112:115]
	v_mfma_f32_16x16x32_bf16 v[100:103], v[184:187], v[212:215], v[100:103]
	v_mfma_f32_16x16x32_bf16 v[96:99], v[196:199], v[212:215], v[96:99]
	v_mfma_f32_16x16x32_bf16 v[84:87], v[184:187], v[220:223], v[84:87]
	v_mfma_f32_16x16x32_bf16 v[80:83], v[196:199], v[220:223], v[80:83]
	v_mfma_f32_16x16x32_bf16 v[68:71], v[184:187], v[228:231], v[68:71]
	v_mfma_f32_16x16x32_bf16 v[64:67], v[196:199], v[228:231], v[64:67]
	s_barrier
	s_add_i32 s6, s56, s44
	s_add_u32 s98, s60, 0x80
	s_addc_u32 s99, s61, 0
	s_add_u32 s100, s78, 0x80
	s_addc_u32 s101, s79, 0
	s_mov_b32 m0, s6
	ds_read_b128 v[200:203], v163 offset:49152
	ds_read_b128 v[204:207], v163 offset:50176
	ds_read_b128 v[208:211], v163 offset:51200
	ds_read_b128 v[212:215], v163 offset:52224
	ds_read_b128 v[216:219], v163 offset:53248
	ds_read_b128 v[220:223], v163 offset:54272
	ds_read_b128 v[224:227], v163 offset:55296
	ds_read_b128 v[228:231], v163 offset:56320
	global_load_lds_dwordx4 v130, s[98:99]
	s_add_i32 m0, s6, 0x2000
	s_add_u32 s6, s60, 0xb0080
	s_addc_u32 s7, s61, 0
	s_add_i32 s56, s57, s44
	global_load_lds_dwordx4 v134, s[98:99]
	s_mov_b32 m0, s56
	s_nop 0
	global_load_lds_dwordx4 v130, s[6:7]
	s_add_i32 m0, s56, 0x2000
	s_nop 0
	global_load_lds_dwordx4 v134, s[6:7]
	s_mov_b32 m0, s31
	s_nop 0
	global_load_lds_dwordx4 v128, s[100:101]
	s_mov_b32 m0, s4
	s_nop 0
	global_load_lds_dwordx4 v132, s[100:101]
	s_waitcnt vmcnt(8)
	s_waitcnt lgkmcnt(0)
	s_barrier
	s_waitcnt lgkmcnt(0)
	v_mfma_f32_16x16x32_bf16 v[60:63], v[144:147], v[200:203], v[60:63]
	v_mfma_f32_16x16x32_bf16 v[56:59], v[172:175], v[200:203], v[56:59]
	v_mfma_f32_16x16x32_bf16 v[44:47], v[144:147], v[208:211], v[44:47]
	v_mfma_f32_16x16x32_bf16 v[40:43], v[172:175], v[208:211], v[40:43]
	v_mfma_f32_16x16x32_bf16 v[28:31], v[144:147], v[216:219], v[28:31]
	v_mfma_f32_16x16x32_bf16 v[24:27], v[172:175], v[216:219], v[24:27]
	v_mfma_f32_16x16x32_bf16 v[12:15], v[144:147], v[224:227], v[12:15]
	v_mfma_f32_16x16x32_bf16 v[8:11], v[172:175], v[224:227], v[8:11]
	v_mfma_f32_16x16x32_bf16 v[60:63], v[168:171], v[204:207], v[60:63]
	v_mfma_f32_16x16x32_bf16 v[56:59], v[176:179], v[204:207], v[56:59]
	v_mfma_f32_16x16x32_bf16 v[44:47], v[168:171], v[212:215], v[44:47]
	v_mfma_f32_16x16x32_bf16 v[40:43], v[176:179], v[212:215], v[40:43]
	v_mfma_f32_16x16x32_bf16 v[28:31], v[168:171], v[220:223], v[28:31]
	v_mfma_f32_16x16x32_bf16 v[24:27], v[176:179], v[220:223], v[24:27]
	v_mfma_f32_16x16x32_bf16 v[12:15], v[168:171], v[228:231], v[12:15]
	v_mfma_f32_16x16x32_bf16 v[8:11], v[176:179], v[228:231], v[8:11]
	v_mfma_f32_16x16x32_bf16 v[52:55], v[180:183], v[200:203], v[52:55]
	v_mfma_f32_16x16x32_bf16 v[48:51], v[188:191], v[200:203], v[48:51]
	v_mfma_f32_16x16x32_bf16 v[36:39], v[180:183], v[208:211], v[36:39]
	v_mfma_f32_16x16x32_bf16 v[32:35], v[188:191], v[208:211], v[32:35]
	v_mfma_f32_16x16x32_bf16 v[20:23], v[180:183], v[216:219], v[20:23]
	v_mfma_f32_16x16x32_bf16 v[16:19], v[188:191], v[216:219], v[16:19]
	v_mfma_f32_16x16x32_bf16 v[4:7], v[180:183], v[224:227], v[4:7]
	v_mfma_f32_16x16x32_bf16 v[0:3], v[188:191], v[224:227], v[0:3]
	v_mfma_f32_16x16x32_bf16 v[52:55], v[184:187], v[204:207], v[52:55]
	v_mfma_f32_16x16x32_bf16 v[48:51], v[196:199], v[204:207], v[48:51]
	v_mfma_f32_16x16x32_bf16 v[36:39], v[184:187], v[212:215], v[36:39]
	v_mfma_f32_16x16x32_bf16 v[32:35], v[196:199], v[212:215], v[32:35]
	v_mfma_f32_16x16x32_bf16 v[20:23], v[184:187], v[220:223], v[20:23]
	v_mfma_f32_16x16x32_bf16 v[16:19], v[196:199], v[220:223], v[16:19]
	v_mfma_f32_16x16x32_bf16 v[4:7], v[184:187], v[228:231], v[4:7]
	v_mfma_f32_16x16x32_bf16 v[0:3], v[196:199], v[228:231], v[0:3]
	s_barrier
	s_add_i32 s72, s72, 2
	s_add_u32 s33, s33, 0x100
	s_addc_u32 s80, s80, 0
	s_cmp_gt_u32 s72, 41
	s_mov_b64 s[56:57], s[58:59]
	s_cbranch_scc0 .LBB0_1014
	s_and_b64 vcc, exec, s[52:53]
	s_cbranch_vccz .LBB0_1017
	s_barrier

; #define PG8_STAGE(bufoff, gbase, voff) do { _Pragma("unroll") for (int _i = 0; _i < 2; ++_i) \
;         __builtin_amdgcn_global_load_lds((const unsigned*)((const char*)(gbase) + (voff)[_i]), (PG8_LAS unsigned*)(lds + (bufoff) + ldsw + _i * 8192), 16, 0, 0); } while (0)
; #define PG8_LDA(dst, b, h) do { _Pragma("unroll") for (int m = 0; m < 4; ++m) _Pragma("unroll") for (int k = 0; k < 2; ++k) dst[m][k] = *(const PG8_LAS bf16x8*)(lds + PG8_SA(b, h) + aoff + m * 2048 + k * 1024); } while (0)
; #define PG8_LDB(dst, b, h) do { _Pragma("unroll") for (int n = 0; n < 2; ++n) _Pragma("unroll") for (int k = 0; k < 2; ++k) dst[n][k] = *(const PG8_LAS bf16x8*)(lds + PG8_SB(b, h) + boff + n * 2048 + k * 1024); } while (0)
; #define PG8_SCHED __builtin_amdgcn_sched_barrier(0)
; template <class Epi, class Sched, bool ALIGN_EPI = false, bool SP2 = false>
; __device__ __forceinline__ void gemm_phase(PG8_LAS unsigned char* lds, const Gemm g, const Sched& S, const Epi& E) {
;     ...
;         const bool has_next = S.next(ui + 1, nxt);
;         const char* nA = has_next ? (const char*)g.A + (size_t)nxt.pm * tstep : cA; const char* nB = has_next ? (const char*)g.Bt + (size_t)nxt.pn * tstep : cB;
;         for (int t = 0; t < nt; t += 2) {
;             const bool last = (t == nt - 2);
;             const char* a1 = cA + (size_t)(t + 1) * kstep;
;             const char* a2 = last ? nA : cA + (size_t)(t + 2) * kstep; const char* b2 = last ? nB : cB + (size_t)(t + 2) * kstep;
;             const char* a3 = a2 + kstep; const char* b3 = b2 + kstep;
;             if (last && has_next) S.a_ready(nxt);
;             if constexpr (SP2) {
;             PG8_LDB(B0, 0, 0); PG8_LDB(B1, 0, 1); PG8_SCHED; PG8_LDA(At, 0, 0); PG8_STAGE(PG8_SA(1, 1), a1 + hstep, voffA);
;     ...
; #pragma unroll
;         for (int a = 0; a < 2; ++a)
; #pragma unroll
;             for (int b = 0; b < 2; ++b)
; #pragma unroll
;                 for (int m = 0; m < 4; ++m)
; #pragma unroll
;                     for (int n = 0; n < 2; ++n) acc[a][b][m][n] = (f32x4){0.f, 0.f, 0.f, 0.f};
.LBB0_1391:
	s_ashr_i32 s51, s50, 31
	s_lshl_b64 s[6:7], s[50:51], 19
	s_add_u32 s52, s22, s6
	s_addc_u32 s53, s23, s7
	s_and_b64 s[6:7], s[46:47], exec
	s_cselect_b32 s51, s53, s59
	s_cselect_b32 s75, s52, s58
	s_ashr_i32 s49, s48, 31
	s_lshl_b64 s[6:7], s[48:49], 19
	s_add_u32 s54, s4, s6
	s_addc_u32 s55, s26, s7
	s_and_b64 s[6:7], s[46:47], exec
	s_cselect_b32 s49, s55, s61
	s_cselect_b32 s76, s54, s60
	s_add_u32 s58, s58, 0x40080
	s_addc_u32 s59, s59, 0
	s_add_u32 s77, s60, 0x100
	v_mov_b32_e32 v0, 0
	s_addc_u32 s33, s61, 0
	s_mov_b32 s72, -2
	v_mov_b32_e32 v1, v0
	v_mov_b32_e32 v2, v0
	v_mov_b32_e32 v3, v0
	v_mov_b32_e32 v4, v0
	v_mov_b32_e32 v5, v0
	v_mov_b32_e32 v6, v0
	v_mov_b32_e32 v7, v0
	v_mov_b32_e32 v12, v0
	v_mov_b32_e32 v13, v0
	v_mov_b32_e32 v14, v0
	v_mov_b32_e32 v15, v0
	v_mov_b32_e32 v16, v0
	v_mov_b32_e32 v17, v0
	v_mov_b32_e32 v18, v0
	v_mov_b32_e32 v19, v0
	v_mov_b32_e32 v28, v0
	v_mov_b32_e32 v29, v0
	v_mov_b32_e32 v30, v0
	v_mov_b32_e32 v31, v0
	v_mov_b32_e32 v32, v0
	v_mov_b32_e32 v33, v0
	v_mov_b32_e32 v34, v0
	v_mov_b32_e32 v35, v0
	v_mov_b32_e32 v44, v0
	v_mov_b32_e32 v45, v0
	v_mov_b32_e32 v46, v0
	v_mov_b32_e32 v47, v0
	v_mov_b32_e32 v48, v0
	v_mov_b32_e32 v49, v0
	v_mov_b32_e32 v50, v0
	v_mov_b32_e32 v51, v0
	v_mov_b32_e32 v8, v0
	v_mov_b32_e32 v9, v0
	v_mov_b32_e32 v10, v0
	v_mov_b32_e32 v11, v0
	v_mov_b32_e32 v20, v0
	v_mov_b32_e32 v21, v0
	v_mov_b32_e32 v22, v0
	v_mov_b32_e32 v23, v0
	v_mov_b32_e32 v24, v0
	v_mov_b32_e32 v25, v0
	v_mov_b32_e32 v26, v0
	v_mov_b32_e32 v27, v0
	v_mov_b32_e32 v36, v0
	v_mov_b32_e32 v37, v0
	v_mov_b32_e32 v38, v0
	v_mov_b32_e32 v39, v0
	v_mov_b32_e32 v40, v0
	v_mov_b32_e32 v41, v0
	v_mov_b32_e32 v42, v0
	v_mov_b32_e32 v43, v0
	v_mov_b32_e32 v52, v0
	v_mov_b32_e32 v53, v0
	v_mov_b32_e32 v54, v0
	v_mov_b32_e32 v55, v0
	v_mov_b32_e32 v56, v0
	v_mov_b32_e32 v57, v0
	v_mov_b32_e32 v58, v0
	v_mov_b32_e32 v59, v0
	v_mov_b32_e32 v60, v0
	v_mov_b32_e32 v61, v0
	v_mov_b32_e32 v62, v0
	v_mov_b32_e32 v63, v0
	v_mov_b32_e32 v64, v0
	v_mov_b32_e32 v65, v0
	v_mov_b32_e32 v66, v0
	v_mov_b32_e32 v67, v0
	v_mov_b32_e32 v68, v0
	v_mov_b32_e32 v69, v0
	v_mov_b32_e32 v70, v0
	v_mov_b32_e32 v71, v0
	v_mov_b32_e32 v76, v0
	v_mov_b32_e32 v77, v0
	v_mov_b32_e32 v78, v0
	v_mov_b32_e32 v79, v0
	v_mov_b32_e32 v84, v0
	v_mov_b32_e32 v85, v0
	v_mov_b32_e32 v86, v0
	v_mov_b32_e32 v87, v0
	v_mov_b32_e32 v92, v0
	v_mov_b32_e32 v93, v0
	v_mov_b32_e32 v94, v0
	v_mov_b32_e32 v95, v0
	v_mov_b32_e32 v100, v0
	v_mov_b32_e32 v101, v0
	v_mov_b32_e32 v102, v0
	v_mov_b32_e32 v103, v0
	v_mov_b32_e32 v108, v0
	v_mov_b32_e32 v109, v0
	v_mov_b32_e32 v110, v0
	v_mov_b32_e32 v111, v0
	v_mov_b32_e32 v116, v0
	v_mov_b32_e32 v117, v0
	v_mov_b32_e32 v118, v0
	v_mov_b32_e32 v119, v0
	v_mov_b32_e32 v72, v0
	v_mov_b32_e32 v73, v0
	v_mov_b32_e32 v74, v0
	v_mov_b32_e32 v75, v0
	v_mov_b32_e32 v80, v0
	v_mov_b32_e32 v81, v0
	v_mov_b32_e32 v82, v0
	v_mov_b32_e32 v83, v0
	v_mov_b32_e32 v88, v0
	v_mov_b32_e32 v89, v0
	v_mov_b32_e32 v90, v0
	v_mov_b32_e32 v91, v0
	v_mov_b32_e32 v96, v0
	v_mov_b32_e32 v97, v0
	v_mov_b32_e32 v98, v0
	v_mov_b32_e32 v99, v0
	v_mov_b32_e32 v104, v0
	v_mov_b32_e32 v105, v0
	v_mov_b32_e32 v106, v0
	v_mov_b32_e32 v107, v0
	v_mov_b32_e32 v112, v0
	v_mov_b32_e32 v113, v0
	v_mov_b32_e32 v114, v0
	v_mov_b32_e32 v115, v0
	v_mov_b32_e32 v120, v0
	v_mov_b32_e32 v121, v0
	v_mov_b32_e32 v122, v0
	v_mov_b32_e32 v123, v0
	v_mov_b32_e32 v124, v0
	v_mov_b32_e32 v125, v0
	v_mov_b32_e32 v126, v0
	v_mov_b32_e32 v127, v0
	v_add_u32_e32 v244, 0x18000, v149
	v_add_u32_e32 v245, 0x1c000, v149
.LBB0_1392:
	ds_read_b128 v[144:147], v157
	ds_read_b128 v[166:169], v157 offset:1024
	ds_read_b128 v[170:173], v157 offset:2048
	ds_read_b128 v[174:177], v157 offset:3072
	ds_read_b128 v[178:181], v158
	ds_read_b128 v[182:185], v158 offset:1024
	ds_read_b128 v[186:189], v158 offset:2048
	ds_read_b128 v[196:199], v158 offset:3072
	s_add_u32 s6, s58, 0xfffc0080
	s_addc_u32 s7, s59, -1
	s_cmp_eq_u32 s72, 12
	s_cselect_b32 s79, s51, s7
	s_cselect_b32 s78, s75, s6
	s_cselect_b32 s61, s49, s33
	s_cselect_b32 s60, s76, s77
	v_lshl_add_u64 v[190:191], s[58:59], 0, v[136:137]
	s_add_i32 m0, s30, 0xc000
	ds_read_b128 v[200:203], v159
	ds_read_b128 v[204:207], v159 offset:1024
	ds_read_b128 v[208:211], v159 offset:2048
	ds_read_b128 v[212:215], v159 offset:3072
	ds_read_b128 v[216:219], v159 offset:4096
	ds_read_b128 v[220:223], v159 offset:5120
	ds_read_b128 v[224:227], v159 offset:6144
	ds_read_b128 v[228:231], v159 offset:7168
	global_load_lds_dwordx4 v[190:191], off
	v_lshl_add_u64 v[190:191], s[58:59], 0, v[138:139]
	s_add_i32 m0, s30, 0xe000
	s_nop 0
	global_load_lds_dwordx4 v[190:191], off
	s_waitcnt vmcnt(8)
	s_waitcnt lgkmcnt(0)
	s_barrier
; #define PG8_STAGE(bufoff, gbase, voff) do { _Pragma("unroll") for (int _i = 0; _i < 2; ++_i) \
;         __builtin_amdgcn_global_load_lds((const unsigned*)((const char*)(gbase) + (voff)[_i]), (PG8_LAS unsigned*)(lds + (bufoff) + ldsw + _i * 8192), 16, 0, 0); } while (0)
; #define PG8_LDA(dst, b, h) do { _Pragma("unroll") for (int m = 0; m < 4; ++m) _Pragma("unroll") for (int k = 0; k < 2; ++k) dst[m][k] = *(const PG8_LAS bf16x8*)(lds + PG8_SA(b, h) + aoff + m * 2048 + k * 1024); } while (0)
; #define PG8_MMA(ai, bj, At, Bt) do { __builtin_amdgcn_s_setprio(1); _Pragma("unroll") for (int m = 0; m < 4; ++m) _Pragma("unroll") for (int n = 0; n < 2; ++n) _Pragma("unroll") for (int k = 0; k < 2; ++k) \
;         acc[ai][bj][m][n] = __builtin_amdgcn_mfma_f32_16x16x32_bf16(Bt[n][k], At[m][k], acc[ai][bj][m][n], 0, 0, 0); __builtin_amdgcn_s_setprio(0); } while (0)
; #define PG8_WAIT_V(n) asm volatile("s_waitcnt vmcnt(" #n ")" ::: "memory")
; #define PG8_WAIT_L(n) asm volatile("s_waitcnt lgkmcnt(" #n ")" ::: "memory")
; #define PG8_BAR __builtin_amdgcn_s_barrier()
; #define PG8_SCHED __builtin_amdgcn_sched_barrier(0)
; template <class Epi, class Sched, bool ALIGN_EPI = false, bool SP2 = false>
; __device__ __forceinline__ void gemm_phase(PG8_LAS unsigned char* lds, const Gemm g, const Sched& S, const Epi& E) {
;     ...
;             PG8_WAIT_V(8); PG8_WAIT_L(0); PG8_BAR; PG8_MMA(0, 0, At, B0); PG8_MMA(0, 1, At, B1); PG8_BAR; PG8_SCHED;
;             PG8_LDA(At, 0, 1); PG8_STAGE(PG8_SB(0, 0), b2, voffB); PG8_STAGE(PG8_SB(0, 1), b2 + hstep, voffB); PG8_STAGE(PG8_SA(0, 0), a2, voffA);
;             PG8_WAIT_V(8); PG8_WAIT_L(0); PG8_BAR; PG8_MMA(1, 0, At, B0); PG8_MMA(1, 1, At, B1); PG8_BAR; PG8_SCHED;
	s_waitcnt lgkmcnt(0)
	v_mfma_f32_16x16x32_bf16 v[124:127], v[144:147], v[200:203], v[124:127]
	v_mfma_f32_16x16x32_bf16 v[120:123], v[170:173], v[200:203], v[120:123]
	v_mfma_f32_16x16x32_bf16 v[112:115], v[144:147], v[208:211], v[112:115]
	v_mfma_f32_16x16x32_bf16 v[104:107], v[170:173], v[208:211], v[104:107]
	v_mfma_f32_16x16x32_bf16 v[96:99], v[144:147], v[216:219], v[96:99]
	v_mfma_f32_16x16x32_bf16 v[88:91], v[170:173], v[216:219], v[88:91]
	v_mfma_f32_16x16x32_bf16 v[80:83], v[144:147], v[224:227], v[80:83]
	v_mfma_f32_16x16x32_bf16 v[72:75], v[170:173], v[224:227], v[72:75]
	v_mfma_f32_16x16x32_bf16 v[124:127], v[166:169], v[204:207], v[124:127]
	v_mfma_f32_16x16x32_bf16 v[120:123], v[174:177], v[204:207], v[120:123]
	v_mfma_f32_16x16x32_bf16 v[112:115], v[166:169], v[212:215], v[112:115]
	v_mfma_f32_16x16x32_bf16 v[104:107], v[174:177], v[212:215], v[104:107]
	v_mfma_f32_16x16x32_bf16 v[96:99], v[166:169], v[220:223], v[96:99]
	v_mfma_f32_16x16x32_bf16 v[88:91], v[174:177], v[220:223], v[88:91]
	v_mfma_f32_16x16x32_bf16 v[80:83], v[166:169], v[228:231], v[80:83]
	v_mfma_f32_16x16x32_bf16 v[72:75], v[174:177], v[228:231], v[72:75]
	v_mfma_f32_16x16x32_bf16 v[116:119], v[178:181], v[200:203], v[116:119]
	v_mfma_f32_16x16x32_bf16 v[108:111], v[186:189], v[200:203], v[108:111]
	v_mfma_f32_16x16x32_bf16 v[100:103], v[178:181], v[208:211], v[100:103]
	v_mfma_f32_16x16x32_bf16 v[92:95], v[186:189], v[208:211], v[92:95]
	v_mfma_f32_16x16x32_bf16 v[84:87], v[178:181], v[216:219], v[84:87]
	v_mfma_f32_16x16x32_bf16 v[76:79], v[186:189], v[216:219], v[76:79]
	v_mfma_f32_16x16x32_bf16 v[68:71], v[178:181], v[224:227], v[68:71]
	v_mfma_f32_16x16x32_bf16 v[64:67], v[186:189], v[224:227], v[64:67]
	v_mfma_f32_16x16x32_bf16 v[116:119], v[182:185], v[204:207], v[116:119]
	v_mfma_f32_16x16x32_bf16 v[108:111], v[196:199], v[204:207], v[108:111]
	v_mfma_f32_16x16x32_bf16 v[100:103], v[182:185], v[212:215], v[100:103]
	v_mfma_f32_16x16x32_bf16 v[92:95], v[196:199], v[212:215], v[92:95]
	v_mfma_f32_16x16x32_bf16 v[84:87], v[182:185], v[220:223], v[84:87]
	v_mfma_f32_16x16x32_bf16 v[76:79], v[196:199], v[220:223], v[76:79]
	v_mfma_f32_16x16x32_bf16 v[68:71], v[182:185], v[228:231], v[68:71]
	v_mfma_f32_16x16x32_bf16 v[64:67], v[196:199], v[228:231], v[64:67]
	s_barrier
	s_add_i32 s6, s57, s27
	v_lshl_add_u64 v[190:191], s[60:61], 0, v[130:131]
	s_mov_b32 m0, s6
	ds_read_b128 v[200:203], v159 offset:16384
	ds_read_b128 v[204:207], v159 offset:17408
	ds_read_b128 v[208:211], v159 offset:18432
	ds_read_b128 v[212:215], v159 offset:19456
	ds_read_b128 v[216:219], v159 offset:20480
	ds_read_b128 v[220:223], v159 offset:21504
	ds_read_b128 v[224:227], v159 offset:22528
	ds_read_b128 v[228:231], v159 offset:23552
	global_load_lds_dwordx4 v[190:191], off
	s_add_i32 m0, s6, 0x2000
	s_add_u32 s6, s60, 0x40000
	v_lshl_add_u64 v[232:233], s[60:61], 0, v[134:135]
	s_addc_u32 s7, s61, 0
	s_add_i32 s73, s67, s27
	global_load_lds_dwordx4 v[232:233], off
	s_mov_b32 m0, s73
	v_lshl_add_u64 v[236:237], s[78:79], 0, v[132:133]
	global_load_lds_dwordx4 v130, s[6:7]
	s_add_i32 m0, s73, 0x2000
	s_nop 0
	global_load_lds_dwordx4 v134, s[6:7]
	v_lshl_add_u64 v[234:235], s[78:79], 0, v[128:129]
	s_mov_b32 m0, s30
	s_nop 0
	global_load_lds_dwordx4 v[234:235], off
	s_mov_b32 m0, s31
	s_nop 0
	global_load_lds_dwordx4 v[236:237], off
	s_waitcnt vmcnt(8)
	s_waitcnt lgkmcnt(0)
	s_barrier
	s_waitcnt lgkmcnt(0)
	v_mfma_f32_16x16x32_bf16 v[60:63], v[144:147], v[200:203], v[60:63]
	v_mfma_f32_16x16x32_bf16 v[56:59], v[170:173], v[200:203], v[56:59]
	v_mfma_f32_16x16x32_bf16 v[52:55], v[144:147], v[208:211], v[52:55]
	v_mfma_f32_16x16x32_bf16 v[40:43], v[170:173], v[208:211], v[40:43]
	v_mfma_f32_16x16x32_bf16 v[36:39], v[144:147], v[216:219], v[36:39]
	v_mfma_f32_16x16x32_bf16 v[24:27], v[170:173], v[216:219], v[24:27]
	v_mfma_f32_16x16x32_bf16 v[20:23], v[144:147], v[224:227], v[20:23]
	v_mfma_f32_16x16x32_bf16 v[8:11], v[170:173], v[224:227], v[8:11]
	v_mfma_f32_16x16x32_bf16 v[60:63], v[166:169], v[204:207], v[60:63]
	v_mfma_f32_16x16x32_bf16 v[56:59], v[174:177], v[204:207], v[56:59]
	v_mfma_f32_16x16x32_bf16 v[52:55], v[166:169], v[212:215], v[52:55]
	v_mfma_f32_16x16x32_bf16 v[40:43], v[174:177], v[212:215], v[40:43]
	v_mfma_f32_16x16x32_bf16 v[36:39], v[166:169], v[220:223], v[36:39]
	v_mfma_f32_16x16x32_bf16 v[24:27], v[174:177], v[220:223], v[24:27]
	v_mfma_f32_16x16x32_bf16 v[20:23], v[166:169], v[228:231], v[20:23]
	v_mfma_f32_16x16x32_bf16 v[8:11], v[174:177], v[228:231], v[8:11]
	v_mfma_f32_16x16x32_bf16 v[48:51], v[178:181], v[200:203], v[48:51]
	v_mfma_f32_16x16x32_bf16 v[44:47], v[186:189], v[200:203], v[44:47]
	v_mfma_f32_16x16x32_bf16 v[32:35], v[178:181], v[208:211], v[32:35]
	v_mfma_f32_16x16x32_bf16 v[28:31], v[186:189], v[208:211], v[28:31]
	v_mfma_f32_16x16x32_bf16 v[16:19], v[178:181], v[216:219], v[16:19]
	v_mfma_f32_16x16x32_bf16 v[12:15], v[186:189], v[216:219], v[12:15]
	v_mfma_f32_16x16x32_bf16 v[4:7], v[178:181], v[224:227], v[4:7]
	v_mfma_f32_16x16x32_bf16 v[0:3], v[186:189], v[224:227], v[0:3]
	v_mfma_f32_16x16x32_bf16 v[48:51], v[182:185], v[204:207], v[48:51]
	v_mfma_f32_16x16x32_bf16 v[44:47], v[196:199], v[204:207], v[44:47]
	v_mfma_f32_16x16x32_bf16 v[32:35], v[182:185], v[212:215], v[32:35]
	v_mfma_f32_16x16x32_bf16 v[28:31], v[196:199], v[212:215], v[28:31]
	v_mfma_f32_16x16x32_bf16 v[16:19], v[182:185], v[220:223], v[16:19]
	v_mfma_f32_16x16x32_bf16 v[12:15], v[196:199], v[220:223], v[12:15]
	v_mfma_f32_16x16x32_bf16 v[4:7], v[182:185], v[228:231], v[4:7]
	v_mfma_f32_16x16x32_bf16 v[0:3], v[196:199], v[228:231], v[0:3]
	s_barrier
; #define PG8_STAGE(bufoff, gbase, voff) do { _Pragma("unroll") for (int _i = 0; _i < 2; ++_i) \
;         __builtin_amdgcn_global_load_lds((const unsigned*)((const char*)(gbase) + (voff)[_i]), (PG8_LAS unsigned*)(lds + (bufoff) + ldsw + _i * 8192), 16, 0, 0); } while (0)
; #define PG8_LDA(dst, b, h) do { _Pragma("unroll") for (int m = 0; m < 4; ++m) _Pragma("unroll") for (int k = 0; k < 2; ++k) dst[m][k] = *(const PG8_LAS bf16x8*)(lds + PG8_SA(b, h) + aoff + m * 2048 + k * 1024); } while (0)
; #define PG8_LDB(dst, b, h) do { _Pragma("unroll") for (int n = 0; n < 2; ++n) _Pragma("unroll") for (int k = 0; k < 2; ++k) dst[n][k] = *(const PG8_LAS bf16x8*)(lds + PG8_SB(b, h) + boff + n * 2048 + k * 1024); } while (0)
; #define PG8_MMA(ai, bj, At, Bt) do { __builtin_amdgcn_s_setprio(1); _Pragma("unroll") for (int m = 0; m < 4; ++m) _Pragma("unroll") for (int n = 0; n < 2; ++n) _Pragma("unroll") for (int k = 0; k < 2; ++k) \
;         acc[ai][bj][m][n] = __builtin_amdgcn_mfma_f32_16x16x32_bf16(Bt[n][k], At[m][k], acc[ai][bj][m][n], 0, 0, 0); __builtin_amdgcn_s_setprio(0); } while (0)
; #define PG8_WAIT_V(n) asm volatile("s_waitcnt vmcnt(" #n ")" ::: "memory")
; #define PG8_WAIT_L(n) asm volatile("s_waitcnt lgkmcnt(" #n ")" ::: "memory")
; #define PG8_BAR __builtin_amdgcn_s_barrier()
; #define PG8_SCHED __builtin_amdgcn_sched_barrier(0)
; template <class Epi, class Sched, bool ALIGN_EPI = false, bool SP2 = false>
; __device__ __forceinline__ void gemm_phase(PG8_LAS unsigned char* lds, const Gemm g, const Sched& S, const Epi& E) {
;     ...
;             PG8_LDB(B0, 1, 0); PG8_LDB(B1, 1, 1); PG8_SCHED; PG8_LDA(At, 1, 0); PG8_STAGE(PG8_SA(0, 1), a2 + hstep, voffA);
;             PG8_WAIT_V(8); PG8_WAIT_L(0); PG8_BAR; PG8_MMA(0, 0, At, B0); PG8_MMA(0, 1, At, B1); PG8_BAR; PG8_SCHED;
;             PG8_LDA(At, 1, 1); PG8_STAGE(PG8_SB(1, 0), b3, voffB); PG8_STAGE(PG8_SB(1, 1), b3 + hstep, voffB); PG8_STAGE(PG8_SA(1, 0), a3, voffA);
;             PG8_WAIT_V(8); PG8_WAIT_L(0); PG8_BAR; PG8_MMA(1, 0, At, B0); PG8_MMA(1, 1, At, B1); PG8_BAR; PG8_SCHED;
	s_add_i32 s73, 0, 0x18000
	s_add_i32 s80, 0, 0x1c000
	ds_read_b128 v[144:147], v244
	ds_read_b128 v[166:169], v244 offset:1024
	ds_read_b128 v[170:173], v244 offset:2048
	ds_read_b128 v[174:177], v244 offset:3072
	ds_read_b128 v[178:181], v245
	ds_read_b128 v[182:185], v245 offset:1024
	ds_read_b128 v[186:189], v245 offset:2048
	ds_read_b128 v[196:199], v245 offset:3072
	s_add_u32 s6, s78, 0x40000
	s_addc_u32 s7, s79, 0
	s_mov_b32 m0, s42
	ds_read_b128 v[200:203], v159 offset:32768
	ds_read_b128 v[204:207], v159 offset:33792
	ds_read_b128 v[208:211], v159 offset:34816
	ds_read_b128 v[212:215], v159 offset:35840
	ds_read_b128 v[216:219], v159 offset:36864
	ds_read_b128 v[220:223], v159 offset:37888
	ds_read_b128 v[224:227], v159 offset:38912
	ds_read_b128 v[228:231], v159 offset:39936
	global_load_lds_dwordx4 v128, s[6:7]
	s_mov_b32 m0, s43
	s_nop 0
	global_load_lds_dwordx4 v132, s[6:7]
	s_waitcnt vmcnt(8)
	s_waitcnt lgkmcnt(0)
	s_barrier
	s_waitcnt lgkmcnt(0)
	v_mfma_f32_16x16x32_bf16 v[124:127], v[144:147], v[200:203], v[124:127]
	v_mfma_f32_16x16x32_bf16 v[120:123], v[170:173], v[200:203], v[120:123]
	v_mfma_f32_16x16x32_bf16 v[112:115], v[144:147], v[208:211], v[112:115]
	v_mfma_f32_16x16x32_bf16 v[104:107], v[170:173], v[208:211], v[104:107]
	v_mfma_f32_16x16x32_bf16 v[96:99], v[144:147], v[216:219], v[96:99]
	v_mfma_f32_16x16x32_bf16 v[88:91], v[170:173], v[216:219], v[88:91]
	v_mfma_f32_16x16x32_bf16 v[80:83], v[144:147], v[224:227], v[80:83]
	v_mfma_f32_16x16x32_bf16 v[72:75], v[170:173], v[224:227], v[72:75]
	v_mfma_f32_16x16x32_bf16 v[124:127], v[166:169], v[204:207], v[124:127]
	v_mfma_f32_16x16x32_bf16 v[120:123], v[174:177], v[204:207], v[120:123]
	v_mfma_f32_16x16x32_bf16 v[112:115], v[166:169], v[212:215], v[112:115]
	v_mfma_f32_16x16x32_bf16 v[104:107], v[174:177], v[212:215], v[104:107]
	v_mfma_f32_16x16x32_bf16 v[96:99], v[166:169], v[220:223], v[96:99]
	v_mfma_f32_16x16x32_bf16 v[88:91], v[174:177], v[220:223], v[88:91]
	v_mfma_f32_16x16x32_bf16 v[80:83], v[166:169], v[228:231], v[80:83]
	v_mfma_f32_16x16x32_bf16 v[72:75], v[174:177], v[228:231], v[72:75]
	v_mfma_f32_16x16x32_bf16 v[116:119], v[178:181], v[200:203], v[116:119]
	v_mfma_f32_16x16x32_bf16 v[108:111], v[186:189], v[200:203], v[108:111]
	v_mfma_f32_16x16x32_bf16 v[100:103], v[178:181], v[208:211], v[100:103]
	v_mfma_f32_16x16x32_bf16 v[92:95], v[186:189], v[208:211], v[92:95]
	v_mfma_f32_16x16x32_bf16 v[84:87], v[178:181], v[216:219], v[84:87]
	v_mfma_f32_16x16x32_bf16 v[76:79], v[186:189], v[216:219], v[76:79]
	v_mfma_f32_16x16x32_bf16 v[68:71], v[178:181], v[224:227], v[68:71]
	v_mfma_f32_16x16x32_bf16 v[64:67], v[186:189], v[224:227], v[64:67]
	v_mfma_f32_16x16x32_bf16 v[116:119], v[182:185], v[204:207], v[116:119]
	v_mfma_f32_16x16x32_bf16 v[108:111], v[196:199], v[204:207], v[108:111]
	v_mfma_f32_16x16x32_bf16 v[100:103], v[182:185], v[212:215], v[100:103]
	v_mfma_f32_16x16x32_bf16 v[92:95], v[196:199], v[212:215], v[92:95]
	v_mfma_f32_16x16x32_bf16 v[84:87], v[182:185], v[220:223], v[84:87]
	v_mfma_f32_16x16x32_bf16 v[76:79], v[196:199], v[220:223], v[76:79]
	v_mfma_f32_16x16x32_bf16 v[68:71], v[182:185], v[228:231], v[68:71]
	v_mfma_f32_16x16x32_bf16 v[64:67], v[196:199], v[228:231], v[64:67]
	s_barrier
	s_add_i32 s6, s73, s27
	v_lshl_add_u64 v[190:191], v[190:191], 0, s[38:39]
	s_mov_b32 m0, s6
	ds_read_b128 v[200:203], v159 offset:49152
	ds_read_b128 v[204:207], v159 offset:50176
	ds_read_b128 v[208:211], v159 offset:51200
	ds_read_b128 v[212:215], v159 offset:52224
	ds_read_b128 v[216:219], v159 offset:53248
	ds_read_b128 v[220:223], v159 offset:54272
	ds_read_b128 v[224:227], v159 offset:55296
	ds_read_b128 v[228:231], v159 offset:56320
	global_load_lds_dwordx4 v[190:191], off
	s_add_i32 m0, s6, 0x2000
	s_add_u32 s6, s60, 0x40080
	v_lshl_add_u64 v[190:191], v[232:233], 0, s[38:39]
	s_addc_u32 s7, s61, 0
	s_add_i32 s60, s80, s27
	global_load_lds_dwordx4 v[190:191], off
	v_lshl_add_u64 v[190:191], s[6:7], 0, v[130:131]
	s_mov_b32 m0, s60
	s_nop 0
	global_load_lds_dwordx4 v[190:191], off
	v_lshl_add_u64 v[190:191], s[6:7], 0, v[134:135]
	s_add_i32 m0, s60, 0x2000
	s_nop 0
	global_load_lds_dwordx4 v[190:191], off
	v_lshl_add_u64 v[190:191], v[234:235], 0, s[38:39]
	s_mov_b32 m0, s44
	s_nop 0
	global_load_lds_dwordx4 v[190:191], off
	v_lshl_add_u64 v[190:191], v[236:237], 0, s[38:39]
	s_mov_b32 m0, s45
	s_nop 0
	global_load_lds_dwordx4 v[190:191], off
	s_waitcnt vmcnt(8)
	s_waitcnt lgkmcnt(0)
	s_barrier
	s_waitcnt lgkmcnt(0)
	v_mfma_f32_16x16x32_bf16 v[60:63], v[144:147], v[200:203], v[60:63]
	v_mfma_f32_16x16x32_bf16 v[56:59], v[170:173], v[200:203], v[56:59]
	v_mfma_f32_16x16x32_bf16 v[52:55], v[144:147], v[208:211], v[52:55]
	v_mfma_f32_16x16x32_bf16 v[40:43], v[170:173], v[208:211], v[40:43]
	v_mfma_f32_16x16x32_bf16 v[36:39], v[144:147], v[216:219], v[36:39]
	v_mfma_f32_16x16x32_bf16 v[24:27], v[170:173], v[216:219], v[24:27]
	v_mfma_f32_16x16x32_bf16 v[20:23], v[144:147], v[224:227], v[20:23]
	v_mfma_f32_16x16x32_bf16 v[8:11], v[170:173], v[224:227], v[8:11]
	v_mfma_f32_16x16x32_bf16 v[60:63], v[166:169], v[204:207], v[60:63]
	v_mfma_f32_16x16x32_bf16 v[56:59], v[174:177], v[204:207], v[56:59]
	v_mfma_f32_16x16x32_bf16 v[52:55], v[166:169], v[212:215], v[52:55]
	v_mfma_f32_16x16x32_bf16 v[40:43], v[174:177], v[212:215], v[40:43]
	v_mfma_f32_16x16x32_bf16 v[36:39], v[166:169], v[220:223], v[36:39]
	v_mfma_f32_16x16x32_bf16 v[24:27], v[174:177], v[220:223], v[24:27]
	v_mfma_f32_16x16x32_bf16 v[20:23], v[166:169], v[228:231], v[20:23]
	v_mfma_f32_16x16x32_bf16 v[8:11], v[174:177], v[228:231], v[8:11]
	v_mfma_f32_16x16x32_bf16 v[48:51], v[178:181], v[200:203], v[48:51]
	v_mfma_f32_16x16x32_bf16 v[44:47], v[186:189], v[200:203], v[44:47]
	v_mfma_f32_16x16x32_bf16 v[32:35], v[178:181], v[208:211], v[32:35]
	v_mfma_f32_16x16x32_bf16 v[28:31], v[186:189], v[208:211], v[28:31]
	v_mfma_f32_16x16x32_bf16 v[16:19], v[178:181], v[216:219], v[16:19]
	v_mfma_f32_16x16x32_bf16 v[12:15], v[186:189], v[216:219], v[12:15]
	v_mfma_f32_16x16x32_bf16 v[4:7], v[178:181], v[224:227], v[4:7]
	v_mfma_f32_16x16x32_bf16 v[0:3], v[186:189], v[224:227], v[0:3]
	v_mfma_f32_16x16x32_bf16 v[48:51], v[182:185], v[204:207], v[48:51]
	v_mfma_f32_16x16x32_bf16 v[44:47], v[196:199], v[204:207], v[44:47]
	v_mfma_f32_16x16x32_bf16 v[32:35], v[182:185], v[212:215], v[32:35]
	v_mfma_f32_16x16x32_bf16 v[28:31], v[196:199], v[212:215], v[28:31]
	v_mfma_f32_16x16x32_bf16 v[16:19], v[182:185], v[220:223], v[16:19]
	v_mfma_f32_16x16x32_bf16 v[12:15], v[196:199], v[220:223], v[12:15]
	v_mfma_f32_16x16x32_bf16 v[4:7], v[182:185], v[228:231], v[4:7]
	v_mfma_f32_16x16x32_bf16 v[0:3], v[196:199], v[228:231], v[0:3]
	s_barrier
	s_add_i32 s72, s72, 2
	s_add_u32 s58, s58, 0x100
	s_addc_u32 s59, s59, 0
	s_add_u32 s77, s77, 0x100
	s_addc_u32 s33, s33, 0
	s_cmp_gt_u32 s72, 13
	s_cbranch_scc0 .LBB0_1392
	s_and_b64 vcc, exec, s[40:41]
	s_cbranch_vccz .LBB0_1395
	s_barrier

; #define PG8_STAGE(bufoff, gbase, voff) do { _Pragma("unroll") for (int _i = 0; _i < 2; ++_i) \
;         __builtin_amdgcn_global_load_lds((const unsigned*)((const char*)(gbase) + (voff)[_i]), (PG8_LAS unsigned*)(lds + (bufoff) + ldsw + _i * 8192), 16, 0, 0); } while (0)
; #define PG8_LDA(dst, b, h) do { _Pragma("unroll") for (int m = 0; m < 4; ++m) _Pragma("unroll") for (int k = 0; k < 2; ++k) dst[m][k] = *(const PG8_LAS bf16x8*)(lds + PG8_SA(b, h) + aoff + m * 2048 + k * 1024); } while (0)
; #define PG8_LDB(dst, b, h) do { _Pragma("unroll") for (int n = 0; n < 2; ++n) _Pragma("unroll") for (int k = 0; k < 2; ++k) dst[n][k] = *(const PG8_LAS bf16x8*)(lds + PG8_SB(b, h) + boff + n * 2048 + k * 1024); } while (0)
; #define PG8_MMA(ai, bj, At, Bt) do { __builtin_amdgcn_s_setprio(1); _Pragma("unroll") for (int m = 0; m < 4; ++m) _Pragma("unroll") for (int n = 0; n < 2; ++n) _Pragma("unroll") for (int k = 0; k < 2; ++k) \
;         acc[ai][bj][m][n] = __builtin_amdgcn_mfma_f32_16x16x32_bf16(Bt[n][k], At[m][k], acc[ai][bj][m][n], 0, 0, 0); __builtin_amdgcn_s_setprio(0); } while (0)
; #define PG8_WAIT_V(n) asm volatile("s_waitcnt vmcnt(" #n ")" ::: "memory")
; template <class Epi, class Sched, bool ALIGN_EPI = false, bool SP2 = false>
; __device__ __forceinline__ void gemm_phase(PG8_LAS unsigned char* lds, const Gemm g, const Sched& S, const Epi& E) {
;     ...
;         for (int t = 0; t < nt; t += 2) {
;             const bool last = (t == nt - 2);
;             const char* a1 = cA + (size_t)(t + 1) * kstep;
;             const char* a2 = last ? nA : cA + (size_t)(t + 2) * kstep; const char* b2 = last ? nB : cB + (size_t)(t + 2) * kstep;
;             const char* a3 = a2 + kstep; const char* b3 = b2 + kstep;
;             if (last && has_next) S.a_ready(nxt);
;             if constexpr (SP2) {
;             PG8_LDB(B0, 0, 0); PG8_LDB(B1, 0, 1); PG8_SCHED; PG8_LDA(At, 0, 0); PG8_STAGE(PG8_SA(1, 1), a1 + hstep, voffA);
;             PG8_WAIT_V(8); PG8_WAIT_L(0); PG8_BAR; PG8_MMA(0, 0, At, B0); PG8_MMA(0, 1, At, B1); PG8_BAR; PG8_SCHED;
;     ...
; #pragma unroll
;         for (int a = 0; a < 2; ++a)
; #pragma unroll
;             for (int b = 0; b < 2; ++b)
; #pragma unroll
;                 for (int m = 0; m < 4; ++m)
; #pragma unroll
;                     for (int n = 0; n < 2; ++n) acc[a][b][m][n] = (f32x4){0.f, 0.f, 0.f, 0.f};
;         cur = nxt; cA = nA; cB = nB; ++ui;
.LBB0_1697:
	s_ashr_i32 s55, s54, 31
	s_lshl_b64 s[6:7], s[54:55], 19
	s_add_u32 s56, s36, s6
	s_addc_u32 s57, s37, s7
	s_and_b64 s[6:7], s[48:49], exec
	s_cselect_b32 s29, s57, s61
	s_cselect_b32 s55, s56, s60
	s_ashr_i32 s53, s52, 31
	s_lshl_b64 s[6:7], s[52:53], 19
	s_add_u32 s58, s5, s6
	s_addc_u32 s59, s27, s7
	s_and_b64 s[6:7], s[48:49], exec
	s_cselect_b32 s53, s59, s79
	s_cselect_b32 s68, s58, s78
	s_add_u32 s60, s60, 0x40080
	s_addc_u32 s61, s61, 0
	s_add_u32 s69, s78, 0x100
	v_mov_b32_e32 v0, 0
	s_addc_u32 s33, s79, 0
	s_mov_b32 s72, -2
	s_waitcnt lgkmcnt(0)
	v_mov_b32_e32 v1, v0
	v_mov_b32_e32 v2, v0
	v_mov_b32_e32 v3, v0
	v_mov_b32_e32 v4, v0
	v_mov_b32_e32 v5, v0
	v_mov_b32_e32 v6, v0
	v_mov_b32_e32 v7, v0
	v_mov_b32_e32 v16, v0
	v_mov_b32_e32 v17, v0
	v_mov_b32_e32 v18, v0
	v_mov_b32_e32 v19, v0
	v_mov_b32_e32 v20, v0
	v_mov_b32_e32 v21, v0
	v_mov_b32_e32 v22, v0
	v_mov_b32_e32 v23, v0
	v_mov_b32_e32 v32, v0
	v_mov_b32_e32 v33, v0
	v_mov_b32_e32 v34, v0
	v_mov_b32_e32 v35, v0
	s_waitcnt vmcnt(0)
	v_mov_b32_e32 v36, v0
	v_mov_b32_e32 v37, v0
	v_mov_b32_e32 v38, v0
	v_mov_b32_e32 v39, v0
	v_mov_b32_e32 v48, v0
	v_mov_b32_e32 v49, v0
	v_mov_b32_e32 v50, v0
	v_mov_b32_e32 v51, v0
	v_mov_b32_e32 v52, v0
	v_mov_b32_e32 v53, v0
	v_mov_b32_e32 v54, v0
	v_mov_b32_e32 v55, v0
	v_mov_b32_e32 v8, v0
	v_mov_b32_e32 v9, v0
	v_mov_b32_e32 v10, v0
	v_mov_b32_e32 v11, v0
	v_mov_b32_e32 v12, v0
	v_mov_b32_e32 v13, v0
	v_mov_b32_e32 v14, v0
	v_mov_b32_e32 v15, v0
	v_mov_b32_e32 v24, v0
	v_mov_b32_e32 v25, v0
	v_mov_b32_e32 v26, v0
	v_mov_b32_e32 v27, v0
	v_mov_b32_e32 v28, v0
	v_mov_b32_e32 v29, v0
	v_mov_b32_e32 v30, v0
	v_mov_b32_e32 v31, v0
	v_mov_b32_e32 v40, v0
	v_mov_b32_e32 v41, v0
	v_mov_b32_e32 v42, v0
	v_mov_b32_e32 v43, v0
	v_mov_b32_e32 v44, v0
	v_mov_b32_e32 v45, v0
	v_mov_b32_e32 v46, v0
	v_mov_b32_e32 v47, v0
	v_mov_b32_e32 v56, v0
	v_mov_b32_e32 v57, v0
	v_mov_b32_e32 v58, v0
	v_mov_b32_e32 v59, v0
	v_mov_b32_e32 v60, v0
	v_mov_b32_e32 v61, v0
	v_mov_b32_e32 v62, v0
	v_mov_b32_e32 v63, v0
	v_mov_b32_e32 v64, v0
	v_mov_b32_e32 v65, v0
	v_mov_b32_e32 v66, v0
	v_mov_b32_e32 v67, v0
	v_mov_b32_e32 v68, v0
	v_mov_b32_e32 v69, v0
	v_mov_b32_e32 v70, v0
	v_mov_b32_e32 v71, v0
	v_mov_b32_e32 v80, v0
	v_mov_b32_e32 v81, v0
	v_mov_b32_e32 v82, v0
	v_mov_b32_e32 v83, v0
	v_mov_b32_e32 v84, v0
	v_mov_b32_e32 v85, v0
	v_mov_b32_e32 v86, v0
	v_mov_b32_e32 v87, v0
	v_mov_b32_e32 v96, v0
	v_mov_b32_e32 v97, v0
	v_mov_b32_e32 v98, v0
	v_mov_b32_e32 v99, v0
	v_mov_b32_e32 v100, v0
	v_mov_b32_e32 v101, v0
	v_mov_b32_e32 v102, v0
	v_mov_b32_e32 v103, v0
	v_mov_b32_e32 v112, v0
	v_mov_b32_e32 v113, v0
	v_mov_b32_e32 v114, v0
	v_mov_b32_e32 v115, v0
	v_mov_b32_e32 v116, v0
	v_mov_b32_e32 v117, v0
	v_mov_b32_e32 v118, v0
	v_mov_b32_e32 v119, v0
	v_mov_b32_e32 v72, v0
	v_mov_b32_e32 v73, v0
	v_mov_b32_e32 v74, v0
	v_mov_b32_e32 v75, v0
	v_mov_b32_e32 v76, v0
	v_mov_b32_e32 v77, v0
	v_mov_b32_e32 v78, v0
	v_mov_b32_e32 v79, v0
	v_mov_b32_e32 v88, v0
	v_mov_b32_e32 v89, v0
	v_mov_b32_e32 v90, v0
	v_mov_b32_e32 v91, v0
	v_mov_b32_e32 v92, v0
	v_mov_b32_e32 v93, v0
	v_mov_b32_e32 v94, v0
	v_mov_b32_e32 v95, v0
	v_mov_b32_e32 v104, v0
	v_mov_b32_e32 v105, v0
	v_mov_b32_e32 v106, v0
	v_mov_b32_e32 v107, v0
	v_mov_b32_e32 v108, v0
	v_mov_b32_e32 v109, v0
	v_mov_b32_e32 v110, v0
	v_mov_b32_e32 v111, v0
	v_mov_b32_e32 v120, v0
	v_mov_b32_e32 v121, v0
	v_mov_b32_e32 v122, v0
	v_mov_b32_e32 v123, v0
	v_mov_b32_e32 v124, v0
	v_mov_b32_e32 v125, v0
	v_mov_b32_e32 v126, v0
	v_mov_b32_e32 v127, v0
	v_add_u32_e32 v244, 0x18000, v151
	v_add_u32_e32 v245, 0x1c000, v151
.LBB0_1698:
	ds_read_b128 v[144:147], v153
	ds_read_b128 v[170:173], v153 offset:1024
	ds_read_b128 v[174:177], v153 offset:2048
	ds_read_b128 v[178:181], v153 offset:3072
	ds_read_b128 v[182:185], v154
	ds_read_b128 v[186:189], v154 offset:1024
	ds_read_b128 v[198:201], v154 offset:2048
	ds_read_b128 v[202:205], v154 offset:3072
	s_add_u32 s6, s60, 0xfffc0080
	s_addc_u32 s7, s61, -1
	s_cmp_eq_u32 s72, 12
	s_cselect_b32 s81, s29, s7
	s_cselect_b32 s80, s55, s6
	s_cselect_b32 s79, s53, s33
	s_cselect_b32 s78, s68, s69
	s_add_i32 m0, s43, 0xc000
	ds_read_b128 v[206:209], v155
	ds_read_b128 v[210:213], v155 offset:1024
	ds_read_b128 v[214:217], v155 offset:2048
	ds_read_b128 v[218:221], v155 offset:3072
	ds_read_b128 v[222:225], v155 offset:4096
	ds_read_b128 v[226:229], v155 offset:5120
	ds_read_b128 v[230:233], v155 offset:6144
	ds_read_b128 v[234:237], v155 offset:7168
	global_load_lds_dwordx4 v136, s[60:61]
	s_add_i32 m0, s43, 0xe000
	s_nop 0
	global_load_lds_dwordx4 v138, s[60:61]
	s_waitcnt vmcnt(8)
	s_waitcnt lgkmcnt(0)
	s_barrier
; #define PG8_STAGE(bufoff, gbase, voff) do { _Pragma("unroll") for (int _i = 0; _i < 2; ++_i) \
;         __builtin_amdgcn_global_load_lds((const unsigned*)((const char*)(gbase) + (voff)[_i]), (PG8_LAS unsigned*)(lds + (bufoff) + ldsw + _i * 8192), 16, 0, 0); } while (0)
; #define PG8_LDA(dst, b, h) do { _Pragma("unroll") for (int m = 0; m < 4; ++m) _Pragma("unroll") for (int k = 0; k < 2; ++k) dst[m][k] = *(const PG8_LAS bf16x8*)(lds + PG8_SA(b, h) + aoff + m * 2048 + k * 1024); } while (0)
; #define PG8_MMA(ai, bj, At, Bt) do { __builtin_amdgcn_s_setprio(1); _Pragma("unroll") for (int m = 0; m < 4; ++m) _Pragma("unroll") for (int n = 0; n < 2; ++n) _Pragma("unroll") for (int k = 0; k < 2; ++k) \
;         acc[ai][bj][m][n] = __builtin_amdgcn_mfma_f32_16x16x32_bf16(Bt[n][k], At[m][k], acc[ai][bj][m][n], 0, 0, 0); __builtin_amdgcn_s_setprio(0); } while (0)
; #define PG8_WAIT_V(n) asm volatile("s_waitcnt vmcnt(" #n ")" ::: "memory")
; #define PG8_WAIT_L(n) asm volatile("s_waitcnt lgkmcnt(" #n ")" ::: "memory")
; #define PG8_BAR __builtin_amdgcn_s_barrier()
; #define PG8_SCHED __builtin_amdgcn_sched_barrier(0)
; template <class Epi, class Sched, bool ALIGN_EPI = false, bool SP2 = false>
; __device__ __forceinline__ void gemm_phase(PG8_LAS unsigned char* lds, const Gemm g, const Sched& S, const Epi& E) {
;     ...
;             PG8_WAIT_V(8); PG8_WAIT_L(0); PG8_BAR; PG8_MMA(0, 0, At, B0); PG8_MMA(0, 1, At, B1); PG8_BAR; PG8_SCHED;
;             PG8_LDA(At, 0, 1); PG8_STAGE(PG8_SB(0, 0), b2, voffB); PG8_STAGE(PG8_SB(0, 1), b2 + hstep, voffB); PG8_STAGE(PG8_SA(0, 0), a2, voffA);
;             PG8_WAIT_V(8); PG8_WAIT_L(0); PG8_BAR; PG8_MMA(1, 0, At, B0); PG8_MMA(1, 1, At, B1); PG8_BAR; PG8_SCHED;
	s_waitcnt lgkmcnt(0)
	v_mfma_f32_16x16x32_bf16 v[124:127], v[144:147], v[206:209], v[124:127]
	v_mfma_f32_16x16x32_bf16 v[120:123], v[174:177], v[206:209], v[120:123]
	v_mfma_f32_16x16x32_bf16 v[108:111], v[144:147], v[214:217], v[108:111]
	v_mfma_f32_16x16x32_bf16 v[104:107], v[174:177], v[214:217], v[104:107]
	v_mfma_f32_16x16x32_bf16 v[92:95], v[144:147], v[222:225], v[92:95]
	v_mfma_f32_16x16x32_bf16 v[88:91], v[174:177], v[222:225], v[88:91]
	v_mfma_f32_16x16x32_bf16 v[76:79], v[144:147], v[230:233], v[76:79]
	v_mfma_f32_16x16x32_bf16 v[72:75], v[174:177], v[230:233], v[72:75]
	v_mfma_f32_16x16x32_bf16 v[124:127], v[170:173], v[210:213], v[124:127]
	v_mfma_f32_16x16x32_bf16 v[120:123], v[178:181], v[210:213], v[120:123]
	v_mfma_f32_16x16x32_bf16 v[108:111], v[170:173], v[218:221], v[108:111]
	v_mfma_f32_16x16x32_bf16 v[104:107], v[178:181], v[218:221], v[104:107]
	v_mfma_f32_16x16x32_bf16 v[92:95], v[170:173], v[226:229], v[92:95]
	v_mfma_f32_16x16x32_bf16 v[88:91], v[178:181], v[226:229], v[88:91]
	v_mfma_f32_16x16x32_bf16 v[76:79], v[170:173], v[234:237], v[76:79]
	v_mfma_f32_16x16x32_bf16 v[72:75], v[178:181], v[234:237], v[72:75]
	v_mfma_f32_16x16x32_bf16 v[116:119], v[182:185], v[206:209], v[116:119]
	v_mfma_f32_16x16x32_bf16 v[112:115], v[198:201], v[206:209], v[112:115]
	v_mfma_f32_16x16x32_bf16 v[100:103], v[182:185], v[214:217], v[100:103]
	v_mfma_f32_16x16x32_bf16 v[96:99], v[198:201], v[214:217], v[96:99]
	v_mfma_f32_16x16x32_bf16 v[84:87], v[182:185], v[222:225], v[84:87]
	v_mfma_f32_16x16x32_bf16 v[80:83], v[198:201], v[222:225], v[80:83]
	v_mfma_f32_16x16x32_bf16 v[68:71], v[182:185], v[230:233], v[68:71]
	v_mfma_f32_16x16x32_bf16 v[64:67], v[198:201], v[230:233], v[64:67]
	v_mfma_f32_16x16x32_bf16 v[116:119], v[186:189], v[210:213], v[116:119]
	v_mfma_f32_16x16x32_bf16 v[112:115], v[202:205], v[210:213], v[112:115]
	v_mfma_f32_16x16x32_bf16 v[100:103], v[186:189], v[218:221], v[100:103]
	v_mfma_f32_16x16x32_bf16 v[96:99], v[202:205], v[218:221], v[96:99]
	v_mfma_f32_16x16x32_bf16 v[84:87], v[186:189], v[226:229], v[84:87]
	v_mfma_f32_16x16x32_bf16 v[80:83], v[202:205], v[226:229], v[80:83]
	v_mfma_f32_16x16x32_bf16 v[68:71], v[186:189], v[234:237], v[68:71]
	v_mfma_f32_16x16x32_bf16 v[64:67], v[202:205], v[234:237], v[64:67]
	s_barrier
	s_add_i32 s6, s26, s42
	s_mov_b32 m0, s6
	ds_read_b128 v[206:209], v155 offset:16384
	ds_read_b128 v[210:213], v155 offset:17408
	ds_read_b128 v[214:217], v155 offset:18432
	ds_read_b128 v[218:221], v155 offset:19456
	ds_read_b128 v[222:225], v155 offset:20480
	ds_read_b128 v[226:229], v155 offset:21504
	ds_read_b128 v[230:233], v155 offset:22528
	ds_read_b128 v[234:237], v155 offset:23552
	global_load_lds_dwordx4 v130, s[78:79]
	s_add_i32 m0, s6, 0x2000
	s_add_u32 s6, s78, 0x40000
	s_addc_u32 s7, s79, 0
	s_add_i32 s73, s74, s42
	global_load_lds_dwordx4 v134, s[78:79]
	s_mov_b32 m0, s73
	s_nop 0
	global_load_lds_dwordx4 v130, s[6:7]
	s_add_i32 m0, s73, 0x2000
	s_nop 0
	global_load_lds_dwordx4 v134, s[6:7]
	s_mov_b32 m0, s43
	s_nop 0
	global_load_lds_dwordx4 v128, s[80:81]
	s_mov_b32 m0, s44
	s_nop 0
	global_load_lds_dwordx4 v132, s[80:81]
	s_waitcnt vmcnt(8)
	s_waitcnt lgkmcnt(0)
	s_barrier
	s_waitcnt lgkmcnt(0)
	v_mfma_f32_16x16x32_bf16 v[60:63], v[144:147], v[206:209], v[60:63]
	v_mfma_f32_16x16x32_bf16 v[56:59], v[174:177], v[206:209], v[56:59]
	v_mfma_f32_16x16x32_bf16 v[44:47], v[144:147], v[214:217], v[44:47]
	v_mfma_f32_16x16x32_bf16 v[40:43], v[174:177], v[214:217], v[40:43]
	v_mfma_f32_16x16x32_bf16 v[28:31], v[144:147], v[222:225], v[28:31]
	v_mfma_f32_16x16x32_bf16 v[24:27], v[174:177], v[222:225], v[24:27]
	v_mfma_f32_16x16x32_bf16 v[12:15], v[144:147], v[230:233], v[12:15]
	v_mfma_f32_16x16x32_bf16 v[8:11], v[174:177], v[230:233], v[8:11]
	v_mfma_f32_16x16x32_bf16 v[60:63], v[170:173], v[210:213], v[60:63]
	v_mfma_f32_16x16x32_bf16 v[56:59], v[178:181], v[210:213], v[56:59]
	v_mfma_f32_16x16x32_bf16 v[44:47], v[170:173], v[218:221], v[44:47]
	v_mfma_f32_16x16x32_bf16 v[40:43], v[178:181], v[218:221], v[40:43]
	v_mfma_f32_16x16x32_bf16 v[28:31], v[170:173], v[226:229], v[28:31]
	v_mfma_f32_16x16x32_bf16 v[24:27], v[178:181], v[226:229], v[24:27]
	v_mfma_f32_16x16x32_bf16 v[12:15], v[170:173], v[234:237], v[12:15]
	v_mfma_f32_16x16x32_bf16 v[8:11], v[178:181], v[234:237], v[8:11]
	v_mfma_f32_16x16x32_bf16 v[52:55], v[182:185], v[206:209], v[52:55]
	v_mfma_f32_16x16x32_bf16 v[48:51], v[198:201], v[206:209], v[48:51]
	v_mfma_f32_16x16x32_bf16 v[36:39], v[182:185], v[214:217], v[36:39]
	v_mfma_f32_16x16x32_bf16 v[32:35], v[198:201], v[214:217], v[32:35]
	v_mfma_f32_16x16x32_bf16 v[20:23], v[182:185], v[222:225], v[20:23]
	v_mfma_f32_16x16x32_bf16 v[16:19], v[198:201], v[222:225], v[16:19]
	v_mfma_f32_16x16x32_bf16 v[4:7], v[182:185], v[230:233], v[4:7]
	v_mfma_f32_16x16x32_bf16 v[0:3], v[198:201], v[230:233], v[0:3]
	v_mfma_f32_16x16x32_bf16 v[52:55], v[186:189], v[210:213], v[52:55]
	v_mfma_f32_16x16x32_bf16 v[48:51], v[202:205], v[210:213], v[48:51]
	v_mfma_f32_16x16x32_bf16 v[36:39], v[186:189], v[218:221], v[36:39]
	v_mfma_f32_16x16x32_bf16 v[32:35], v[202:205], v[218:221], v[32:35]
	v_mfma_f32_16x16x32_bf16 v[20:23], v[186:189], v[226:229], v[20:23]
	v_mfma_f32_16x16x32_bf16 v[16:19], v[202:205], v[226:229], v[16:19]
	v_mfma_f32_16x16x32_bf16 v[4:7], v[186:189], v[234:237], v[4:7]
	v_mfma_f32_16x16x32_bf16 v[0:3], v[202:205], v[234:237], v[0:3]
	s_barrier
; #define PG8_STAGE(bufoff, gbase, voff) do { _Pragma("unroll") for (int _i = 0; _i < 2; ++_i) \
;         __builtin_amdgcn_global_load_lds((const unsigned*)((const char*)(gbase) + (voff)[_i]), (PG8_LAS unsigned*)(lds + (bufoff) + ldsw + _i * 8192), 16, 0, 0); } while (0)
; #define PG8_LDA(dst, b, h) do { _Pragma("unroll") for (int m = 0; m < 4; ++m) _Pragma("unroll") for (int k = 0; k < 2; ++k) dst[m][k] = *(const PG8_LAS bf16x8*)(lds + PG8_SA(b, h) + aoff + m * 2048 + k * 1024); } while (0)
; #define PG8_LDB(dst, b, h) do { _Pragma("unroll") for (int n = 0; n < 2; ++n) _Pragma("unroll") for (int k = 0; k < 2; ++k) dst[n][k] = *(const PG8_LAS bf16x8*)(lds + PG8_SB(b, h) + boff + n * 2048 + k * 1024); } while (0)
; #define PG8_MMA(ai, bj, At, Bt) do { __builtin_amdgcn_s_setprio(1); _Pragma("unroll") for (int m = 0; m < 4; ++m) _Pragma("unroll") for (int n = 0; n < 2; ++n) _Pragma("unroll") for (int k = 0; k < 2; ++k) \
;         acc[ai][bj][m][n] = __builtin_amdgcn_mfma_f32_16x16x32_bf16(Bt[n][k], At[m][k], acc[ai][bj][m][n], 0, 0, 0); __builtin_amdgcn_s_setprio(0); } while (0)
; #define PG8_WAIT_V(n) asm volatile("s_waitcnt vmcnt(" #n ")" ::: "memory")
; #define PG8_WAIT_L(n) asm volatile("s_waitcnt lgkmcnt(" #n ")" ::: "memory")
; #define PG8_BAR __builtin_amdgcn_s_barrier()
; #define PG8_SCHED __builtin_amdgcn_sched_barrier(0)
; template <class Epi, class Sched, bool ALIGN_EPI = false, bool SP2 = false>
; __device__ __forceinline__ void gemm_phase(PG8_LAS unsigned char* lds, const Gemm g, const Sched& S, const Epi& E) {
;     ...
;             PG8_LDB(B0, 1, 0); PG8_LDB(B1, 1, 1); PG8_SCHED; PG8_LDA(At, 1, 0); PG8_STAGE(PG8_SA(0, 1), a2 + hstep, voffA);
;             PG8_WAIT_V(8); PG8_WAIT_L(0); PG8_BAR; PG8_MMA(0, 0, At, B0); PG8_MMA(0, 1, At, B1); PG8_BAR; PG8_SCHED;
;             PG8_LDA(At, 1, 1); PG8_STAGE(PG8_SB(1, 0), b3, voffB); PG8_STAGE(PG8_SB(1, 1), b3 + hstep, voffB); PG8_STAGE(PG8_SA(1, 0), a3, voffA);
;             PG8_WAIT_V(8); PG8_WAIT_L(0); PG8_BAR; PG8_MMA(1, 0, At, B0); PG8_MMA(1, 1, At, B1); PG8_BAR; PG8_SCHED;
	s_add_i32 s73, 0, 0x18000
	s_add_i32 s82, 0, 0x1c000
	ds_read_b128 v[144:147], v244
	ds_read_b128 v[170:173], v244 offset:1024
	ds_read_b128 v[174:177], v244 offset:2048
	ds_read_b128 v[178:181], v244 offset:3072
	ds_read_b128 v[182:185], v245
	ds_read_b128 v[186:189], v245 offset:1024
	ds_read_b128 v[198:201], v245 offset:2048
	ds_read_b128 v[202:205], v245 offset:3072
	s_add_u32 s6, s80, 0x40000
	s_addc_u32 s7, s81, 0
	s_mov_b32 m0, s45
	ds_read_b128 v[206:209], v155 offset:32768
	ds_read_b128 v[210:213], v155 offset:33792
	ds_read_b128 v[214:217], v155 offset:34816
	ds_read_b128 v[218:221], v155 offset:35840
	ds_read_b128 v[222:225], v155 offset:36864
	ds_read_b128 v[226:229], v155 offset:37888
	ds_read_b128 v[230:233], v155 offset:38912
	ds_read_b128 v[234:237], v155 offset:39936
	global_load_lds_dwordx4 v128, s[6:7]
	s_mov_b32 m0, s67
	s_nop 0
	global_load_lds_dwordx4 v132, s[6:7]
	s_waitcnt vmcnt(8)
	s_waitcnt lgkmcnt(0)
	s_barrier
	s_waitcnt lgkmcnt(0)
	v_mfma_f32_16x16x32_bf16 v[124:127], v[144:147], v[206:209], v[124:127]
	v_mfma_f32_16x16x32_bf16 v[120:123], v[174:177], v[206:209], v[120:123]
	v_mfma_f32_16x16x32_bf16 v[108:111], v[144:147], v[214:217], v[108:111]
	v_mfma_f32_16x16x32_bf16 v[104:107], v[174:177], v[214:217], v[104:107]
	v_mfma_f32_16x16x32_bf16 v[92:95], v[144:147], v[222:225], v[92:95]
	v_mfma_f32_16x16x32_bf16 v[88:91], v[174:177], v[222:225], v[88:91]
	v_mfma_f32_16x16x32_bf16 v[76:79], v[144:147], v[230:233], v[76:79]
	v_mfma_f32_16x16x32_bf16 v[72:75], v[174:177], v[230:233], v[72:75]
	v_mfma_f32_16x16x32_bf16 v[124:127], v[170:173], v[210:213], v[124:127]
	v_mfma_f32_16x16x32_bf16 v[120:123], v[178:181], v[210:213], v[120:123]
	v_mfma_f32_16x16x32_bf16 v[108:111], v[170:173], v[218:221], v[108:111]
	v_mfma_f32_16x16x32_bf16 v[104:107], v[178:181], v[218:221], v[104:107]
	v_mfma_f32_16x16x32_bf16 v[92:95], v[170:173], v[226:229], v[92:95]
	v_mfma_f32_16x16x32_bf16 v[88:91], v[178:181], v[226:229], v[88:91]
	v_mfma_f32_16x16x32_bf16 v[76:79], v[170:173], v[234:237], v[76:79]
	v_mfma_f32_16x16x32_bf16 v[72:75], v[178:181], v[234:237], v[72:75]
	v_mfma_f32_16x16x32_bf16 v[116:119], v[182:185], v[206:209], v[116:119]
	v_mfma_f32_16x16x32_bf16 v[112:115], v[198:201], v[206:209], v[112:115]
	v_mfma_f32_16x16x32_bf16 v[100:103], v[182:185], v[214:217], v[100:103]
	v_mfma_f32_16x16x32_bf16 v[96:99], v[198:201], v[214:217], v[96:99]
	v_mfma_f32_16x16x32_bf16 v[84:87], v[182:185], v[222:225], v[84:87]
	v_mfma_f32_16x16x32_bf16 v[80:83], v[198:201], v[222:225], v[80:83]
	v_mfma_f32_16x16x32_bf16 v[68:71], v[182:185], v[230:233], v[68:71]
	v_mfma_f32_16x16x32_bf16 v[64:67], v[198:201], v[230:233], v[64:67]
	v_mfma_f32_16x16x32_bf16 v[116:119], v[186:189], v[210:213], v[116:119]
	v_mfma_f32_16x16x32_bf16 v[112:115], v[202:205], v[210:213], v[112:115]
	v_mfma_f32_16x16x32_bf16 v[100:103], v[186:189], v[218:221], v[100:103]
	v_mfma_f32_16x16x32_bf16 v[96:99], v[202:205], v[218:221], v[96:99]
	v_mfma_f32_16x16x32_bf16 v[84:87], v[186:189], v[226:229], v[84:87]
	v_mfma_f32_16x16x32_bf16 v[80:83], v[202:205], v[226:229], v[80:83]
	v_mfma_f32_16x16x32_bf16 v[68:71], v[186:189], v[234:237], v[68:71]
	v_mfma_f32_16x16x32_bf16 v[64:67], v[202:205], v[234:237], v[64:67]
	s_barrier
	s_add_i32 s6, s73, s42
	s_add_u32 s98, s78, 0x80
	s_addc_u32 s99, s79, 0
	s_add_u32 s100, s80, 0x80
	s_addc_u32 s101, s81, 0
	s_mov_b32 m0, s6
	ds_read_b128 v[206:209], v155 offset:49152
	ds_read_b128 v[210:213], v155 offset:50176
	ds_read_b128 v[214:217], v155 offset:51200
	ds_read_b128 v[218:221], v155 offset:52224
	ds_read_b128 v[222:225], v155 offset:53248
	ds_read_b128 v[226:229], v155 offset:54272
	ds_read_b128 v[230:233], v155 offset:55296
	ds_read_b128 v[234:237], v155 offset:56320
	global_load_lds_dwordx4 v130, s[98:99]
	s_add_i32 m0, s6, 0x2000
	s_add_u32 s6, s78, 0x40080
	s_addc_u32 s7, s79, 0
	s_add_i32 s73, s82, s42
	global_load_lds_dwordx4 v134, s[98:99]
	s_mov_b32 m0, s73
	s_nop 0
	global_load_lds_dwordx4 v130, s[6:7]
	s_add_i32 m0, s73, 0x2000
	s_nop 0
	global_load_lds_dwordx4 v134, s[6:7]
	s_mov_b32 m0, s4
	s_nop 0
	global_load_lds_dwordx4 v128, s[100:101]
	s_mov_b32 m0, s77
	s_nop 0
	global_load_lds_dwordx4 v132, s[100:101]
	s_waitcnt vmcnt(8)
	s_waitcnt lgkmcnt(0)
	s_barrier
	s_waitcnt lgkmcnt(0)
	v_mfma_f32_16x16x32_bf16 v[60:63], v[144:147], v[206:209], v[60:63]
	v_mfma_f32_16x16x32_bf16 v[56:59], v[174:177], v[206:209], v[56:59]
	v_mfma_f32_16x16x32_bf16 v[44:47], v[144:147], v[214:217], v[44:47]
	v_mfma_f32_16x16x32_bf16 v[40:43], v[174:177], v[214:217], v[40:43]
	v_mfma_f32_16x16x32_bf16 v[28:31], v[144:147], v[222:225], v[28:31]
	v_mfma_f32_16x16x32_bf16 v[24:27], v[174:177], v[222:225], v[24:27]
	v_mfma_f32_16x16x32_bf16 v[12:15], v[144:147], v[230:233], v[12:15]
	v_mfma_f32_16x16x32_bf16 v[8:11], v[174:177], v[230:233], v[8:11]
	v_mfma_f32_16x16x32_bf16 v[60:63], v[170:173], v[210:213], v[60:63]
	v_mfma_f32_16x16x32_bf16 v[56:59], v[178:181], v[210:213], v[56:59]
	v_mfma_f32_16x16x32_bf16 v[44:47], v[170:173], v[218:221], v[44:47]
	v_mfma_f32_16x16x32_bf16 v[40:43], v[178:181], v[218:221], v[40:43]
	v_mfma_f32_16x16x32_bf16 v[28:31], v[170:173], v[226:229], v[28:31]
	v_mfma_f32_16x16x32_bf16 v[24:27], v[178:181], v[226:229], v[24:27]
	v_mfma_f32_16x16x32_bf16 v[12:15], v[170:173], v[234:237], v[12:15]
	v_mfma_f32_16x16x32_bf16 v[8:11], v[178:181], v[234:237], v[8:11]
	v_mfma_f32_16x16x32_bf16 v[52:55], v[182:185], v[206:209], v[52:55]
	v_mfma_f32_16x16x32_bf16 v[48:51], v[198:201], v[206:209], v[48:51]
	v_mfma_f32_16x16x32_bf16 v[36:39], v[182:185], v[214:217], v[36:39]
	v_mfma_f32_16x16x32_bf16 v[32:35], v[198:201], v[214:217], v[32:35]
	v_mfma_f32_16x16x32_bf16 v[20:23], v[182:185], v[222:225], v[20:23]
	v_mfma_f32_16x16x32_bf16 v[16:19], v[198:201], v[222:225], v[16:19]
	v_mfma_f32_16x16x32_bf16 v[4:7], v[182:185], v[230:233], v[4:7]
	v_mfma_f32_16x16x32_bf16 v[0:3], v[198:201], v[230:233], v[0:3]
	v_mfma_f32_16x16x32_bf16 v[52:55], v[186:189], v[210:213], v[52:55]
	v_mfma_f32_16x16x32_bf16 v[48:51], v[202:205], v[210:213], v[48:51]
	v_mfma_f32_16x16x32_bf16 v[36:39], v[186:189], v[218:221], v[36:39]
	v_mfma_f32_16x16x32_bf16 v[32:35], v[202:205], v[218:221], v[32:35]
	v_mfma_f32_16x16x32_bf16 v[20:23], v[186:189], v[226:229], v[20:23]
	v_mfma_f32_16x16x32_bf16 v[16:19], v[202:205], v[226:229], v[16:19]
	v_mfma_f32_16x16x32_bf16 v[4:7], v[186:189], v[234:237], v[4:7]
	v_mfma_f32_16x16x32_bf16 v[0:3], v[202:205], v[234:237], v[0:3]
	s_barrier
	s_add_i32 s72, s72, 2
	s_add_u32 s60, s60, 0x100
	s_addc_u32 s61, s61, 0
	s_add_u32 s69, s69, 0x100
	s_addc_u32 s33, s33, 0
	s_cmp_gt_u32 s72, 13
	s_cbranch_scc0 .LBB0_1698
	s_and_b64 vcc, exec, s[50:51]
	s_cbranch_vccz .LBB0_1701
	s_barrier

; #define PG8_STAGE(bufoff, gbase, voff) do { _Pragma("unroll") for (int _i = 0; _i < 2; ++_i) \
;         __builtin_amdgcn_global_load_lds((const unsigned*)((const char*)(gbase) + (voff)[_i]), (PG8_LAS unsigned*)(lds + (bufoff) + ldsw + _i * 8192), 16, 0, 0); } while (0)
; #define PG8_LDA(dst, b, h) do { _Pragma("unroll") for (int m = 0; m < 4; ++m) _Pragma("unroll") for (int k = 0; k < 2; ++k) dst[m][k] = *(const PG8_LAS bf16x8*)(lds + PG8_SA(b, h) + aoff + m * 2048 + k * 1024); } while (0)
; #define PG8_LDB(dst, b, h) do { _Pragma("unroll") for (int n = 0; n < 2; ++n) _Pragma("unroll") for (int k = 0; k < 2; ++k) dst[n][k] = *(const PG8_LAS bf16x8*)(lds + PG8_SB(b, h) + boff + n * 2048 + k * 1024); } while (0)
; #define PG8_MMA(ai, bj, At, Bt) do { __builtin_amdgcn_s_setprio(1); _Pragma("unroll") for (int m = 0; m < 4; ++m) _Pragma("unroll") for (int n = 0; n < 2; ++n) _Pragma("unroll") for (int k = 0; k < 2; ++k) \
;         acc[ai][bj][m][n] = __builtin_amdgcn_mfma_f32_16x16x32_bf16(Bt[n][k], At[m][k], acc[ai][bj][m][n], 0, 0, 0); __builtin_amdgcn_s_setprio(0); } while (0)
; #define PG8_WAIT_V(n) asm volatile("s_waitcnt vmcnt(" #n ")" ::: "memory")
; template <class Epi, class Sched, bool ALIGN_EPI = false, bool SP2 = false>
; __device__ __forceinline__ void gemm_phase(PG8_LAS unsigned char* lds, const Gemm g, const Sched& S, const Epi& E) {
;     ...
;         for (int t = 0; t < nt; t += 2) {
;             const bool last = (t == nt - 2);
;             const char* a1 = cA + (size_t)(t + 1) * kstep;
;             const char* a2 = last ? nA : cA + (size_t)(t + 2) * kstep; const char* b2 = last ? nB : cB + (size_t)(t + 2) * kstep;
;             const char* a3 = a2 + kstep; const char* b3 = b2 + kstep;
;             if (last && has_next) S.a_ready(nxt);
;             if constexpr (SP2) {
;             PG8_LDB(B0, 0, 0); PG8_LDB(B1, 0, 1); PG8_SCHED; PG8_LDA(At, 0, 0); PG8_STAGE(PG8_SA(1, 1), a1 + hstep, voffA);
;             PG8_WAIT_V(8); PG8_WAIT_L(0); PG8_BAR; PG8_MMA(0, 0, At, B0); PG8_MMA(0, 1, At, B1); PG8_BAR; PG8_SCHED;
;     ...
; #pragma unroll
;         for (int a = 0; a < 2; ++a)
; #pragma unroll
;             for (int b = 0; b < 2; ++b)
; #pragma unroll
;                 for (int m = 0; m < 4; ++m)
; #pragma unroll
;                     for (int n = 0; n < 2; ++n) acc[a][b][m][n] = (f32x4){0.f, 0.f, 0.f, 0.f};
;         cur = nxt; cA = nA; cB = nB; ++ui;
.LBB0_1821:
	s_ashr_i32 s39, s38, 31
	s_lshl_b64 s[6:7], s[38:39], 19
	s_add_u32 s40, s22, s6
	s_addc_u32 s41, s23, s7
	s_and_b64 s[6:7], s[44:45], exec
	s_cselect_b32 s39, s41, s51
	s_cselect_b32 s69, s40, s50
	s_ashr_i32 s37, s36, 31
	s_lshl_b64 s[6:7], s[36:37], 19
	s_add_u32 s46, s4, s6
	s_addc_u32 s47, s5, s7
	s_and_b64 s[6:7], s[44:45], exec
	s_cselect_b32 s37, s47, s53
	s_cselect_b32 s74, s46, s52
	s_add_u32 s50, s50, 0x40080
	s_addc_u32 s51, s51, 0
	s_add_u32 s75, s52, 0x100
	v_mov_b32_e32 v0, 0
	s_addc_u32 s33, s53, 0
	s_mov_b32 s72, -2
	v_mov_b32_e32 v1, v0
	v_mov_b32_e32 v2, v0
	v_mov_b32_e32 v3, v0
	v_mov_b32_e32 v8, v0
	v_mov_b32_e32 v9, v0
	v_mov_b32_e32 v10, v0
	v_mov_b32_e32 v11, v0
	v_mov_b32_e32 v16, v0
	v_mov_b32_e32 v17, v0
	v_mov_b32_e32 v18, v0
	v_mov_b32_e32 v19, v0
	v_mov_b32_e32 v24, v0
	v_mov_b32_e32 v25, v0
	v_mov_b32_e32 v26, v0
	v_mov_b32_e32 v27, v0
	v_mov_b32_e32 v32, v0
	v_mov_b32_e32 v33, v0
	v_mov_b32_e32 v34, v0
	v_mov_b32_e32 v35, v0
	v_mov_b32_e32 v40, v0
	v_mov_b32_e32 v41, v0
	v_mov_b32_e32 v42, v0
	v_mov_b32_e32 v43, v0
	v_mov_b32_e32 v48, v0
	v_mov_b32_e32 v49, v0
	v_mov_b32_e32 v50, v0
	v_mov_b32_e32 v51, v0
	v_mov_b32_e32 v56, v0
	v_mov_b32_e32 v57, v0
	v_mov_b32_e32 v58, v0
	v_mov_b32_e32 v59, v0
	v_mov_b32_e32 v4, v0
	v_mov_b32_e32 v5, v0
	v_mov_b32_e32 v6, v0
	v_mov_b32_e32 v7, v0
	v_mov_b32_e32 v12, v0
	v_mov_b32_e32 v13, v0
	v_mov_b32_e32 v14, v0
	v_mov_b32_e32 v15, v0
	v_mov_b32_e32 v20, v0
	v_mov_b32_e32 v21, v0
	v_mov_b32_e32 v22, v0
	v_mov_b32_e32 v23, v0
	v_mov_b32_e32 v28, v0
	v_mov_b32_e32 v29, v0
	v_mov_b32_e32 v30, v0
	v_mov_b32_e32 v31, v0
	v_mov_b32_e32 v36, v0
	v_mov_b32_e32 v37, v0
	v_mov_b32_e32 v38, v0
	v_mov_b32_e32 v39, v0
	v_mov_b32_e32 v44, v0
	v_mov_b32_e32 v45, v0
	v_mov_b32_e32 v46, v0
	v_mov_b32_e32 v47, v0
	v_mov_b32_e32 v52, v0
	v_mov_b32_e32 v53, v0
	v_mov_b32_e32 v54, v0
	v_mov_b32_e32 v55, v0
	v_mov_b32_e32 v60, v0
	v_mov_b32_e32 v61, v0
	v_mov_b32_e32 v62, v0
	v_mov_b32_e32 v63, v0
	v_mov_b32_e32 v64, v0
	v_mov_b32_e32 v65, v0
	v_mov_b32_e32 v66, v0
	v_mov_b32_e32 v67, v0
	v_mov_b32_e32 v72, v0
	v_mov_b32_e32 v73, v0
	v_mov_b32_e32 v74, v0
	v_mov_b32_e32 v75, v0
	v_mov_b32_e32 v80, v0
	v_mov_b32_e32 v81, v0
	v_mov_b32_e32 v82, v0
	v_mov_b32_e32 v83, v0
	v_mov_b32_e32 v88, v0
	v_mov_b32_e32 v89, v0
	v_mov_b32_e32 v90, v0
	v_mov_b32_e32 v91, v0
	v_mov_b32_e32 v96, v0
	v_mov_b32_e32 v97, v0
	v_mov_b32_e32 v98, v0
	v_mov_b32_e32 v99, v0
	v_mov_b32_e32 v104, v0
	v_mov_b32_e32 v105, v0
	v_mov_b32_e32 v106, v0
	v_mov_b32_e32 v107, v0
	v_mov_b32_e32 v112, v0
	v_mov_b32_e32 v113, v0
	v_mov_b32_e32 v114, v0
	v_mov_b32_e32 v115, v0
	v_mov_b32_e32 v120, v0
	v_mov_b32_e32 v121, v0
	v_mov_b32_e32 v122, v0
	v_mov_b32_e32 v123, v0
	v_mov_b32_e32 v68, v0
	v_mov_b32_e32 v69, v0
	v_mov_b32_e32 v70, v0
	v_mov_b32_e32 v71, v0
	v_mov_b32_e32 v76, v0
	v_mov_b32_e32 v77, v0
	v_mov_b32_e32 v78, v0
	v_mov_b32_e32 v79, v0
	v_mov_b32_e32 v84, v0
	v_mov_b32_e32 v85, v0
	v_mov_b32_e32 v86, v0
	v_mov_b32_e32 v87, v0
	v_mov_b32_e32 v92, v0
	v_mov_b32_e32 v93, v0
	v_mov_b32_e32 v94, v0
	v_mov_b32_e32 v95, v0
	v_mov_b32_e32 v100, v0
	v_mov_b32_e32 v101, v0
	v_mov_b32_e32 v102, v0
	v_mov_b32_e32 v103, v0
	v_mov_b32_e32 v108, v0
	v_mov_b32_e32 v109, v0
	v_mov_b32_e32 v110, v0
	v_mov_b32_e32 v111, v0
	v_mov_b32_e32 v116, v0
	v_mov_b32_e32 v117, v0
	v_mov_b32_e32 v118, v0
	v_mov_b32_e32 v119, v0
	v_mov_b32_e32 v124, v0
	v_mov_b32_e32 v125, v0
	v_mov_b32_e32 v126, v0
	v_mov_b32_e32 v127, v0
	v_add_u32_e32 v244, 0x18000, v151
	v_add_u32_e32 v245, 0x1c000, v151
.LBB0_1822:
	ds_read_b128 v[144:147], v154
	ds_read_b128 v[168:171], v154 offset:1024
	ds_read_b128 v[172:175], v154 offset:2048
	ds_read_b128 v[176:179], v154 offset:3072
	ds_read_b128 v[180:183], v155
	ds_read_b128 v[184:187], v155 offset:1024
	ds_read_b128 v[188:191], v155 offset:2048
	ds_read_b128 v[198:201], v155 offset:3072
	s_add_u32 s6, s50, 0xfffc0080
	s_addc_u32 s7, s51, -1
	s_cmp_eq_u32 s72, 12
	s_cselect_b32 s55, s39, s7
	s_cselect_b32 s54, s69, s6
	s_cselect_b32 s53, s37, s33
	s_cselect_b32 s52, s74, s75
	s_add_i32 m0, s27, 0xc000
	ds_read_b128 v[202:205], v156
	ds_read_b128 v[206:209], v156 offset:1024
	ds_read_b128 v[210:213], v156 offset:2048
	ds_read_b128 v[214:217], v156 offset:3072
	ds_read_b128 v[218:221], v156 offset:4096
	ds_read_b128 v[222:225], v156 offset:5120
	ds_read_b128 v[226:229], v156 offset:6144
	ds_read_b128 v[230:233], v156 offset:7168
	global_load_lds_dwordx4 v136, s[50:51]
	s_add_i32 m0, s27, 0xe000
	s_nop 0
	global_load_lds_dwordx4 v138, s[50:51]
	s_waitcnt vmcnt(8)
	s_waitcnt lgkmcnt(0)
	s_barrier
; #define PG8_STAGE(bufoff, gbase, voff) do { _Pragma("unroll") for (int _i = 0; _i < 2; ++_i) \
;         __builtin_amdgcn_global_load_lds((const unsigned*)((const char*)(gbase) + (voff)[_i]), (PG8_LAS unsigned*)(lds + (bufoff) + ldsw + _i * 8192), 16, 0, 0); } while (0)
; #define PG8_LDA(dst, b, h) do { _Pragma("unroll") for (int m = 0; m < 4; ++m) _Pragma("unroll") for (int k = 0; k < 2; ++k) dst[m][k] = *(const PG8_LAS bf16x8*)(lds + PG8_SA(b, h) + aoff + m * 2048 + k * 1024); } while (0)
; #define PG8_MMA(ai, bj, At, Bt) do { __builtin_amdgcn_s_setprio(1); _Pragma("unroll") for (int m = 0; m < 4; ++m) _Pragma("unroll") for (int n = 0; n < 2; ++n) _Pragma("unroll") for (int k = 0; k < 2; ++k) \
;         acc[ai][bj][m][n] = __builtin_amdgcn_mfma_f32_16x16x32_bf16(Bt[n][k], At[m][k], acc[ai][bj][m][n], 0, 0, 0); __builtin_amdgcn_s_setprio(0); } while (0)
; #define PG8_WAIT_V(n) asm volatile("s_waitcnt vmcnt(" #n ")" ::: "memory")
; #define PG8_WAIT_L(n) asm volatile("s_waitcnt lgkmcnt(" #n ")" ::: "memory")
; #define PG8_BAR __builtin_amdgcn_s_barrier()
; #define PG8_SCHED __builtin_amdgcn_sched_barrier(0)
; template <class Epi, class Sched, bool ALIGN_EPI = false, bool SP2 = false>
; __device__ __forceinline__ void gemm_phase(PG8_LAS unsigned char* lds, const Gemm g, const Sched& S, const Epi& E) {
;     ...
;             PG8_WAIT_V(8); PG8_WAIT_L(0); PG8_BAR; PG8_MMA(0, 0, At, B0); PG8_MMA(0, 1, At, B1); PG8_BAR; PG8_SCHED;
;             PG8_LDA(At, 0, 1); PG8_STAGE(PG8_SB(0, 0), b2, voffB); PG8_STAGE(PG8_SB(0, 1), b2 + hstep, voffB); PG8_STAGE(PG8_SA(0, 0), a2, voffA);
;             PG8_WAIT_V(8); PG8_WAIT_L(0); PG8_BAR; PG8_MMA(1, 0, At, B0); PG8_MMA(1, 1, At, B1); PG8_BAR; PG8_SCHED;
	s_waitcnt lgkmcnt(0)
	v_mfma_f32_16x16x32_bf16 v[124:127], v[144:147], v[202:205], v[124:127]
	v_mfma_f32_16x16x32_bf16 v[116:119], v[172:175], v[202:205], v[116:119]
	v_mfma_f32_16x16x32_bf16 v[108:111], v[144:147], v[210:213], v[108:111]
	v_mfma_f32_16x16x32_bf16 v[100:103], v[172:175], v[210:213], v[100:103]
	v_mfma_f32_16x16x32_bf16 v[92:95], v[144:147], v[218:221], v[92:95]
	v_mfma_f32_16x16x32_bf16 v[84:87], v[172:175], v[218:221], v[84:87]
	v_mfma_f32_16x16x32_bf16 v[76:79], v[144:147], v[226:229], v[76:79]
	v_mfma_f32_16x16x32_bf16 v[68:71], v[172:175], v[226:229], v[68:71]
	v_mfma_f32_16x16x32_bf16 v[124:127], v[168:171], v[206:209], v[124:127]
	v_mfma_f32_16x16x32_bf16 v[116:119], v[176:179], v[206:209], v[116:119]
	v_mfma_f32_16x16x32_bf16 v[108:111], v[168:171], v[214:217], v[108:111]
	v_mfma_f32_16x16x32_bf16 v[100:103], v[176:179], v[214:217], v[100:103]
	v_mfma_f32_16x16x32_bf16 v[92:95], v[168:171], v[222:225], v[92:95]
	v_mfma_f32_16x16x32_bf16 v[84:87], v[176:179], v[222:225], v[84:87]
	v_mfma_f32_16x16x32_bf16 v[76:79], v[168:171], v[230:233], v[76:79]
	v_mfma_f32_16x16x32_bf16 v[68:71], v[176:179], v[230:233], v[68:71]
	v_mfma_f32_16x16x32_bf16 v[120:123], v[180:183], v[202:205], v[120:123]
	v_mfma_f32_16x16x32_bf16 v[112:115], v[188:191], v[202:205], v[112:115]
	v_mfma_f32_16x16x32_bf16 v[104:107], v[180:183], v[210:213], v[104:107]
	v_mfma_f32_16x16x32_bf16 v[96:99], v[188:191], v[210:213], v[96:99]
	v_mfma_f32_16x16x32_bf16 v[88:91], v[180:183], v[218:221], v[88:91]
	v_mfma_f32_16x16x32_bf16 v[80:83], v[188:191], v[218:221], v[80:83]
	v_mfma_f32_16x16x32_bf16 v[72:75], v[180:183], v[226:229], v[72:75]
	v_mfma_f32_16x16x32_bf16 v[64:67], v[188:191], v[226:229], v[64:67]
	v_mfma_f32_16x16x32_bf16 v[120:123], v[184:187], v[206:209], v[120:123]
	v_mfma_f32_16x16x32_bf16 v[112:115], v[198:201], v[206:209], v[112:115]
	v_mfma_f32_16x16x32_bf16 v[104:107], v[184:187], v[214:217], v[104:107]
	v_mfma_f32_16x16x32_bf16 v[96:99], v[198:201], v[214:217], v[96:99]
	v_mfma_f32_16x16x32_bf16 v[88:91], v[184:187], v[222:225], v[88:91]
	v_mfma_f32_16x16x32_bf16 v[80:83], v[198:201], v[222:225], v[80:83]
	v_mfma_f32_16x16x32_bf16 v[72:75], v[184:187], v[230:233], v[72:75]
	v_mfma_f32_16x16x32_bf16 v[64:67], v[198:201], v[230:233], v[64:67]
	s_barrier
	s_add_i32 s6, s59, s26
	s_mov_b32 m0, s6
	ds_read_b128 v[202:205], v156 offset:16384
	ds_read_b128 v[206:209], v156 offset:17408
	ds_read_b128 v[210:213], v156 offset:18432
	ds_read_b128 v[214:217], v156 offset:19456
	ds_read_b128 v[218:221], v156 offset:20480
	ds_read_b128 v[222:225], v156 offset:21504
	ds_read_b128 v[226:229], v156 offset:22528
	ds_read_b128 v[230:233], v156 offset:23552
	global_load_lds_dwordx4 v132, s[52:53]
	s_add_i32 m0, s6, 0x2000
	s_add_u32 s6, s52, 0x40000
	s_addc_u32 s7, s53, 0
	s_add_i32 s73, s60, s26
	global_load_lds_dwordx4 v128, s[52:53]
	s_mov_b32 m0, s73
	s_nop 0
	global_load_lds_dwordx4 v132, s[6:7]
	s_add_i32 m0, s73, 0x2000
	s_nop 0
	global_load_lds_dwordx4 v128, s[6:7]
	s_mov_b32 m0, s27
	s_nop 0
	global_load_lds_dwordx4 v134, s[54:55]
	s_mov_b32 m0, s42
	s_nop 0
	global_load_lds_dwordx4 v130, s[54:55]
	s_waitcnt vmcnt(8)
	s_waitcnt lgkmcnt(0)
	s_barrier
	s_waitcnt lgkmcnt(0)
	v_mfma_f32_16x16x32_bf16 v[60:63], v[144:147], v[202:205], v[60:63]
	v_mfma_f32_16x16x32_bf16 v[52:55], v[172:175], v[202:205], v[52:55]
	v_mfma_f32_16x16x32_bf16 v[44:47], v[144:147], v[210:213], v[44:47]
	v_mfma_f32_16x16x32_bf16 v[36:39], v[172:175], v[210:213], v[36:39]
	v_mfma_f32_16x16x32_bf16 v[28:31], v[144:147], v[218:221], v[28:31]
	v_mfma_f32_16x16x32_bf16 v[20:23], v[172:175], v[218:221], v[20:23]
	v_mfma_f32_16x16x32_bf16 v[12:15], v[144:147], v[226:229], v[12:15]
	v_mfma_f32_16x16x32_bf16 v[4:7], v[172:175], v[226:229], v[4:7]
	v_mfma_f32_16x16x32_bf16 v[60:63], v[168:171], v[206:209], v[60:63]
	v_mfma_f32_16x16x32_bf16 v[52:55], v[176:179], v[206:209], v[52:55]
	v_mfma_f32_16x16x32_bf16 v[44:47], v[168:171], v[214:217], v[44:47]
	v_mfma_f32_16x16x32_bf16 v[36:39], v[176:179], v[214:217], v[36:39]
	v_mfma_f32_16x16x32_bf16 v[28:31], v[168:171], v[222:225], v[28:31]
	v_mfma_f32_16x16x32_bf16 v[20:23], v[176:179], v[222:225], v[20:23]
	v_mfma_f32_16x16x32_bf16 v[12:15], v[168:171], v[230:233], v[12:15]
	v_mfma_f32_16x16x32_bf16 v[4:7], v[176:179], v[230:233], v[4:7]
	v_mfma_f32_16x16x32_bf16 v[56:59], v[180:183], v[202:205], v[56:59]
	v_mfma_f32_16x16x32_bf16 v[48:51], v[188:191], v[202:205], v[48:51]
	v_mfma_f32_16x16x32_bf16 v[40:43], v[180:183], v[210:213], v[40:43]
	v_mfma_f32_16x16x32_bf16 v[32:35], v[188:191], v[210:213], v[32:35]
	v_mfma_f32_16x16x32_bf16 v[24:27], v[180:183], v[218:221], v[24:27]
	v_mfma_f32_16x16x32_bf16 v[16:19], v[188:191], v[218:221], v[16:19]
	v_mfma_f32_16x16x32_bf16 v[8:11], v[180:183], v[226:229], v[8:11]
	v_mfma_f32_16x16x32_bf16 v[0:3], v[188:191], v[226:229], v[0:3]
	v_mfma_f32_16x16x32_bf16 v[56:59], v[184:187], v[206:209], v[56:59]
	v_mfma_f32_16x16x32_bf16 v[48:51], v[198:201], v[206:209], v[48:51]
	v_mfma_f32_16x16x32_bf16 v[40:43], v[184:187], v[214:217], v[40:43]
	v_mfma_f32_16x16x32_bf16 v[32:35], v[198:201], v[214:217], v[32:35]
	v_mfma_f32_16x16x32_bf16 v[24:27], v[184:187], v[222:225], v[24:27]
	v_mfma_f32_16x16x32_bf16 v[16:19], v[198:201], v[222:225], v[16:19]
	v_mfma_f32_16x16x32_bf16 v[8:11], v[184:187], v[230:233], v[8:11]
	v_mfma_f32_16x16x32_bf16 v[0:3], v[198:201], v[230:233], v[0:3]
	s_barrier
; #define PG8_STAGE(bufoff, gbase, voff) do { _Pragma("unroll") for (int _i = 0; _i < 2; ++_i) \
;         __builtin_amdgcn_global_load_lds((const unsigned*)((const char*)(gbase) + (voff)[_i]), (PG8_LAS unsigned*)(lds + (bufoff) + ldsw + _i * 8192), 16, 0, 0); } while (0)
; #define PG8_LDA(dst, b, h) do { _Pragma("unroll") for (int m = 0; m < 4; ++m) _Pragma("unroll") for (int k = 0; k < 2; ++k) dst[m][k] = *(const PG8_LAS bf16x8*)(lds + PG8_SA(b, h) + aoff + m * 2048 + k * 1024); } while (0)
; #define PG8_LDB(dst, b, h) do { _Pragma("unroll") for (int n = 0; n < 2; ++n) _Pragma("unroll") for (int k = 0; k < 2; ++k) dst[n][k] = *(const PG8_LAS bf16x8*)(lds + PG8_SB(b, h) + boff + n * 2048 + k * 1024); } while (0)
; #define PG8_MMA(ai, bj, At, Bt) do { __builtin_amdgcn_s_setprio(1); _Pragma("unroll") for (int m = 0; m < 4; ++m) _Pragma("unroll") for (int n = 0; n < 2; ++n) _Pragma("unroll") for (int k = 0; k < 2; ++k) \
;         acc[ai][bj][m][n] = __builtin_amdgcn_mfma_f32_16x16x32_bf16(Bt[n][k], At[m][k], acc[ai][bj][m][n], 0, 0, 0); __builtin_amdgcn_s_setprio(0); } while (0)
; #define PG8_WAIT_V(n) asm volatile("s_waitcnt vmcnt(" #n ")" ::: "memory")
; #define PG8_WAIT_L(n) asm volatile("s_waitcnt lgkmcnt(" #n ")" ::: "memory")
; #define PG8_BAR __builtin_amdgcn_s_barrier()
; #define PG8_SCHED __builtin_amdgcn_sched_barrier(0)
; template <class Epi, class Sched, bool ALIGN_EPI = false, bool SP2 = false>
; __device__ __forceinline__ void gemm_phase(PG8_LAS unsigned char* lds, const Gemm g, const Sched& S, const Epi& E) {
;     ...
;             PG8_LDB(B0, 1, 0); PG8_LDB(B1, 1, 1); PG8_SCHED; PG8_LDA(At, 1, 0); PG8_STAGE(PG8_SA(0, 1), a2 + hstep, voffA);
;             PG8_WAIT_V(8); PG8_WAIT_L(0); PG8_BAR; PG8_MMA(0, 0, At, B0); PG8_MMA(0, 1, At, B1); PG8_BAR; PG8_SCHED;
;             PG8_LDA(At, 1, 1); PG8_STAGE(PG8_SB(1, 0), b3, voffB); PG8_STAGE(PG8_SB(1, 1), b3 + hstep, voffB); PG8_STAGE(PG8_SA(1, 0), a3, voffA);
;             PG8_WAIT_V(8); PG8_WAIT_L(0); PG8_BAR; PG8_MMA(1, 0, At, B0); PG8_MMA(1, 1, At, B1); PG8_BAR; PG8_SCHED;
	s_add_i32 s73, 0, 0x18000
	s_add_i32 s76, 0, 0x1c000
	ds_read_b128 v[144:147], v244
	ds_read_b128 v[168:171], v244 offset:1024
	ds_read_b128 v[172:175], v244 offset:2048
	ds_read_b128 v[176:179], v244 offset:3072
	ds_read_b128 v[180:183], v245
	ds_read_b128 v[184:187], v245 offset:1024
	ds_read_b128 v[188:191], v245 offset:2048
	ds_read_b128 v[198:201], v245 offset:3072
	s_add_u32 s6, s54, 0x40000
	s_addc_u32 s7, s55, 0
	s_mov_b32 m0, s43
	ds_read_b128 v[202:205], v156 offset:32768
	ds_read_b128 v[206:209], v156 offset:33792
	ds_read_b128 v[210:213], v156 offset:34816
	ds_read_b128 v[214:217], v156 offset:35840
	ds_read_b128 v[218:221], v156 offset:36864
	ds_read_b128 v[222:225], v156 offset:37888
	ds_read_b128 v[226:229], v156 offset:38912
	ds_read_b128 v[230:233], v156 offset:39936
	global_load_lds_dwordx4 v134, s[6:7]
	s_mov_b32 m0, s56
	s_nop 0
	global_load_lds_dwordx4 v130, s[6:7]
	s_waitcnt vmcnt(8)
	s_waitcnt lgkmcnt(0)
	s_barrier
	s_waitcnt lgkmcnt(0)
	v_mfma_f32_16x16x32_bf16 v[124:127], v[144:147], v[202:205], v[124:127]
	v_mfma_f32_16x16x32_bf16 v[116:119], v[172:175], v[202:205], v[116:119]
	v_mfma_f32_16x16x32_bf16 v[108:111], v[144:147], v[210:213], v[108:111]
	v_mfma_f32_16x16x32_bf16 v[100:103], v[172:175], v[210:213], v[100:103]
	v_mfma_f32_16x16x32_bf16 v[92:95], v[144:147], v[218:221], v[92:95]
	v_mfma_f32_16x16x32_bf16 v[84:87], v[172:175], v[218:221], v[84:87]
	v_mfma_f32_16x16x32_bf16 v[76:79], v[144:147], v[226:229], v[76:79]
	v_mfma_f32_16x16x32_bf16 v[68:71], v[172:175], v[226:229], v[68:71]
	v_mfma_f32_16x16x32_bf16 v[124:127], v[168:171], v[206:209], v[124:127]
	v_mfma_f32_16x16x32_bf16 v[116:119], v[176:179], v[206:209], v[116:119]
	v_mfma_f32_16x16x32_bf16 v[108:111], v[168:171], v[214:217], v[108:111]
	v_mfma_f32_16x16x32_bf16 v[100:103], v[176:179], v[214:217], v[100:103]
	v_mfma_f32_16x16x32_bf16 v[92:95], v[168:171], v[222:225], v[92:95]
	v_mfma_f32_16x16x32_bf16 v[84:87], v[176:179], v[222:225], v[84:87]
	v_mfma_f32_16x16x32_bf16 v[76:79], v[168:171], v[230:233], v[76:79]
	v_mfma_f32_16x16x32_bf16 v[68:71], v[176:179], v[230:233], v[68:71]
	v_mfma_f32_16x16x32_bf16 v[120:123], v[180:183], v[202:205], v[120:123]
	v_mfma_f32_16x16x32_bf16 v[112:115], v[188:191], v[202:205], v[112:115]
	v_mfma_f32_16x16x32_bf16 v[104:107], v[180:183], v[210:213], v[104:107]
	v_mfma_f32_16x16x32_bf16 v[96:99], v[188:191], v[210:213], v[96:99]
	v_mfma_f32_16x16x32_bf16 v[88:91], v[180:183], v[218:221], v[88:91]
	v_mfma_f32_16x16x32_bf16 v[80:83], v[188:191], v[218:221], v[80:83]
	v_mfma_f32_16x16x32_bf16 v[72:75], v[180:183], v[226:229], v[72:75]
	v_mfma_f32_16x16x32_bf16 v[64:67], v[188:191], v[226:229], v[64:67]
	v_mfma_f32_16x16x32_bf16 v[120:123], v[184:187], v[206:209], v[120:123]
	v_mfma_f32_16x16x32_bf16 v[112:115], v[198:201], v[206:209], v[112:115]
	v_mfma_f32_16x16x32_bf16 v[104:107], v[184:187], v[214:217], v[104:107]
	v_mfma_f32_16x16x32_bf16 v[96:99], v[198:201], v[214:217], v[96:99]
	v_mfma_f32_16x16x32_bf16 v[88:91], v[184:187], v[222:225], v[88:91]
	v_mfma_f32_16x16x32_bf16 v[80:83], v[198:201], v[222:225], v[80:83]
	v_mfma_f32_16x16x32_bf16 v[72:75], v[184:187], v[230:233], v[72:75]
	v_mfma_f32_16x16x32_bf16 v[64:67], v[198:201], v[230:233], v[64:67]
	s_barrier
	s_add_i32 s6, s73, s26
	s_add_u32 s98, s52, 0x80
	s_addc_u32 s99, s53, 0
	s_add_u32 s100, s54, 0x80
	s_addc_u32 s101, s55, 0
	s_mov_b32 m0, s6
	ds_read_b128 v[202:205], v156 offset:49152
	ds_read_b128 v[206:209], v156 offset:50176
	ds_read_b128 v[210:213], v156 offset:51200
	ds_read_b128 v[214:217], v156 offset:52224
	ds_read_b128 v[218:221], v156 offset:53248
	ds_read_b128 v[222:225], v156 offset:54272
	ds_read_b128 v[226:229], v156 offset:55296
	ds_read_b128 v[230:233], v156 offset:56320
	global_load_lds_dwordx4 v132, s[98:99]
	s_add_i32 m0, s6, 0x2000
	s_add_u32 s6, s52, 0x40080
	s_addc_u32 s7, s53, 0
	s_add_i32 s52, s76, s26
	global_load_lds_dwordx4 v128, s[98:99]
	s_mov_b32 m0, s52
	s_nop 0
	global_load_lds_dwordx4 v132, s[6:7]
	s_add_i32 m0, s52, 0x2000
	s_nop 0
	global_load_lds_dwordx4 v128, s[6:7]
	s_mov_b32 m0, s57
	s_nop 0
	global_load_lds_dwordx4 v134, s[100:101]
	s_mov_b32 m0, s58
	s_nop 0
	global_load_lds_dwordx4 v130, s[100:101]
	s_waitcnt vmcnt(8)
	s_waitcnt lgkmcnt(0)
	s_barrier
	s_waitcnt lgkmcnt(0)
	v_mfma_f32_16x16x32_bf16 v[60:63], v[144:147], v[202:205], v[60:63]
	v_mfma_f32_16x16x32_bf16 v[52:55], v[172:175], v[202:205], v[52:55]
	v_mfma_f32_16x16x32_bf16 v[44:47], v[144:147], v[210:213], v[44:47]
	v_mfma_f32_16x16x32_bf16 v[36:39], v[172:175], v[210:213], v[36:39]
	v_mfma_f32_16x16x32_bf16 v[28:31], v[144:147], v[218:221], v[28:31]
	v_mfma_f32_16x16x32_bf16 v[20:23], v[172:175], v[218:221], v[20:23]
	v_mfma_f32_16x16x32_bf16 v[12:15], v[144:147], v[226:229], v[12:15]
	v_mfma_f32_16x16x32_bf16 v[4:7], v[172:175], v[226:229], v[4:7]
	v_mfma_f32_16x16x32_bf16 v[60:63], v[168:171], v[206:209], v[60:63]
	v_mfma_f32_16x16x32_bf16 v[52:55], v[176:179], v[206:209], v[52:55]
	v_mfma_f32_16x16x32_bf16 v[44:47], v[168:171], v[214:217], v[44:47]
	v_mfma_f32_16x16x32_bf16 v[36:39], v[176:179], v[214:217], v[36:39]
	v_mfma_f32_16x16x32_bf16 v[28:31], v[168:171], v[222:225], v[28:31]
	v_mfma_f32_16x16x32_bf16 v[20:23], v[176:179], v[222:225], v[20:23]
	v_mfma_f32_16x16x32_bf16 v[12:15], v[168:171], v[230:233], v[12:15]
	v_mfma_f32_16x16x32_bf16 v[4:7], v[176:179], v[230:233], v[4:7]
	v_mfma_f32_16x16x32_bf16 v[56:59], v[180:183], v[202:205], v[56:59]
	v_mfma_f32_16x16x32_bf16 v[48:51], v[188:191], v[202:205], v[48:51]
	v_mfma_f32_16x16x32_bf16 v[40:43], v[180:183], v[210:213], v[40:43]
	v_mfma_f32_16x16x32_bf16 v[32:35], v[188:191], v[210:213], v[32:35]
	v_mfma_f32_16x16x32_bf16 v[24:27], v[180:183], v[218:221], v[24:27]
	v_mfma_f32_16x16x32_bf16 v[16:19], v[188:191], v[218:221], v[16:19]
	v_mfma_f32_16x16x32_bf16 v[8:11], v[180:183], v[226:229], v[8:11]
	v_mfma_f32_16x16x32_bf16 v[0:3], v[188:191], v[226:229], v[0:3]
	v_mfma_f32_16x16x32_bf16 v[56:59], v[184:187], v[206:209], v[56:59]
	v_mfma_f32_16x16x32_bf16 v[48:51], v[198:201], v[206:209], v[48:51]
	v_mfma_f32_16x16x32_bf16 v[40:43], v[184:187], v[214:217], v[40:43]
	v_mfma_f32_16x16x32_bf16 v[32:35], v[198:201], v[214:217], v[32:35]
	v_mfma_f32_16x16x32_bf16 v[24:27], v[184:187], v[222:225], v[24:27]
	v_mfma_f32_16x16x32_bf16 v[16:19], v[198:201], v[222:225], v[16:19]
	v_mfma_f32_16x16x32_bf16 v[8:11], v[184:187], v[230:233], v[8:11]
	v_mfma_f32_16x16x32_bf16 v[0:3], v[198:201], v[230:233], v[0:3]
	s_barrier
	s_add_i32 s72, s72, 2
	s_add_u32 s50, s50, 0x100
	s_addc_u32 s51, s51, 0
	s_add_u32 s75, s75, 0x100
	s_addc_u32 s33, s33, 0
	s_cmp_gt_u32 s72, 13
	s_cbranch_scc0 .LBB0_1822
	v_readlane_b32 s74, v243, 57
	s_and_b64 vcc, exec, s[34:35]
	v_readlane_b32 s75, v243, 58
	s_cbranch_vccz .LBB0_1825
	s_barrier

; #define PG8_STAGE(bufoff, gbase, voff) do { _Pragma("unroll") for (int _i = 0; _i < 2; ++_i) \
;         __builtin_amdgcn_global_load_lds((const unsigned*)((const char*)(gbase) + (voff)[_i]), (PG8_LAS unsigned*)(lds + (bufoff) + ldsw + _i * 8192), 16, 0, 0); } while (0)
; #define PG8_LDA(dst, b, h) do { _Pragma("unroll") for (int m = 0; m < 4; ++m) _Pragma("unroll") for (int k = 0; k < 2; ++k) dst[m][k] = *(const PG8_LAS bf16x8*)(lds + PG8_SA(b, h) + aoff + m * 2048 + k * 1024); } while (0)
; #define PG8_LDB(dst, b, h) do { _Pragma("unroll") for (int n = 0; n < 2; ++n) _Pragma("unroll") for (int k = 0; k < 2; ++k) dst[n][k] = *(const PG8_LAS bf16x8*)(lds + PG8_SB(b, h) + boff + n * 2048 + k * 1024); } while (0)
; #define PG8_MMA(ai, bj, At, Bt) do { __builtin_amdgcn_s_setprio(1); _Pragma("unroll") for (int m = 0; m < 4; ++m) _Pragma("unroll") for (int n = 0; n < 2; ++n) _Pragma("unroll") for (int k = 0; k < 2; ++k) \
;         acc[ai][bj][m][n] = __builtin_amdgcn_mfma_f32_16x16x32_bf16(Bt[n][k], At[m][k], acc[ai][bj][m][n], 0, 0, 0); __builtin_amdgcn_s_setprio(0); } while (0)
; #define PG8_WAIT_V(n) asm volatile("s_waitcnt vmcnt(" #n ")" ::: "memory")
; template <class Epi, class Sched, bool ALIGN_EPI = false, bool SP2 = false>
; __device__ __forceinline__ void gemm_phase(PG8_LAS unsigned char* lds, const Gemm g, const Sched& S, const Epi& E) {
;     ...
;         for (int t = 0; t < nt; t += 2) {
;             const bool last = (t == nt - 2);
;             const char* a1 = cA + (size_t)(t + 1) * kstep;
;             const char* a2 = last ? nA : cA + (size_t)(t + 2) * kstep; const char* b2 = last ? nB : cB + (size_t)(t + 2) * kstep;
;             const char* a3 = a2 + kstep; const char* b3 = b2 + kstep;
;             if (last && has_next) S.a_ready(nxt);
;             if constexpr (SP2) {
;             PG8_LDB(B0, 0, 0); PG8_LDB(B1, 0, 1); PG8_SCHED; PG8_LDA(At, 0, 0); PG8_STAGE(PG8_SA(1, 1), a1 + hstep, voffA);
;             PG8_WAIT_V(8); PG8_WAIT_L(0); PG8_BAR; PG8_MMA(0, 0, At, B0); PG8_MMA(0, 1, At, B1); PG8_BAR; PG8_SCHED;
;     ...
; #pragma unroll
;         for (int a = 0; a < 2; ++a)
; #pragma unroll
;             for (int b = 0; b < 2; ++b)
; #pragma unroll
;                 for (int m = 0; m < 4; ++m)
; #pragma unroll
;                     for (int n = 0; n < 2; ++n) acc[a][b][m][n] = (f32x4){0.f, 0.f, 0.f, 0.f};
;         cur = nxt; cA = nA; cB = nB; ++ui;
.LBB0_1934:
	s_add_u32 s33, s50, 0x100
	v_mov_b32_e32 v0, 0
	s_addc_u32 s77, s51, 0
	s_mov_b32 s72, -2
	s_waitcnt lgkmcnt(0)
	v_mov_b32_e32 v1, v0
	v_mov_b32_e32 v2, v0
	v_mov_b32_e32 v3, v0
	v_mov_b32_e32 v4, v0
	v_mov_b32_e32 v5, v0
	v_mov_b32_e32 v6, v0
	v_mov_b32_e32 v7, v0
	v_mov_b32_e32 v16, v0
	v_mov_b32_e32 v17, v0
	v_mov_b32_e32 v18, v0
	v_mov_b32_e32 v19, v0
	v_mov_b32_e32 v20, v0
	v_mov_b32_e32 v21, v0
	v_mov_b32_e32 v22, v0
	v_mov_b32_e32 v23, v0
	v_mov_b32_e32 v32, v0
	v_mov_b32_e32 v33, v0
	v_mov_b32_e32 v34, v0
	v_mov_b32_e32 v35, v0
	v_mov_b32_e32 v36, v0
	v_mov_b32_e32 v37, v0
	v_mov_b32_e32 v38, v0
	v_mov_b32_e32 v39, v0
	v_mov_b32_e32 v48, v0
	v_mov_b32_e32 v49, v0
	v_mov_b32_e32 v50, v0
	v_mov_b32_e32 v51, v0
	v_mov_b32_e32 v52, v0
	v_mov_b32_e32 v53, v0
	v_mov_b32_e32 v54, v0
	v_mov_b32_e32 v55, v0
	v_mov_b32_e32 v8, v0
	v_mov_b32_e32 v9, v0
	v_mov_b32_e32 v10, v0
	v_mov_b32_e32 v11, v0
	v_mov_b32_e32 v12, v0
	v_mov_b32_e32 v13, v0
	v_mov_b32_e32 v14, v0
	v_mov_b32_e32 v15, v0
	v_mov_b32_e32 v24, v0
	v_mov_b32_e32 v25, v0
	v_mov_b32_e32 v26, v0
	v_mov_b32_e32 v27, v0
	v_mov_b32_e32 v28, v0
	v_mov_b32_e32 v29, v0
	v_mov_b32_e32 v30, v0
	v_mov_b32_e32 v31, v0
	v_mov_b32_e32 v40, v0
	v_mov_b32_e32 v41, v0
	v_mov_b32_e32 v42, v0
	v_mov_b32_e32 v43, v0
	v_mov_b32_e32 v44, v0
	v_mov_b32_e32 v45, v0
	v_mov_b32_e32 v46, v0
	v_mov_b32_e32 v47, v0
	v_mov_b32_e32 v56, v0
	v_mov_b32_e32 v57, v0
	v_mov_b32_e32 v58, v0
	v_mov_b32_e32 v59, v0
	v_mov_b32_e32 v60, v0
	v_mov_b32_e32 v61, v0
	v_mov_b32_e32 v62, v0
	v_mov_b32_e32 v63, v0
	v_mov_b32_e32 v64, v0
	v_mov_b32_e32 v65, v0
	v_mov_b32_e32 v66, v0
	v_mov_b32_e32 v67, v0
	v_mov_b32_e32 v68, v0
	v_mov_b32_e32 v69, v0
	v_mov_b32_e32 v70, v0
	v_mov_b32_e32 v71, v0
	v_mov_b32_e32 v80, v0
	v_mov_b32_e32 v81, v0
	v_mov_b32_e32 v82, v0
	v_mov_b32_e32 v83, v0
	v_mov_b32_e32 v84, v0
	v_mov_b32_e32 v85, v0
	v_mov_b32_e32 v86, v0
	v_mov_b32_e32 v87, v0
	v_mov_b32_e32 v96, v0
	v_mov_b32_e32 v97, v0
	v_mov_b32_e32 v98, v0
	v_mov_b32_e32 v99, v0
	v_mov_b32_e32 v100, v0
	v_mov_b32_e32 v101, v0
	v_mov_b32_e32 v102, v0
	v_mov_b32_e32 v103, v0
	v_mov_b32_e32 v112, v0
	v_mov_b32_e32 v113, v0
	v_mov_b32_e32 v114, v0
	v_mov_b32_e32 v115, v0
	v_mov_b32_e32 v116, v0
	v_mov_b32_e32 v117, v0
	v_mov_b32_e32 v118, v0
	v_mov_b32_e32 v119, v0
	v_mov_b32_e32 v72, v0
	v_mov_b32_e32 v73, v0
	v_mov_b32_e32 v74, v0
	v_mov_b32_e32 v75, v0
	v_mov_b32_e32 v76, v0
	v_mov_b32_e32 v77, v0
	v_mov_b32_e32 v78, v0
	v_mov_b32_e32 v79, v0
	v_mov_b32_e32 v88, v0
	v_mov_b32_e32 v89, v0
	v_mov_b32_e32 v90, v0
	v_mov_b32_e32 v91, v0
	v_mov_b32_e32 v92, v0
	v_mov_b32_e32 v93, v0
	v_mov_b32_e32 v94, v0
	v_mov_b32_e32 v95, v0
	v_mov_b32_e32 v104, v0
	v_mov_b32_e32 v105, v0
	v_mov_b32_e32 v106, v0
	v_mov_b32_e32 v107, v0
	v_mov_b32_e32 v108, v0
	v_mov_b32_e32 v109, v0
	v_mov_b32_e32 v110, v0
	v_mov_b32_e32 v111, v0
	v_mov_b32_e32 v120, v0
	v_mov_b32_e32 v121, v0
	v_mov_b32_e32 v122, v0
	v_mov_b32_e32 v123, v0
	v_mov_b32_e32 v124, v0
	v_mov_b32_e32 v125, v0
	v_mov_b32_e32 v126, v0
	v_mov_b32_e32 v127, v0
	v_add_u32_e32 v244, 0x18000, v151
	v_add_u32_e32 v245, 0x1c000, v151
.LBB0_1935:
	ds_read_b128 v[144:147], v153
	ds_read_b128 v[168:171], v153 offset:1024
	ds_read_b128 v[172:175], v153 offset:2048
	ds_read_b128 v[176:179], v153 offset:3072
	ds_read_b128 v[180:183], v154
	ds_read_b128 v[184:187], v154 offset:1024
	ds_read_b128 v[188:191], v154 offset:2048
	ds_read_b128 v[198:201], v154 offset:3072
	s_add_u32 s50, s48, 0x100
	s_addc_u32 s51, s49, 0
	s_cmp_eq_u32 s72, 40
	s_cselect_b32 s55, s41, s51
	s_cselect_b32 s54, s40, s50
	s_cselect_b32 s53, s47, s77
	s_cselect_b32 s52, s46, s33
	s_add_i32 m0, s58, 0xc000
	ds_read_b128 v[202:205], v155
	ds_read_b128 v[206:209], v155 offset:1024
	ds_read_b128 v[210:213], v155 offset:2048
	ds_read_b128 v[214:217], v155 offset:3072
	ds_read_b128 v[218:221], v155 offset:4096
	ds_read_b128 v[222:225], v155 offset:5120
	ds_read_b128 v[226:229], v155 offset:6144
	ds_read_b128 v[230:233], v155 offset:7168
	global_load_lds_dwordx4 v136, s[48:49]
	s_add_i32 m0, s58, 0xe000
	s_nop 0
	global_load_lds_dwordx4 v138, s[48:49]
	s_waitcnt vmcnt(8)
	s_waitcnt lgkmcnt(0)
	s_barrier
	s_waitcnt lgkmcnt(0)
	v_mfma_f32_16x16x32_bf16 v[124:127], v[144:147], v[202:205], v[124:127]
	v_mfma_f32_16x16x32_bf16 v[120:123], v[172:175], v[202:205], v[120:123]
	v_mfma_f32_16x16x32_bf16 v[108:111], v[144:147], v[210:213], v[108:111]
	v_mfma_f32_16x16x32_bf16 v[104:107], v[172:175], v[210:213], v[104:107]
	v_mfma_f32_16x16x32_bf16 v[92:95], v[144:147], v[218:221], v[92:95]
	v_mfma_f32_16x16x32_bf16 v[88:91], v[172:175], v[218:221], v[88:91]
	v_mfma_f32_16x16x32_bf16 v[76:79], v[144:147], v[226:229], v[76:79]
	v_mfma_f32_16x16x32_bf16 v[72:75], v[172:175], v[226:229], v[72:75]
	v_mfma_f32_16x16x32_bf16 v[124:127], v[168:171], v[206:209], v[124:127]
	v_mfma_f32_16x16x32_bf16 v[120:123], v[176:179], v[206:209], v[120:123]
	v_mfma_f32_16x16x32_bf16 v[108:111], v[168:171], v[214:217], v[108:111]
	v_mfma_f32_16x16x32_bf16 v[104:107], v[176:179], v[214:217], v[104:107]
	v_mfma_f32_16x16x32_bf16 v[92:95], v[168:171], v[222:225], v[92:95]
	v_mfma_f32_16x16x32_bf16 v[88:91], v[176:179], v[222:225], v[88:91]
	v_mfma_f32_16x16x32_bf16 v[76:79], v[168:171], v[230:233], v[76:79]
	v_mfma_f32_16x16x32_bf16 v[72:75], v[176:179], v[230:233], v[72:75]
	v_mfma_f32_16x16x32_bf16 v[116:119], v[180:183], v[202:205], v[116:119]
	v_mfma_f32_16x16x32_bf16 v[112:115], v[188:191], v[202:205], v[112:115]
	v_mfma_f32_16x16x32_bf16 v[100:103], v[180:183], v[210:213], v[100:103]
	v_mfma_f32_16x16x32_bf16 v[96:99], v[188:191], v[210:213], v[96:99]
	v_mfma_f32_16x16x32_bf16 v[84:87], v[180:183], v[218:221], v[84:87]
	v_mfma_f32_16x16x32_bf16 v[80:83], v[188:191], v[218:221], v[80:83]
	v_mfma_f32_16x16x32_bf16 v[68:71], v[180:183], v[226:229], v[68:71]
	v_mfma_f32_16x16x32_bf16 v[64:67], v[188:191], v[226:229], v[64:67]
	v_mfma_f32_16x16x32_bf16 v[116:119], v[184:187], v[206:209], v[116:119]
	v_mfma_f32_16x16x32_bf16 v[112:115], v[198:201], v[206:209], v[112:115]
	v_mfma_f32_16x16x32_bf16 v[100:103], v[184:187], v[214:217], v[100:103]
	v_mfma_f32_16x16x32_bf16 v[96:99], v[198:201], v[214:217], v[96:99]
	v_mfma_f32_16x16x32_bf16 v[84:87], v[184:187], v[222:225], v[84:87]
	v_mfma_f32_16x16x32_bf16 v[80:83], v[198:201], v[222:225], v[80:83]
	v_mfma_f32_16x16x32_bf16 v[68:71], v[184:187], v[230:233], v[68:71]
	v_mfma_f32_16x16x32_bf16 v[64:67], v[198:201], v[230:233], v[64:67]
	s_barrier
; #define PG8_STAGE(bufoff, gbase, voff) do { _Pragma("unroll") for (int _i = 0; _i < 2; ++_i) \
;         __builtin_amdgcn_global_load_lds((const unsigned*)((const char*)(gbase) + (voff)[_i]), (PG8_LAS unsigned*)(lds + (bufoff) + ldsw + _i * 8192), 16, 0, 0); } while (0)
; #define PG8_LDA(dst, b, h) do { _Pragma("unroll") for (int m = 0; m < 4; ++m) _Pragma("unroll") for (int k = 0; k < 2; ++k) dst[m][k] = *(const PG8_LAS bf16x8*)(lds + PG8_SA(b, h) + aoff + m * 2048 + k * 1024); } while (0)
; #define PG8_LDB(dst, b, h) do { _Pragma("unroll") for (int n = 0; n < 2; ++n) _Pragma("unroll") for (int k = 0; k < 2; ++k) dst[n][k] = *(const PG8_LAS bf16x8*)(lds + PG8_SB(b, h) + boff + n * 2048 + k * 1024); } while (0)
; #define PG8_MMA(ai, bj, At, Bt) do { __builtin_amdgcn_s_setprio(1); _Pragma("unroll") for (int m = 0; m < 4; ++m) _Pragma("unroll") for (int n = 0; n < 2; ++n) _Pragma("unroll") for (int k = 0; k < 2; ++k) \
;         acc[ai][bj][m][n] = __builtin_amdgcn_mfma_f32_16x16x32_bf16(Bt[n][k], At[m][k], acc[ai][bj][m][n], 0, 0, 0); __builtin_amdgcn_s_setprio(0); } while (0)
; #define PG8_WAIT_V(n) asm volatile("s_waitcnt vmcnt(" #n ")" ::: "memory")
; #define PG8_WAIT_L(n) asm volatile("s_waitcnt lgkmcnt(" #n ")" ::: "memory")
; #define PG8_BAR __builtin_amdgcn_s_barrier()
; #define PG8_SCHED __builtin_amdgcn_sched_barrier(0)
; template <class Epi, class Sched, bool ALIGN_EPI = false, bool SP2 = false>
; __device__ __forceinline__ void gemm_phase(PG8_LAS unsigned char* lds, const Gemm g, const Sched& S, const Epi& E) {
;     ...
;             PG8_LDA(At, 0, 1); PG8_STAGE(PG8_SB(0, 0), b2, voffB); PG8_STAGE(PG8_SB(0, 1), b2 + hstep, voffB); PG8_STAGE(PG8_SA(0, 0), a2, voffA);
;             PG8_WAIT_V(8); PG8_WAIT_L(0); PG8_BAR; PG8_MMA(1, 0, At, B0); PG8_MMA(1, 1, At, B1); PG8_BAR; PG8_SCHED;
;             PG8_LDB(B0, 1, 0); PG8_LDB(B1, 1, 1); PG8_SCHED; PG8_LDA(At, 1, 0); PG8_STAGE(PG8_SA(0, 1), a2 + hstep, voffA);
;             PG8_WAIT_V(8); PG8_WAIT_L(0); PG8_BAR; PG8_MMA(0, 0, At, B0); PG8_MMA(0, 1, At, B1); PG8_BAR; PG8_SCHED;
	s_add_i32 s6, s26, s57
	s_mov_b32 m0, s6
	ds_read_b128 v[202:205], v155 offset:16384
	ds_read_b128 v[206:209], v155 offset:17408
	ds_read_b128 v[210:213], v155 offset:18432
	ds_read_b128 v[214:217], v155 offset:19456
	ds_read_b128 v[218:221], v155 offset:20480
	ds_read_b128 v[222:225], v155 offset:21504
	ds_read_b128 v[226:229], v155 offset:22528
	ds_read_b128 v[230:233], v155 offset:23552
	global_load_lds_dwordx4 v130, s[52:53]
	s_add_i32 m0, s6, 0x2000
	s_add_u32 s6, s52, 0xb0000
	s_addc_u32 s7, s53, 0
	s_add_i32 s48, s74, s57
	global_load_lds_dwordx4 v134, s[52:53]
	s_mov_b32 m0, s48
	s_nop 0
	global_load_lds_dwordx4 v130, s[6:7]
	s_add_i32 m0, s48, 0x2000
	s_nop 0
	global_load_lds_dwordx4 v134, s[6:7]
	s_mov_b32 m0, s58
	s_nop 0
	global_load_lds_dwordx4 v128, s[54:55]
	s_mov_b32 m0, s59
	s_nop 0
	global_load_lds_dwordx4 v132, s[54:55]
	s_waitcnt vmcnt(8)
	s_waitcnt lgkmcnt(0)
	s_barrier
	s_waitcnt lgkmcnt(0)
	v_mfma_f32_16x16x32_bf16 v[60:63], v[144:147], v[202:205], v[60:63]
	v_mfma_f32_16x16x32_bf16 v[56:59], v[172:175], v[202:205], v[56:59]
	v_mfma_f32_16x16x32_bf16 v[44:47], v[144:147], v[210:213], v[44:47]
	v_mfma_f32_16x16x32_bf16 v[40:43], v[172:175], v[210:213], v[40:43]
	v_mfma_f32_16x16x32_bf16 v[28:31], v[144:147], v[218:221], v[28:31]
	v_mfma_f32_16x16x32_bf16 v[24:27], v[172:175], v[218:221], v[24:27]
	v_mfma_f32_16x16x32_bf16 v[12:15], v[144:147], v[226:229], v[12:15]
	v_mfma_f32_16x16x32_bf16 v[8:11], v[172:175], v[226:229], v[8:11]
	v_mfma_f32_16x16x32_bf16 v[60:63], v[168:171], v[206:209], v[60:63]
	v_mfma_f32_16x16x32_bf16 v[56:59], v[176:179], v[206:209], v[56:59]
	v_mfma_f32_16x16x32_bf16 v[44:47], v[168:171], v[214:217], v[44:47]
	v_mfma_f32_16x16x32_bf16 v[40:43], v[176:179], v[214:217], v[40:43]
	v_mfma_f32_16x16x32_bf16 v[28:31], v[168:171], v[222:225], v[28:31]
	v_mfma_f32_16x16x32_bf16 v[24:27], v[176:179], v[222:225], v[24:27]
	v_mfma_f32_16x16x32_bf16 v[12:15], v[168:171], v[230:233], v[12:15]
	v_mfma_f32_16x16x32_bf16 v[8:11], v[176:179], v[230:233], v[8:11]
	v_mfma_f32_16x16x32_bf16 v[52:55], v[180:183], v[202:205], v[52:55]
	v_mfma_f32_16x16x32_bf16 v[48:51], v[188:191], v[202:205], v[48:51]
	v_mfma_f32_16x16x32_bf16 v[36:39], v[180:183], v[210:213], v[36:39]
	v_mfma_f32_16x16x32_bf16 v[32:35], v[188:191], v[210:213], v[32:35]
	v_mfma_f32_16x16x32_bf16 v[20:23], v[180:183], v[218:221], v[20:23]
	v_mfma_f32_16x16x32_bf16 v[16:19], v[188:191], v[218:221], v[16:19]
	v_mfma_f32_16x16x32_bf16 v[4:7], v[180:183], v[226:229], v[4:7]
	v_mfma_f32_16x16x32_bf16 v[0:3], v[188:191], v[226:229], v[0:3]
	v_mfma_f32_16x16x32_bf16 v[52:55], v[184:187], v[206:209], v[52:55]
	v_mfma_f32_16x16x32_bf16 v[48:51], v[198:201], v[206:209], v[48:51]
	v_mfma_f32_16x16x32_bf16 v[36:39], v[184:187], v[214:217], v[36:39]
	v_mfma_f32_16x16x32_bf16 v[32:35], v[198:201], v[214:217], v[32:35]
	v_mfma_f32_16x16x32_bf16 v[20:23], v[184:187], v[222:225], v[20:23]
	v_mfma_f32_16x16x32_bf16 v[16:19], v[198:201], v[222:225], v[16:19]
	v_mfma_f32_16x16x32_bf16 v[4:7], v[184:187], v[230:233], v[4:7]
	v_mfma_f32_16x16x32_bf16 v[0:3], v[198:201], v[230:233], v[0:3]
	s_barrier
	s_add_i32 s48, 0, 0x18000
	s_add_i32 s49, 0, 0x1c000
	ds_read_b128 v[144:147], v244
	ds_read_b128 v[168:171], v244 offset:1024
	ds_read_b128 v[172:175], v244 offset:2048
	ds_read_b128 v[176:179], v244 offset:3072
	ds_read_b128 v[180:183], v245
	ds_read_b128 v[184:187], v245 offset:1024
	ds_read_b128 v[188:191], v245 offset:2048
	ds_read_b128 v[198:201], v245 offset:3072
	s_add_u32 s6, s54, 0xb0000
	s_addc_u32 s7, s55, 0
	s_mov_b32 m0, s60
	ds_read_b128 v[202:205], v155 offset:32768
	ds_read_b128 v[206:209], v155 offset:33792
	ds_read_b128 v[210:213], v155 offset:34816
	ds_read_b128 v[214:217], v155 offset:35840
	ds_read_b128 v[218:221], v155 offset:36864
	ds_read_b128 v[222:225], v155 offset:37888
	ds_read_b128 v[226:229], v155 offset:38912
	ds_read_b128 v[230:233], v155 offset:39936
	global_load_lds_dwordx4 v128, s[6:7]
	s_mov_b32 m0, s61
	s_nop 0
	global_load_lds_dwordx4 v132, s[6:7]
	s_waitcnt vmcnt(8)
	s_waitcnt lgkmcnt(0)
	s_barrier
; #define PG8_STAGE(bufoff, gbase, voff) do { _Pragma("unroll") for (int _i = 0; _i < 2; ++_i) \
;         __builtin_amdgcn_global_load_lds((const unsigned*)((const char*)(gbase) + (voff)[_i]), (PG8_LAS unsigned*)(lds + (bufoff) + ldsw + _i * 8192), 16, 0, 0); } while (0)
; #define PG8_LDA(dst, b, h) do { _Pragma("unroll") for (int m = 0; m < 4; ++m) _Pragma("unroll") for (int k = 0; k < 2; ++k) dst[m][k] = *(const PG8_LAS bf16x8*)(lds + PG8_SA(b, h) + aoff + m * 2048 + k * 1024); } while (0)
; #define PG8_MMA(ai, bj, At, Bt) do { __builtin_amdgcn_s_setprio(1); _Pragma("unroll") for (int m = 0; m < 4; ++m) _Pragma("unroll") for (int n = 0; n < 2; ++n) _Pragma("unroll") for (int k = 0; k < 2; ++k) \
;         acc[ai][bj][m][n] = __builtin_amdgcn_mfma_f32_16x16x32_bf16(Bt[n][k], At[m][k], acc[ai][bj][m][n], 0, 0, 0); __builtin_amdgcn_s_setprio(0); } while (0)
; #define PG8_WAIT_V(n) asm volatile("s_waitcnt vmcnt(" #n ")" ::: "memory")
; #define PG8_WAIT_L(n) asm volatile("s_waitcnt lgkmcnt(" #n ")" ::: "memory")
; #define PG8_BAR __builtin_amdgcn_s_barrier()
; #define PG8_SCHED __builtin_amdgcn_sched_barrier(0)
; template <class Epi, class Sched, bool ALIGN_EPI = false, bool SP2 = false>
; __device__ __forceinline__ void gemm_phase(PG8_LAS unsigned char* lds, const Gemm g, const Sched& S, const Epi& E) {
;     ...
;             PG8_WAIT_V(8); PG8_WAIT_L(0); PG8_BAR; PG8_MMA(0, 0, At, B0); PG8_MMA(0, 1, At, B1); PG8_BAR; PG8_SCHED;
;             PG8_LDA(At, 1, 1); PG8_STAGE(PG8_SB(1, 0), b3, voffB); PG8_STAGE(PG8_SB(1, 1), b3 + hstep, voffB); PG8_STAGE(PG8_SA(1, 0), a3, voffA);
;             PG8_WAIT_V(8); PG8_WAIT_L(0); PG8_BAR; PG8_MMA(1, 0, At, B0); PG8_MMA(1, 1, At, B1); PG8_BAR; PG8_SCHED;
	s_waitcnt lgkmcnt(0)
	v_mfma_f32_16x16x32_bf16 v[124:127], v[144:147], v[202:205], v[124:127]
	v_mfma_f32_16x16x32_bf16 v[120:123], v[172:175], v[202:205], v[120:123]
	v_mfma_f32_16x16x32_bf16 v[108:111], v[144:147], v[210:213], v[108:111]
	v_mfma_f32_16x16x32_bf16 v[104:107], v[172:175], v[210:213], v[104:107]
	v_mfma_f32_16x16x32_bf16 v[92:95], v[144:147], v[218:221], v[92:95]
	v_mfma_f32_16x16x32_bf16 v[88:91], v[172:175], v[218:221], v[88:91]
	v_mfma_f32_16x16x32_bf16 v[76:79], v[144:147], v[226:229], v[76:79]
	v_mfma_f32_16x16x32_bf16 v[72:75], v[172:175], v[226:229], v[72:75]
	v_mfma_f32_16x16x32_bf16 v[124:127], v[168:171], v[206:209], v[124:127]
	v_mfma_f32_16x16x32_bf16 v[120:123], v[176:179], v[206:209], v[120:123]
	v_mfma_f32_16x16x32_bf16 v[108:111], v[168:171], v[214:217], v[108:111]
	v_mfma_f32_16x16x32_bf16 v[104:107], v[176:179], v[214:217], v[104:107]
	v_mfma_f32_16x16x32_bf16 v[92:95], v[168:171], v[222:225], v[92:95]
	v_mfma_f32_16x16x32_bf16 v[88:91], v[176:179], v[222:225], v[88:91]
	v_mfma_f32_16x16x32_bf16 v[76:79], v[168:171], v[230:233], v[76:79]
	v_mfma_f32_16x16x32_bf16 v[72:75], v[176:179], v[230:233], v[72:75]
	v_mfma_f32_16x16x32_bf16 v[116:119], v[180:183], v[202:205], v[116:119]
	v_mfma_f32_16x16x32_bf16 v[112:115], v[188:191], v[202:205], v[112:115]
	v_mfma_f32_16x16x32_bf16 v[100:103], v[180:183], v[210:213], v[100:103]
	v_mfma_f32_16x16x32_bf16 v[96:99], v[188:191], v[210:213], v[96:99]
	v_mfma_f32_16x16x32_bf16 v[84:87], v[180:183], v[218:221], v[84:87]
	v_mfma_f32_16x16x32_bf16 v[80:83], v[188:191], v[218:221], v[80:83]
	v_mfma_f32_16x16x32_bf16 v[68:71], v[180:183], v[226:229], v[68:71]
	v_mfma_f32_16x16x32_bf16 v[64:67], v[188:191], v[226:229], v[64:67]
	v_mfma_f32_16x16x32_bf16 v[116:119], v[184:187], v[206:209], v[116:119]
	v_mfma_f32_16x16x32_bf16 v[112:115], v[198:201], v[206:209], v[112:115]
	v_mfma_f32_16x16x32_bf16 v[100:103], v[184:187], v[214:217], v[100:103]
	v_mfma_f32_16x16x32_bf16 v[96:99], v[198:201], v[214:217], v[96:99]
	v_mfma_f32_16x16x32_bf16 v[84:87], v[184:187], v[222:225], v[84:87]
	v_mfma_f32_16x16x32_bf16 v[80:83], v[198:201], v[222:225], v[80:83]
	v_mfma_f32_16x16x32_bf16 v[68:71], v[184:187], v[230:233], v[68:71]
	v_mfma_f32_16x16x32_bf16 v[64:67], v[198:201], v[230:233], v[64:67]
	s_barrier
	s_add_i32 s6, s48, s57
	s_add_u32 s98, s52, 0x80
	s_addc_u32 s99, s53, 0
	s_add_u32 s100, s54, 0x80
	s_addc_u32 s101, s55, 0
	s_mov_b32 m0, s6
	ds_read_b128 v[202:205], v155 offset:49152
	ds_read_b128 v[206:209], v155 offset:50176
	ds_read_b128 v[210:213], v155 offset:51200
	ds_read_b128 v[214:217], v155 offset:52224
	ds_read_b128 v[218:221], v155 offset:53248
	ds_read_b128 v[222:225], v155 offset:54272
	ds_read_b128 v[226:229], v155 offset:55296
	ds_read_b128 v[230:233], v155 offset:56320
	global_load_lds_dwordx4 v130, s[98:99]
	s_add_i32 m0, s6, 0x2000
	s_add_u32 s6, s52, 0xb0080
	s_addc_u32 s7, s53, 0
	s_add_i32 s48, s49, s57
	global_load_lds_dwordx4 v134, s[98:99]
	s_mov_b32 m0, s48
	s_nop 0
	global_load_lds_dwordx4 v130, s[6:7]
	s_add_i32 m0, s48, 0x2000
	s_nop 0
	global_load_lds_dwordx4 v134, s[6:7]
	s_mov_b32 m0, s76
	s_nop 0
	global_load_lds_dwordx4 v128, s[100:101]
	s_mov_b32 m0, s4
	s_nop 0
	global_load_lds_dwordx4 v132, s[100:101]
	s_waitcnt vmcnt(8)
	s_waitcnt lgkmcnt(0)
	s_barrier
	s_waitcnt lgkmcnt(0)
	v_mfma_f32_16x16x32_bf16 v[60:63], v[144:147], v[202:205], v[60:63]
	v_mfma_f32_16x16x32_bf16 v[56:59], v[172:175], v[202:205], v[56:59]
	v_mfma_f32_16x16x32_bf16 v[44:47], v[144:147], v[210:213], v[44:47]
	v_mfma_f32_16x16x32_bf16 v[40:43], v[172:175], v[210:213], v[40:43]
	v_mfma_f32_16x16x32_bf16 v[28:31], v[144:147], v[218:221], v[28:31]
	v_mfma_f32_16x16x32_bf16 v[24:27], v[172:175], v[218:221], v[24:27]
	v_mfma_f32_16x16x32_bf16 v[12:15], v[144:147], v[226:229], v[12:15]
	v_mfma_f32_16x16x32_bf16 v[8:11], v[172:175], v[226:229], v[8:11]
	v_mfma_f32_16x16x32_bf16 v[60:63], v[168:171], v[206:209], v[60:63]
	v_mfma_f32_16x16x32_bf16 v[56:59], v[176:179], v[206:209], v[56:59]
	v_mfma_f32_16x16x32_bf16 v[44:47], v[168:171], v[214:217], v[44:47]
	v_mfma_f32_16x16x32_bf16 v[40:43], v[176:179], v[214:217], v[40:43]
	v_mfma_f32_16x16x32_bf16 v[28:31], v[168:171], v[222:225], v[28:31]
	v_mfma_f32_16x16x32_bf16 v[24:27], v[176:179], v[222:225], v[24:27]
	v_mfma_f32_16x16x32_bf16 v[12:15], v[168:171], v[230:233], v[12:15]
	v_mfma_f32_16x16x32_bf16 v[8:11], v[176:179], v[230:233], v[8:11]
	v_mfma_f32_16x16x32_bf16 v[52:55], v[180:183], v[202:205], v[52:55]
	v_mfma_f32_16x16x32_bf16 v[48:51], v[188:191], v[202:205], v[48:51]
	v_mfma_f32_16x16x32_bf16 v[36:39], v[180:183], v[210:213], v[36:39]
	v_mfma_f32_16x16x32_bf16 v[32:35], v[188:191], v[210:213], v[32:35]
	v_mfma_f32_16x16x32_bf16 v[20:23], v[180:183], v[218:221], v[20:23]
	v_mfma_f32_16x16x32_bf16 v[16:19], v[188:191], v[218:221], v[16:19]
	v_mfma_f32_16x16x32_bf16 v[4:7], v[180:183], v[226:229], v[4:7]
	v_mfma_f32_16x16x32_bf16 v[0:3], v[188:191], v[226:229], v[0:3]
	v_mfma_f32_16x16x32_bf16 v[52:55], v[184:187], v[206:209], v[52:55]
	v_mfma_f32_16x16x32_bf16 v[48:51], v[198:201], v[206:209], v[48:51]
	v_mfma_f32_16x16x32_bf16 v[36:39], v[184:187], v[214:217], v[36:39]
	v_mfma_f32_16x16x32_bf16 v[32:35], v[198:201], v[214:217], v[32:35]
	v_mfma_f32_16x16x32_bf16 v[20:23], v[184:187], v[222:225], v[20:23]
	v_mfma_f32_16x16x32_bf16 v[16:19], v[198:201], v[222:225], v[16:19]
	v_mfma_f32_16x16x32_bf16 v[4:7], v[184:187], v[230:233], v[4:7]
	v_mfma_f32_16x16x32_bf16 v[0:3], v[198:201], v[230:233], v[0:3]
	s_barrier
	s_add_i32 s72, s72, 2
	s_add_u32 s33, s33, 0x100
	s_addc_u32 s77, s77, 0
	s_cmp_gt_u32 s72, 41
	s_mov_b64 s[48:49], s[50:51]
	s_cbranch_scc0 .LBB0_1935
	s_and_b64 vcc, exec, s[38:39]
	s_cbranch_vccz .LBB0_1938
	s_barrier
